# first K-iteration of each GEMM tile peeled: accumulators initialised by MFMA with srcC=0, 128 v_mov zeroing per tile removed
# speedup vs baseline: 1.0130x; 1.0016x over previous
.LBB0_253:
	s_ashr_i32 s21, s20, 31
	s_lshl_b64 s[22:23], s[20:21], 19
	s_add_u32 s22, s92, s22
	s_addc_u32 s23, s93, s23
	s_and_b64 s[24:25], s[2:3], exec
	s_cselect_b32 s21, s23, s15
	s_cselect_b32 s63, s22, s14
	s_ashr_i32 s13, s12, 31
	s_lshl_b64 s[24:25], s[12:13], 19
	s_add_u32 s24, s0, s24
	s_addc_u32 s25, s1, s25
	s_and_b64 s[30:31], s[2:3], exec
	s_cselect_b32 s13, s25, s41
	s_cselect_b32 s64, s24, s40
	s_add_u32 s30, s14, 0x40080
	s_addc_u32 s31, s15, 0
	s_add_u32 s65, s40, 0x100

	s_addc_u32 s66, s41, 0
	s_mov_b32 s67, -2


	ds_read_b128 v[162:165], v157
	ds_read_b128 v[166:169], v157 offset:1024
	ds_read_b128 v[170:173], v157 offset:2048
	ds_read_b128 v[174:177], v157 offset:3072
	ds_read_b128 v[182:185], v158
	ds_read_b128 v[186:189], v158 offset:1024
	ds_read_b128 v[190:193], v158 offset:2048
	ds_read_b128 v[194:197], v158 offset:3072
	s_add_u32 s14, s30, 0xfffc0080
	s_addc_u32 s15, s31, -1
	s_cmp_eq_u32 s67, 12
	s_cselect_b32 s41, s21, s15
	s_cselect_b32 s40, s63, s14
	s_cselect_b32 s15, s13, s66
	s_cselect_b32 s14, s64, s65
	v_lshl_add_u64 v[178:179], s[30:31], 0, v[146:147]
	s_add_i32 m0, s29, 0xc000
	ds_read_b128 v[198:201], v159
	ds_read_b128 v[202:205], v159 offset:1024
	ds_read_b128 v[206:209], v159 offset:2048
	ds_read_b128 v[210:213], v159 offset:3072
	ds_read_b128 v[214:217], v159 offset:4096
	ds_read_b128 v[218:221], v159 offset:5120
	ds_read_b128 v[222:225], v159 offset:6144
	ds_read_b128 v[226:229], v159 offset:7168
	global_load_lds_dwordx4 v[178:179], off
	v_lshl_add_u64 v[178:179], s[30:31], 0, v[148:149]
	s_add_i32 m0, s29, 0xe000
	s_nop 0
	global_load_lds_dwordx4 v[178:179], off
	s_waitcnt vmcnt(8)
	s_waitcnt lgkmcnt(0)
	s_barrier
	s_setprio 1
	s_waitcnt lgkmcnt(0)
	v_mfma_f32_16x16x32_bf16 v[126:129], v[162:165], v[198:201], 0
	v_mfma_f32_16x16x32_bf16 v[118:121], v[170:173], v[198:201], 0
	v_mfma_f32_16x16x32_bf16 v[110:113], v[162:165], v[206:209], 0
	v_mfma_f32_16x16x32_bf16 v[102:105], v[170:173], v[206:209], 0
	v_mfma_f32_16x16x32_bf16 v[94:97], v[162:165], v[214:217], 0
	v_mfma_f32_16x16x32_bf16 v[86:89], v[170:173], v[214:217], 0
	v_mfma_f32_16x16x32_bf16 v[78:81], v[162:165], v[222:225], 0
	v_mfma_f32_16x16x32_bf16 v[70:73], v[170:173], v[222:225], 0
	v_mfma_f32_16x16x32_bf16 v[126:129], v[166:169], v[202:205], v[126:129]
	v_mfma_f32_16x16x32_bf16 v[118:121], v[174:177], v[202:205], v[118:121]
	v_mfma_f32_16x16x32_bf16 v[110:113], v[166:169], v[210:213], v[110:113]
	v_mfma_f32_16x16x32_bf16 v[102:105], v[174:177], v[210:213], v[102:105]
	v_mfma_f32_16x16x32_bf16 v[94:97], v[166:169], v[218:221], v[94:97]
	v_mfma_f32_16x16x32_bf16 v[86:89], v[174:177], v[218:221], v[86:89]
	v_mfma_f32_16x16x32_bf16 v[78:81], v[166:169], v[226:229], v[78:81]
	v_mfma_f32_16x16x32_bf16 v[70:73], v[174:177], v[226:229], v[70:73]
	s_setprio 0
	s_setprio 1
	v_mfma_f32_16x16x32_bf16 v[122:125], v[182:185], v[198:201], 0
	v_mfma_f32_16x16x32_bf16 v[114:117], v[190:193], v[198:201], 0
	v_mfma_f32_16x16x32_bf16 v[106:109], v[182:185], v[206:209], 0
	v_mfma_f32_16x16x32_bf16 v[98:101], v[190:193], v[206:209], 0
	v_mfma_f32_16x16x32_bf16 v[90:93], v[182:185], v[214:217], 0
	v_mfma_f32_16x16x32_bf16 v[82:85], v[190:193], v[214:217], 0
	v_mfma_f32_16x16x32_bf16 v[74:77], v[182:185], v[222:225], 0
	v_mfma_f32_16x16x32_bf16 v[66:69], v[190:193], v[222:225], 0
	v_mfma_f32_16x16x32_bf16 v[122:125], v[186:189], v[202:205], v[122:125]
	v_mfma_f32_16x16x32_bf16 v[114:117], v[194:197], v[202:205], v[114:117]
	v_mfma_f32_16x16x32_bf16 v[106:109], v[186:189], v[210:213], v[106:109]
	v_mfma_f32_16x16x32_bf16 v[98:101], v[194:197], v[210:213], v[98:101]
	v_mfma_f32_16x16x32_bf16 v[90:93], v[186:189], v[218:221], v[90:93]
	v_mfma_f32_16x16x32_bf16 v[82:85], v[194:197], v[218:221], v[82:85]
	v_mfma_f32_16x16x32_bf16 v[74:77], v[186:189], v[226:229], v[74:77]
	v_mfma_f32_16x16x32_bf16 v[66:69], v[194:197], v[226:229], v[66:69]
	s_setprio 0
	s_barrier
	s_add_i32 s33, s58, s27
	v_lshl_add_u64 v[178:179], s[14:15], 0, v[132:133]
	s_mov_b32 m0, s33
	ds_read_b128 v[198:201], v159 offset:16384
	ds_read_b128 v[202:205], v159 offset:17408
	ds_read_b128 v[206:209], v159 offset:18432
	ds_read_b128 v[210:213], v159 offset:19456
	ds_read_b128 v[214:217], v159 offset:20480
	ds_read_b128 v[218:221], v159 offset:21504
	ds_read_b128 v[222:225], v159 offset:22528
	ds_read_b128 v[226:229], v159 offset:23552
	global_load_lds_dwordx4 v[178:179], off
	s_add_i32 m0, s33, 0x2000
	s_add_u32 s54, s14, 0x40000
	v_lshl_add_u64 v[230:231], s[14:15], 0, v[136:137]
	s_addc_u32 s55, s15, 0
	s_add_i32 s33, s59, s27
	global_load_lds_dwordx4 v[230:231], off
	v_lshl_add_u64 v[232:233], s[54:55], 0, v[132:133]
	s_mov_b32 m0, s33
	v_lshl_add_u64 v[234:235], s[40:41], 0, v[134:135]
	global_load_lds_dwordx4 v[232:233], off
	v_lshl_add_u64 v[232:233], s[54:55], 0, v[136:137]
	s_add_i32 m0, s33, 0x2000
	s_nop 0
	global_load_lds_dwordx4 v[232:233], off
	v_lshl_add_u64 v[232:233], s[40:41], 0, v[130:131]
	s_mov_b32 m0, s29
	s_nop 0
	global_load_lds_dwordx4 v[232:233], off
	s_mov_b32 m0, s42
	s_nop 0
	global_load_lds_dwordx4 v[234:235], off
	s_waitcnt vmcnt(8)
	s_waitcnt lgkmcnt(0)
	s_barrier
	s_setprio 1
	s_waitcnt lgkmcnt(0)
	v_mfma_f32_16x16x32_bf16 v[62:65], v[162:165], v[198:201], 0
	v_mfma_f32_16x16x32_bf16 v[54:57], v[170:173], v[198:201], 0
	v_mfma_f32_16x16x32_bf16 v[46:49], v[162:165], v[206:209], 0
	v_mfma_f32_16x16x32_bf16 v[38:41], v[170:173], v[206:209], 0
	v_mfma_f32_16x16x32_bf16 v[30:33], v[162:165], v[214:217], 0
	v_mfma_f32_16x16x32_bf16 v[22:25], v[170:173], v[214:217], 0
	v_mfma_f32_16x16x32_bf16 v[14:17], v[162:165], v[222:225], 0
	v_mfma_f32_16x16x32_bf16 v[6:9], v[170:173], v[222:225], 0
	v_mfma_f32_16x16x32_bf16 v[62:65], v[166:169], v[202:205], v[62:65]
	v_mfma_f32_16x16x32_bf16 v[54:57], v[174:177], v[202:205], v[54:57]
	v_mfma_f32_16x16x32_bf16 v[46:49], v[166:169], v[210:213], v[46:49]
	v_mfma_f32_16x16x32_bf16 v[38:41], v[174:177], v[210:213], v[38:41]
	v_mfma_f32_16x16x32_bf16 v[30:33], v[166:169], v[218:221], v[30:33]
	v_mfma_f32_16x16x32_bf16 v[22:25], v[174:177], v[218:221], v[22:25]
	v_mfma_f32_16x16x32_bf16 v[14:17], v[166:169], v[226:229], v[14:17]
	v_mfma_f32_16x16x32_bf16 v[6:9], v[174:177], v[226:229], v[6:9]
	s_setprio 0
	s_setprio 1
	v_mfma_f32_16x16x32_bf16 v[58:61], v[182:185], v[198:201], 0
	v_mfma_f32_16x16x32_bf16 v[50:53], v[190:193], v[198:201], 0
	v_mfma_f32_16x16x32_bf16 v[42:45], v[182:185], v[206:209], 0
	v_mfma_f32_16x16x32_bf16 v[34:37], v[190:193], v[206:209], 0
	v_mfma_f32_16x16x32_bf16 v[26:29], v[182:185], v[214:217], 0
	v_mfma_f32_16x16x32_bf16 v[18:21], v[190:193], v[214:217], 0
	v_mfma_f32_16x16x32_bf16 v[10:13], v[182:185], v[222:225], 0
	v_mfma_f32_16x16x32_bf16 v[2:5], v[190:193], v[222:225], 0
	v_mfma_f32_16x16x32_bf16 v[58:61], v[186:189], v[202:205], v[58:61]
	v_mfma_f32_16x16x32_bf16 v[50:53], v[194:197], v[202:205], v[50:53]
	v_mfma_f32_16x16x32_bf16 v[42:45], v[186:189], v[210:213], v[42:45]
	v_mfma_f32_16x16x32_bf16 v[34:37], v[194:197], v[210:213], v[34:37]
	v_mfma_f32_16x16x32_bf16 v[26:29], v[186:189], v[218:221], v[26:29]
	v_mfma_f32_16x16x32_bf16 v[18:21], v[194:197], v[218:221], v[18:21]
	v_mfma_f32_16x16x32_bf16 v[10:13], v[186:189], v[226:229], v[10:13]
	v_mfma_f32_16x16x32_bf16 v[2:5], v[194:197], v[226:229], v[2:5]
	s_setprio 0
	s_barrier
	s_add_i32 s33, 0, 0x18000
	v_add_u32_e32 v161, s33, v155
	s_add_i32 s51, 0, 0x1c000
	ds_read_b128 v[162:165], v161
	ds_read_b128 v[166:169], v161 offset:1024
	ds_read_b128 v[170:173], v161 offset:2048
	ds_read_b128 v[174:177], v161 offset:3072
	v_add_u32_e32 v161, s51, v155
	ds_read_b128 v[182:185], v161
	ds_read_b128 v[186:189], v161 offset:1024
	ds_read_b128 v[190:193], v161 offset:2048
	ds_read_b128 v[194:197], v161 offset:3072
	s_add_u32 s40, s40, 0x40000
	s_addc_u32 s41, s41, 0
	s_mov_b32 m0, s43
	v_lshl_add_u64 v[236:237], s[40:41], 0, v[130:131]
	ds_read_b128 v[198:201], v159 offset:32768
	ds_read_b128 v[202:205], v159 offset:33792
	ds_read_b128 v[206:209], v159 offset:34816
	ds_read_b128 v[210:213], v159 offset:35840
	ds_read_b128 v[214:217], v159 offset:36864
	ds_read_b128 v[218:221], v159 offset:37888
	ds_read_b128 v[222:225], v159 offset:38912
	ds_read_b128 v[226:229], v159 offset:39936
	global_load_lds_dwordx4 v[236:237], off
	v_lshl_add_u64 v[236:237], s[40:41], 0, v[134:135]
	s_mov_b32 m0, s46
	s_nop 0
	global_load_lds_dwordx4 v[236:237], off
	s_waitcnt vmcnt(8)
	s_waitcnt lgkmcnt(0)
	s_barrier
	s_setprio 1
	s_waitcnt lgkmcnt(0)
	v_mfma_f32_16x16x32_bf16 v[126:129], v[162:165], v[198:201], v[126:129]
	v_mfma_f32_16x16x32_bf16 v[118:121], v[170:173], v[198:201], v[118:121]
	v_mfma_f32_16x16x32_bf16 v[110:113], v[162:165], v[206:209], v[110:113]
	v_mfma_f32_16x16x32_bf16 v[102:105], v[170:173], v[206:209], v[102:105]
	v_mfma_f32_16x16x32_bf16 v[94:97], v[162:165], v[214:217], v[94:97]
	v_mfma_f32_16x16x32_bf16 v[86:89], v[170:173], v[214:217], v[86:89]
	v_mfma_f32_16x16x32_bf16 v[78:81], v[162:165], v[222:225], v[78:81]
	v_mfma_f32_16x16x32_bf16 v[70:73], v[170:173], v[222:225], v[70:73]
	v_mfma_f32_16x16x32_bf16 v[126:129], v[166:169], v[202:205], v[126:129]
	v_mfma_f32_16x16x32_bf16 v[118:121], v[174:177], v[202:205], v[118:121]
	v_mfma_f32_16x16x32_bf16 v[110:113], v[166:169], v[210:213], v[110:113]
	v_mfma_f32_16x16x32_bf16 v[102:105], v[174:177], v[210:213], v[102:105]
	v_mfma_f32_16x16x32_bf16 v[94:97], v[166:169], v[218:221], v[94:97]
	v_mfma_f32_16x16x32_bf16 v[86:89], v[174:177], v[218:221], v[86:89]
	v_mfma_f32_16x16x32_bf16 v[78:81], v[166:169], v[226:229], v[78:81]
	v_mfma_f32_16x16x32_bf16 v[70:73], v[174:177], v[226:229], v[70:73]
	s_setprio 0
	s_setprio 1
	v_mfma_f32_16x16x32_bf16 v[122:125], v[182:185], v[198:201], v[122:125]
	v_mfma_f32_16x16x32_bf16 v[114:117], v[190:193], v[198:201], v[114:117]
	v_mfma_f32_16x16x32_bf16 v[106:109], v[182:185], v[206:209], v[106:109]
	v_mfma_f32_16x16x32_bf16 v[98:101], v[190:193], v[206:209], v[98:101]
	v_mfma_f32_16x16x32_bf16 v[90:93], v[182:185], v[214:217], v[90:93]
	v_mfma_f32_16x16x32_bf16 v[82:85], v[190:193], v[214:217], v[82:85]
	v_mfma_f32_16x16x32_bf16 v[74:77], v[182:185], v[222:225], v[74:77]
	v_mfma_f32_16x16x32_bf16 v[66:69], v[190:193], v[222:225], v[66:69]
	v_mfma_f32_16x16x32_bf16 v[122:125], v[186:189], v[202:205], v[122:125]
	v_mfma_f32_16x16x32_bf16 v[114:117], v[194:197], v[202:205], v[114:117]
	v_mfma_f32_16x16x32_bf16 v[106:109], v[186:189], v[210:213], v[106:109]
	v_mfma_f32_16x16x32_bf16 v[98:101], v[194:197], v[210:213], v[98:101]
	v_mfma_f32_16x16x32_bf16 v[90:93], v[186:189], v[218:221], v[90:93]
	v_mfma_f32_16x16x32_bf16 v[82:85], v[194:197], v[218:221], v[82:85]
	v_mfma_f32_16x16x32_bf16 v[74:77], v[186:189], v[226:229], v[74:77]
	v_mfma_f32_16x16x32_bf16 v[66:69], v[194:197], v[226:229], v[66:69]
	s_setprio 0
	s_barrier
	s_add_i32 s33, s33, s27
	v_lshl_add_u64 v[178:179], v[178:179], 0, s[10:11]
	s_mov_b32 m0, s33
	ds_read_b128 v[198:201], v159 offset:49152
	ds_read_b128 v[202:205], v159 offset:50176
	ds_read_b128 v[206:209], v159 offset:51200
	ds_read_b128 v[210:213], v159 offset:52224
	ds_read_b128 v[214:217], v159 offset:53248
	ds_read_b128 v[218:221], v159 offset:54272
	ds_read_b128 v[222:225], v159 offset:55296
	ds_read_b128 v[226:229], v159 offset:56320
	global_load_lds_dwordx4 v[178:179], off
	s_add_i32 m0, s33, 0x2000
	s_add_u32 s14, s14, 0x40080
	v_lshl_add_u64 v[178:179], v[230:231], 0, s[10:11]
	s_addc_u32 s15, s15, 0
	s_add_i32 s33, s51, s27
	global_load_lds_dwordx4 v[178:179], off
	v_lshl_add_u64 v[178:179], s[14:15], 0, v[132:133]
	s_mov_b32 m0, s33
	s_nop 0
	global_load_lds_dwordx4 v[178:179], off
	v_lshl_add_u64 v[178:179], s[14:15], 0, v[136:137]
	s_add_i32 m0, s33, 0x2000
	s_nop 0
	global_load_lds_dwordx4 v[178:179], off
	v_lshl_add_u64 v[178:179], v[232:233], 0, s[10:11]
	s_mov_b32 m0, s49
	s_nop 0
	global_load_lds_dwordx4 v[178:179], off
	v_lshl_add_u64 v[178:179], v[234:235], 0, s[10:11]
	s_mov_b32 m0, s52
	s_nop 0
	global_load_lds_dwordx4 v[178:179], off
	s_waitcnt vmcnt(8)
	s_waitcnt lgkmcnt(0)
	s_barrier
	s_setprio 1
	s_waitcnt lgkmcnt(0)
	v_mfma_f32_16x16x32_bf16 v[62:65], v[162:165], v[198:201], v[62:65]
	v_mfma_f32_16x16x32_bf16 v[54:57], v[170:173], v[198:201], v[54:57]
	v_mfma_f32_16x16x32_bf16 v[46:49], v[162:165], v[206:209], v[46:49]
	v_mfma_f32_16x16x32_bf16 v[38:41], v[170:173], v[206:209], v[38:41]
	v_mfma_f32_16x16x32_bf16 v[30:33], v[162:165], v[214:217], v[30:33]
	v_mfma_f32_16x16x32_bf16 v[22:25], v[170:173], v[214:217], v[22:25]
	v_mfma_f32_16x16x32_bf16 v[14:17], v[162:165], v[222:225], v[14:17]
	v_mfma_f32_16x16x32_bf16 v[6:9], v[170:173], v[222:225], v[6:9]
	v_mfma_f32_16x16x32_bf16 v[62:65], v[166:169], v[202:205], v[62:65]
	v_mfma_f32_16x16x32_bf16 v[54:57], v[174:177], v[202:205], v[54:57]
	v_mfma_f32_16x16x32_bf16 v[46:49], v[166:169], v[210:213], v[46:49]
	v_mfma_f32_16x16x32_bf16 v[38:41], v[174:177], v[210:213], v[38:41]
	v_mfma_f32_16x16x32_bf16 v[30:33], v[166:169], v[218:221], v[30:33]
	v_mfma_f32_16x16x32_bf16 v[22:25], v[174:177], v[218:221], v[22:25]
	v_mfma_f32_16x16x32_bf16 v[14:17], v[166:169], v[226:229], v[14:17]
	v_mfma_f32_16x16x32_bf16 v[6:9], v[174:177], v[226:229], v[6:9]
	s_setprio 0
	s_setprio 1
	v_mfma_f32_16x16x32_bf16 v[58:61], v[182:185], v[198:201], v[58:61]
	v_mfma_f32_16x16x32_bf16 v[50:53], v[190:193], v[198:201], v[50:53]
	v_mfma_f32_16x16x32_bf16 v[42:45], v[182:185], v[206:209], v[42:45]
	v_mfma_f32_16x16x32_bf16 v[34:37], v[190:193], v[206:209], v[34:37]
	v_mfma_f32_16x16x32_bf16 v[26:29], v[182:185], v[214:217], v[26:29]
	v_mfma_f32_16x16x32_bf16 v[18:21], v[190:193], v[214:217], v[18:21]
	v_mfma_f32_16x16x32_bf16 v[10:13], v[182:185], v[222:225], v[10:13]
	v_mfma_f32_16x16x32_bf16 v[2:5], v[190:193], v[222:225], v[2:5]
	v_mfma_f32_16x16x32_bf16 v[58:61], v[186:189], v[202:205], v[58:61]
	v_mfma_f32_16x16x32_bf16 v[50:53], v[194:197], v[202:205], v[50:53]
	v_mfma_f32_16x16x32_bf16 v[42:45], v[186:189], v[210:213], v[42:45]
	v_mfma_f32_16x16x32_bf16 v[34:37], v[194:197], v[210:213], v[34:37]
	v_mfma_f32_16x16x32_bf16 v[26:29], v[186:189], v[218:221], v[26:29]
	v_mfma_f32_16x16x32_bf16 v[18:21], v[194:197], v[218:221], v[18:21]
	v_mfma_f32_16x16x32_bf16 v[10:13], v[186:189], v[226:229], v[10:13]
	v_mfma_f32_16x16x32_bf16 v[2:5], v[194:197], v[226:229], v[2:5]
	s_setprio 0
	s_barrier
	s_add_i32 s67, s67, 2
	s_add_u32 s30, s30, 0x100
	s_addc_u32 s31, s31, 0
	s_add_u32 s65, s65, 0x100
	s_addc_u32 s66, s66, 0

.LBB0_361:
	s_add_u32 s62, s14, 0x100
	s_addc_u32 s63, s15, 0
	s_add_u32 s24, s24, 0xc000

	s_addc_u32 s25, s25, 0
	s_mov_b32 s64, -2
	s_waitcnt lgkmcnt(0)


	ds_read_b128 v[130:133], v170
	ds_read_b128 v[134:137], v170 offset:1024
	ds_read_b128 v[160:163], v170 offset:2048
	ds_read_b128 v[164:167], v170 offset:3072
	ds_read_b128 v[174:177], v171
	ds_read_b128 v[182:185], v171 offset:1024
	ds_read_b128 v[186:189], v171 offset:2048
	ds_read_b128 v[190:193], v171 offset:3072
	s_add_u32 s14, s24, 0x4000
	s_addc_u32 s15, s25, 0
	s_cmp_eq_u32 s64, 40
	s_cselect_b32 s28, s6, s14
	s_cselect_b32 s29, s7, s15
	s_cselect_b32 s26, s22, s62
	s_cselect_b32 s27, s23, s63
	s_add_u32 s14, s28, 0x8000
	s_addc_u32 s15, s29, 0
	v_lshl_add_u64 v[138:139], s[24:25], 0, v[152:153]
	s_add_i32 m0, s31, 0xc000
	ds_read_b128 v[194:197], v172
	ds_read_b128 v[198:201], v172 offset:1024
	ds_read_b128 v[202:205], v172 offset:2048
	ds_read_b128 v[206:209], v172 offset:3072
	ds_read_b128 v[210:213], v172 offset:4096
	ds_read_b128 v[214:217], v172 offset:5120
	ds_read_b128 v[218:221], v172 offset:6144
	ds_read_b128 v[222:225], v172 offset:7168
	global_load_lds_dwordx4 v[138:139], off
	v_lshl_add_u64 v[138:139], s[24:25], 0, v[154:155]
	s_add_i32 m0, s31, 0xe000
	s_nop 0
	global_load_lds_dwordx4 v[138:139], off
	s_waitcnt vmcnt(8)
	s_waitcnt lgkmcnt(0)
	s_barrier
	s_setprio 1
	s_waitcnt lgkmcnt(0)
	v_mfma_f32_16x16x32_bf16 v[126:129], v[130:133], v[194:197], 0
	v_mfma_f32_16x16x32_bf16 v[122:125], v[160:163], v[194:197], 0
	v_mfma_f32_16x16x32_bf16 v[110:113], v[130:133], v[202:205], 0
	v_mfma_f32_16x16x32_bf16 v[106:109], v[160:163], v[202:205], 0
	v_mfma_f32_16x16x32_bf16 v[94:97], v[130:133], v[210:213], 0
	v_mfma_f32_16x16x32_bf16 v[90:93], v[160:163], v[210:213], 0
	v_mfma_f32_16x16x32_bf16 v[78:81], v[130:133], v[218:221], 0
	v_mfma_f32_16x16x32_bf16 v[74:77], v[160:163], v[218:221], 0
	v_mfma_f32_16x16x32_bf16 v[126:129], v[134:137], v[198:201], v[126:129]
	v_mfma_f32_16x16x32_bf16 v[122:125], v[164:167], v[198:201], v[122:125]
	v_mfma_f32_16x16x32_bf16 v[110:113], v[134:137], v[206:209], v[110:113]
	v_mfma_f32_16x16x32_bf16 v[106:109], v[164:167], v[206:209], v[106:109]
	v_mfma_f32_16x16x32_bf16 v[94:97], v[134:137], v[214:217], v[94:97]
	v_mfma_f32_16x16x32_bf16 v[90:93], v[164:167], v[214:217], v[90:93]
	v_mfma_f32_16x16x32_bf16 v[78:81], v[134:137], v[222:225], v[78:81]
	v_mfma_f32_16x16x32_bf16 v[74:77], v[164:167], v[222:225], v[74:77]
	s_setprio 0
	s_setprio 1
	v_mfma_f32_16x16x32_bf16 v[118:121], v[174:177], v[194:197], 0
	v_mfma_f32_16x16x32_bf16 v[114:117], v[186:189], v[194:197], 0
	v_mfma_f32_16x16x32_bf16 v[102:105], v[174:177], v[202:205], 0
	v_mfma_f32_16x16x32_bf16 v[98:101], v[186:189], v[202:205], 0
	v_mfma_f32_16x16x32_bf16 v[86:89], v[174:177], v[210:213], 0
	v_mfma_f32_16x16x32_bf16 v[82:85], v[186:189], v[210:213], 0
	v_mfma_f32_16x16x32_bf16 v[70:73], v[174:177], v[218:221], 0
	v_mfma_f32_16x16x32_bf16 v[66:69], v[186:189], v[218:221], 0
	v_mfma_f32_16x16x32_bf16 v[118:121], v[182:185], v[198:201], v[118:121]
	v_mfma_f32_16x16x32_bf16 v[114:117], v[190:193], v[198:201], v[114:117]
	v_mfma_f32_16x16x32_bf16 v[102:105], v[182:185], v[206:209], v[102:105]
	v_mfma_f32_16x16x32_bf16 v[98:101], v[190:193], v[206:209], v[98:101]
	v_mfma_f32_16x16x32_bf16 v[86:89], v[182:185], v[214:217], v[86:89]
	v_mfma_f32_16x16x32_bf16 v[82:85], v[190:193], v[214:217], v[82:85]
	v_mfma_f32_16x16x32_bf16 v[70:73], v[182:185], v[222:225], v[70:73]
	v_mfma_f32_16x16x32_bf16 v[66:69], v[190:193], v[222:225], v[66:69]
	s_setprio 0
	s_barrier
	s_add_i32 s33, s53, s30
	v_lshl_add_u64 v[138:139], s[26:27], 0, v[144:145]
	s_mov_b32 m0, s33
	ds_read_b128 v[194:197], v172 offset:16384
	ds_read_b128 v[198:201], v172 offset:17408
	ds_read_b128 v[202:205], v172 offset:18432
	ds_read_b128 v[206:209], v172 offset:19456
	ds_read_b128 v[210:213], v172 offset:20480
	ds_read_b128 v[214:217], v172 offset:21504
	ds_read_b128 v[218:221], v172 offset:22528
	ds_read_b128 v[222:225], v172 offset:23552
	global_load_lds_dwordx4 v[138:139], off
	s_add_i32 m0, s33, 0x2000
	s_add_u32 s54, s26, 0xb0000
	v_lshl_add_u64 v[178:179], s[26:27], 0, v[148:149]
	s_addc_u32 s55, s27, 0
	s_add_i32 s33, s56, s30
	global_load_lds_dwordx4 v[178:179], off
	v_lshl_add_u64 v[226:227], s[54:55], 0, v[144:145]
	s_mov_b32 m0, s33
	s_nop 0
	global_load_lds_dwordx4 v[226:227], off
	v_lshl_add_u64 v[226:227], s[54:55], 0, v[148:149]
	s_add_i32 m0, s33, 0x2000
	s_nop 0
	global_load_lds_dwordx4 v[226:227], off
	v_lshl_add_u64 v[226:227], s[28:29], 0, v[142:143]
	s_mov_b32 m0, s31
	s_nop 0
	global_load_lds_dwordx4 v[226:227], off
	v_lshl_add_u64 v[226:227], s[28:29], 0, v[146:147]
	s_mov_b32 m0, s35
	s_nop 0
	global_load_lds_dwordx4 v[226:227], off
	s_waitcnt vmcnt(8)
	s_waitcnt lgkmcnt(0)
	s_barrier
	s_setprio 1
	s_waitcnt lgkmcnt(0)
	v_mfma_f32_16x16x32_bf16 v[62:65], v[130:133], v[194:197], 0
	v_mfma_f32_16x16x32_bf16 v[58:61], v[160:163], v[194:197], 0
	v_mfma_f32_16x16x32_bf16 v[46:49], v[130:133], v[202:205], 0
	v_mfma_f32_16x16x32_bf16 v[42:45], v[160:163], v[202:205], 0
	v_mfma_f32_16x16x32_bf16 v[30:33], v[130:133], v[210:213], 0
	v_mfma_f32_16x16x32_bf16 v[26:29], v[160:163], v[210:213], 0
	v_mfma_f32_16x16x32_bf16 v[14:17], v[130:133], v[218:221], 0
	v_mfma_f32_16x16x32_bf16 v[10:13], v[160:163], v[218:221], 0
	v_mfma_f32_16x16x32_bf16 v[62:65], v[134:137], v[198:201], v[62:65]
	v_mfma_f32_16x16x32_bf16 v[58:61], v[164:167], v[198:201], v[58:61]
	v_mfma_f32_16x16x32_bf16 v[46:49], v[134:137], v[206:209], v[46:49]
	v_mfma_f32_16x16x32_bf16 v[42:45], v[164:167], v[206:209], v[42:45]
	v_mfma_f32_16x16x32_bf16 v[30:33], v[134:137], v[214:217], v[30:33]
	v_mfma_f32_16x16x32_bf16 v[26:29], v[164:167], v[214:217], v[26:29]
	v_mfma_f32_16x16x32_bf16 v[14:17], v[134:137], v[222:225], v[14:17]
	v_mfma_f32_16x16x32_bf16 v[10:13], v[164:167], v[222:225], v[10:13]
	s_setprio 0
	s_setprio 1
	v_mfma_f32_16x16x32_bf16 v[54:57], v[174:177], v[194:197], 0
	v_mfma_f32_16x16x32_bf16 v[50:53], v[186:189], v[194:197], 0
	v_mfma_f32_16x16x32_bf16 v[38:41], v[174:177], v[202:205], 0
	v_mfma_f32_16x16x32_bf16 v[34:37], v[186:189], v[202:205], 0
	v_mfma_f32_16x16x32_bf16 v[22:25], v[174:177], v[210:213], 0
	v_mfma_f32_16x16x32_bf16 v[18:21], v[186:189], v[210:213], 0
	v_mfma_f32_16x16x32_bf16 v[6:9], v[174:177], v[218:221], 0
	v_mfma_f32_16x16x32_bf16 v[2:5], v[186:189], v[218:221], 0
	v_mfma_f32_16x16x32_bf16 v[54:57], v[182:185], v[198:201], v[54:57]
	v_mfma_f32_16x16x32_bf16 v[50:53], v[190:193], v[198:201], v[50:53]
	v_mfma_f32_16x16x32_bf16 v[38:41], v[182:185], v[206:209], v[38:41]
	v_mfma_f32_16x16x32_bf16 v[34:37], v[190:193], v[206:209], v[34:37]
	v_mfma_f32_16x16x32_bf16 v[22:25], v[182:185], v[214:217], v[22:25]
	v_mfma_f32_16x16x32_bf16 v[18:21], v[190:193], v[214:217], v[18:21]
	v_mfma_f32_16x16x32_bf16 v[6:9], v[182:185], v[222:225], v[6:9]
	v_mfma_f32_16x16x32_bf16 v[2:5], v[190:193], v[222:225], v[2:5]
	s_setprio 0
	s_barrier
	s_add_i32 s33, 0, 0x18000
	v_add_u32_e32 v150, s33, v168
	s_add_i32 s51, 0, 0x1c000
	ds_read_b128 v[130:133], v150
	ds_read_b128 v[134:137], v150 offset:1024
	ds_read_b128 v[160:163], v150 offset:2048
	ds_read_b128 v[164:167], v150 offset:3072
	v_add_u32_e32 v150, s51, v168
	ds_read_b128 v[174:177], v150
	ds_read_b128 v[182:185], v150 offset:1024
	ds_read_b128 v[186:189], v150 offset:2048
	ds_read_b128 v[190:193], v150 offset:3072
	s_add_u32 s28, s28, 0x4000
	s_addc_u32 s29, s29, 0
	s_mov_b32 m0, s40
	v_lshl_add_u64 v[226:227], s[28:29], 0, v[142:143]
	ds_read_b128 v[194:197], v172 offset:32768
	ds_read_b128 v[198:201], v172 offset:33792
	ds_read_b128 v[202:205], v172 offset:34816
	ds_read_b128 v[206:209], v172 offset:35840
	ds_read_b128 v[210:213], v172 offset:36864
	ds_read_b128 v[214:217], v172 offset:37888
	ds_read_b128 v[218:221], v172 offset:38912
	ds_read_b128 v[222:225], v172 offset:39936
	global_load_lds_dwordx4 v[226:227], off
	v_lshl_add_u64 v[226:227], s[28:29], 0, v[146:147]
	s_mov_b32 m0, s41
	s_nop 0
	global_load_lds_dwordx4 v[226:227], off
	s_waitcnt vmcnt(8)
	s_waitcnt lgkmcnt(0)
	s_barrier
	s_setprio 1
	s_waitcnt lgkmcnt(0)
	v_mfma_f32_16x16x32_bf16 v[126:129], v[130:133], v[194:197], v[126:129]
	v_mfma_f32_16x16x32_bf16 v[122:125], v[160:163], v[194:197], v[122:125]
	v_mfma_f32_16x16x32_bf16 v[110:113], v[130:133], v[202:205], v[110:113]
	v_mfma_f32_16x16x32_bf16 v[106:109], v[160:163], v[202:205], v[106:109]
	v_mfma_f32_16x16x32_bf16 v[94:97], v[130:133], v[210:213], v[94:97]
	v_mfma_f32_16x16x32_bf16 v[90:93], v[160:163], v[210:213], v[90:93]
	v_mfma_f32_16x16x32_bf16 v[78:81], v[130:133], v[218:221], v[78:81]
	v_mfma_f32_16x16x32_bf16 v[74:77], v[160:163], v[218:221], v[74:77]
	v_mfma_f32_16x16x32_bf16 v[126:129], v[134:137], v[198:201], v[126:129]
	v_mfma_f32_16x16x32_bf16 v[122:125], v[164:167], v[198:201], v[122:125]
	v_mfma_f32_16x16x32_bf16 v[110:113], v[134:137], v[206:209], v[110:113]
	v_mfma_f32_16x16x32_bf16 v[106:109], v[164:167], v[206:209], v[106:109]
	v_mfma_f32_16x16x32_bf16 v[94:97], v[134:137], v[214:217], v[94:97]
	v_mfma_f32_16x16x32_bf16 v[90:93], v[164:167], v[214:217], v[90:93]
	v_mfma_f32_16x16x32_bf16 v[78:81], v[134:137], v[222:225], v[78:81]
	v_mfma_f32_16x16x32_bf16 v[74:77], v[164:167], v[222:225], v[74:77]
	s_setprio 0
	s_setprio 1
	v_mfma_f32_16x16x32_bf16 v[118:121], v[174:177], v[194:197], v[118:121]
	v_mfma_f32_16x16x32_bf16 v[114:117], v[186:189], v[194:197], v[114:117]
	v_mfma_f32_16x16x32_bf16 v[102:105], v[174:177], v[202:205], v[102:105]
	v_mfma_f32_16x16x32_bf16 v[98:101], v[186:189], v[202:205], v[98:101]
	v_mfma_f32_16x16x32_bf16 v[86:89], v[174:177], v[210:213], v[86:89]
	v_mfma_f32_16x16x32_bf16 v[82:85], v[186:189], v[210:213], v[82:85]
	v_mfma_f32_16x16x32_bf16 v[70:73], v[174:177], v[218:221], v[70:73]
	v_mfma_f32_16x16x32_bf16 v[66:69], v[186:189], v[218:221], v[66:69]
	v_mfma_f32_16x16x32_bf16 v[118:121], v[182:185], v[198:201], v[118:121]
	v_mfma_f32_16x16x32_bf16 v[114:117], v[190:193], v[198:201], v[114:117]
	v_mfma_f32_16x16x32_bf16 v[102:105], v[182:185], v[206:209], v[102:105]
	v_mfma_f32_16x16x32_bf16 v[98:101], v[190:193], v[206:209], v[98:101]
	v_mfma_f32_16x16x32_bf16 v[86:89], v[182:185], v[214:217], v[86:89]
	v_mfma_f32_16x16x32_bf16 v[82:85], v[190:193], v[214:217], v[82:85]
	v_mfma_f32_16x16x32_bf16 v[70:73], v[182:185], v[222:225], v[70:73]
	v_mfma_f32_16x16x32_bf16 v[66:69], v[190:193], v[222:225], v[66:69]
	s_setprio 0
	s_barrier
	s_add_i32 s28, s33, s30
	v_lshl_add_u64 v[138:139], v[138:139], 0, s[12:13]
	s_mov_b32 m0, s28
	ds_read_b128 v[194:197], v172 offset:49152
	ds_read_b128 v[198:201], v172 offset:50176
	ds_read_b128 v[202:205], v172 offset:51200
	ds_read_b128 v[206:209], v172 offset:52224
	ds_read_b128 v[210:213], v172 offset:53248
	ds_read_b128 v[214:217], v172 offset:54272
	ds_read_b128 v[218:221], v172 offset:55296
	ds_read_b128 v[222:225], v172 offset:56320
	global_load_lds_dwordx4 v[138:139], off
	s_add_i32 m0, s28, 0x2000
	s_add_u32 s26, s26, 0xb0080
	v_lshl_add_u64 v[138:139], v[178:179], 0, s[12:13]
	s_addc_u32 s27, s27, 0
	s_add_i32 s28, s51, s30
	global_load_lds_dwordx4 v[138:139], off
	v_lshl_add_u64 v[138:139], s[26:27], 0, v[144:145]
	s_mov_b32 m0, s28
	s_nop 0
	global_load_lds_dwordx4 v[138:139], off
	v_lshl_add_u64 v[138:139], s[26:27], 0, v[148:149]
	s_add_i32 m0, s28, 0x2000
	s_nop 0
	global_load_lds_dwordx4 v[138:139], off
	v_lshl_add_u64 v[138:139], s[14:15], 0, v[142:143]
	s_mov_b32 m0, s46
	s_nop 0
	global_load_lds_dwordx4 v[138:139], off
	v_lshl_add_u64 v[138:139], s[14:15], 0, v[146:147]
	s_mov_b32 m0, s47
	s_nop 0
	global_load_lds_dwordx4 v[138:139], off
	s_waitcnt vmcnt(8)
	s_waitcnt lgkmcnt(0)
	s_barrier
	s_setprio 1
	s_waitcnt lgkmcnt(0)
	v_mfma_f32_16x16x32_bf16 v[62:65], v[130:133], v[194:197], v[62:65]
	v_mfma_f32_16x16x32_bf16 v[58:61], v[160:163], v[194:197], v[58:61]
	v_mfma_f32_16x16x32_bf16 v[46:49], v[130:133], v[202:205], v[46:49]
	v_mfma_f32_16x16x32_bf16 v[42:45], v[160:163], v[202:205], v[42:45]
	v_mfma_f32_16x16x32_bf16 v[30:33], v[130:133], v[210:213], v[30:33]
	v_mfma_f32_16x16x32_bf16 v[26:29], v[160:163], v[210:213], v[26:29]
	v_mfma_f32_16x16x32_bf16 v[14:17], v[130:133], v[218:221], v[14:17]
	v_mfma_f32_16x16x32_bf16 v[10:13], v[160:163], v[218:221], v[10:13]
	v_mfma_f32_16x16x32_bf16 v[62:65], v[134:137], v[198:201], v[62:65]
	v_mfma_f32_16x16x32_bf16 v[58:61], v[164:167], v[198:201], v[58:61]
	v_mfma_f32_16x16x32_bf16 v[46:49], v[134:137], v[206:209], v[46:49]
	v_mfma_f32_16x16x32_bf16 v[42:45], v[164:167], v[206:209], v[42:45]
	v_mfma_f32_16x16x32_bf16 v[30:33], v[134:137], v[214:217], v[30:33]
	v_mfma_f32_16x16x32_bf16 v[26:29], v[164:167], v[214:217], v[26:29]
	v_mfma_f32_16x16x32_bf16 v[14:17], v[134:137], v[222:225], v[14:17]
	v_mfma_f32_16x16x32_bf16 v[10:13], v[164:167], v[222:225], v[10:13]
	s_setprio 0
	s_setprio 1
	v_mfma_f32_16x16x32_bf16 v[54:57], v[174:177], v[194:197], v[54:57]
	v_mfma_f32_16x16x32_bf16 v[50:53], v[186:189], v[194:197], v[50:53]
	v_mfma_f32_16x16x32_bf16 v[38:41], v[174:177], v[202:205], v[38:41]
	v_mfma_f32_16x16x32_bf16 v[34:37], v[186:189], v[202:205], v[34:37]
	v_mfma_f32_16x16x32_bf16 v[22:25], v[174:177], v[210:213], v[22:25]
	v_mfma_f32_16x16x32_bf16 v[18:21], v[186:189], v[210:213], v[18:21]
	v_mfma_f32_16x16x32_bf16 v[6:9], v[174:177], v[218:221], v[6:9]
	v_mfma_f32_16x16x32_bf16 v[2:5], v[186:189], v[218:221], v[2:5]
	v_mfma_f32_16x16x32_bf16 v[54:57], v[182:185], v[198:201], v[54:57]
	v_mfma_f32_16x16x32_bf16 v[50:53], v[190:193], v[198:201], v[50:53]
	v_mfma_f32_16x16x32_bf16 v[38:41], v[182:185], v[206:209], v[38:41]
	v_mfma_f32_16x16x32_bf16 v[34:37], v[190:193], v[206:209], v[34:37]
	v_mfma_f32_16x16x32_bf16 v[22:25], v[182:185], v[214:217], v[22:25]
	v_mfma_f32_16x16x32_bf16 v[18:21], v[190:193], v[214:217], v[18:21]
	v_mfma_f32_16x16x32_bf16 v[6:9], v[182:185], v[222:225], v[6:9]
	v_mfma_f32_16x16x32_bf16 v[2:5], v[190:193], v[222:225], v[2:5]
	s_setprio 0
	s_barrier
	s_add_i32 s64, s64, 2
	s_add_u32 s62, s62, 0x100
	s_addc_u32 s63, s63, 0
	s_add_u32 s24, s24, 0x10000
	s_addc_u32 s25, s25, 0

.LBB0_549:
	s_ashr_i32 s27, s26, 31
	s_lshl_b64 s[28:29], s[26:27], 19
	s_add_u32 s28, s92, s28
	s_addc_u32 s29, s93, s29
	s_and_b64 s[30:31], s[2:3], exec
	s_cselect_b32 s5, s29, s41
	s_cselect_b32 s7, s28, s40
	s_ashr_i32 s25, s24, 31
	s_lshl_b64 s[30:31], s[24:25], 19
	v_readlane_b32 s36, v244, 35
	v_readlane_b32 s37, v244, 36
	s_add_u32 s30, s36, s30
	s_addc_u32 s31, s37, s31
	s_and_b64 s[42:43], s[2:3], exec
	s_cselect_b32 s25, s31, s15
	s_cselect_b32 s27, s30, s14
	s_add_u32 s40, s40, 0x40080
	s_addc_u32 s41, s41, 0
	s_add_u32 s74, s14, 0x100

	s_addc_u32 s75, s15, 0
	s_mov_b32 s86, -2


	ds_read_b128 v[158:161], v170
	ds_read_b128 v[174:177], v170 offset:1024
	ds_read_b128 v[182:185], v170 offset:2048
	ds_read_b128 v[186:189], v170 offset:3072
	ds_read_b128 v[190:193], v171
	ds_read_b128 v[194:197], v171 offset:1024
	ds_read_b128 v[198:201], v171 offset:2048
	ds_read_b128 v[202:205], v171 offset:3072
	s_add_u32 s14, s40, 0xfffc0080
	s_addc_u32 s15, s41, -1
	s_cmp_eq_u32 s86, 12
	s_cselect_b32 s43, s5, s15
	s_cselect_b32 s42, s7, s14
	s_cselect_b32 s15, s25, s75
	s_cselect_b32 s14, s27, s74
	v_lshl_add_u64 v[162:163], s[40:41], 0, v[150:151]
	s_add_i32 m0, s48, 0xc000
	ds_read_b128 v[206:209], v172
	ds_read_b128 v[210:213], v172 offset:1024
	ds_read_b128 v[214:217], v172 offset:2048
	ds_read_b128 v[218:221], v172 offset:3072
	ds_read_b128 v[222:225], v172 offset:4096
	ds_read_b128 v[226:229], v172 offset:5120
	ds_read_b128 v[230:233], v172 offset:6144
	ds_read_b128 v[234:237], v172 offset:7168
	global_load_lds_dwordx4 v[162:163], off
	v_lshl_add_u64 v[162:163], s[40:41], 0, v[152:153]
	s_add_i32 m0, s48, 0xe000
	s_nop 0
	global_load_lds_dwordx4 v[162:163], off
	s_waitcnt vmcnt(8)
	s_waitcnt lgkmcnt(0)
	s_barrier
	s_setprio 1
	s_waitcnt lgkmcnt(0)
	v_mfma_f32_16x16x32_bf16 v[126:129], v[158:161], v[206:209], 0
	v_mfma_f32_16x16x32_bf16 v[122:125], v[182:185], v[206:209], 0
	v_mfma_f32_16x16x32_bf16 v[110:113], v[158:161], v[214:217], 0
	v_mfma_f32_16x16x32_bf16 v[106:109], v[182:185], v[214:217], 0
	v_mfma_f32_16x16x32_bf16 v[94:97], v[158:161], v[222:225], 0
	v_mfma_f32_16x16x32_bf16 v[90:93], v[182:185], v[222:225], 0
	v_mfma_f32_16x16x32_bf16 v[78:81], v[158:161], v[230:233], 0
	v_mfma_f32_16x16x32_bf16 v[74:77], v[182:185], v[230:233], 0
	v_mfma_f32_16x16x32_bf16 v[126:129], v[174:177], v[210:213], v[126:129]
	v_mfma_f32_16x16x32_bf16 v[122:125], v[186:189], v[210:213], v[122:125]
	v_mfma_f32_16x16x32_bf16 v[110:113], v[174:177], v[218:221], v[110:113]
	v_mfma_f32_16x16x32_bf16 v[106:109], v[186:189], v[218:221], v[106:109]
	v_mfma_f32_16x16x32_bf16 v[94:97], v[174:177], v[226:229], v[94:97]
	v_mfma_f32_16x16x32_bf16 v[90:93], v[186:189], v[226:229], v[90:93]
	v_mfma_f32_16x16x32_bf16 v[78:81], v[174:177], v[234:237], v[78:81]
	v_mfma_f32_16x16x32_bf16 v[74:77], v[186:189], v[234:237], v[74:77]
	s_setprio 0
	s_setprio 1
	v_mfma_f32_16x16x32_bf16 v[118:121], v[190:193], v[206:209], 0
	v_mfma_f32_16x16x32_bf16 v[114:117], v[198:201], v[206:209], 0
	v_mfma_f32_16x16x32_bf16 v[102:105], v[190:193], v[214:217], 0
	v_mfma_f32_16x16x32_bf16 v[98:101], v[198:201], v[214:217], 0
	v_mfma_f32_16x16x32_bf16 v[86:89], v[190:193], v[222:225], 0
	v_mfma_f32_16x16x32_bf16 v[82:85], v[198:201], v[222:225], 0
	v_mfma_f32_16x16x32_bf16 v[70:73], v[190:193], v[230:233], 0
	v_mfma_f32_16x16x32_bf16 v[66:69], v[198:201], v[230:233], 0
	v_mfma_f32_16x16x32_bf16 v[118:121], v[194:197], v[210:213], v[118:121]
	v_mfma_f32_16x16x32_bf16 v[114:117], v[202:205], v[210:213], v[114:117]
	v_mfma_f32_16x16x32_bf16 v[102:105], v[194:197], v[218:221], v[102:105]
	v_mfma_f32_16x16x32_bf16 v[98:101], v[202:205], v[218:221], v[98:101]
	v_mfma_f32_16x16x32_bf16 v[86:89], v[194:197], v[226:229], v[86:89]
	v_mfma_f32_16x16x32_bf16 v[82:85], v[202:205], v[226:229], v[82:85]
	v_mfma_f32_16x16x32_bf16 v[70:73], v[194:197], v[234:237], v[70:73]
	v_mfma_f32_16x16x32_bf16 v[66:69], v[202:205], v[234:237], v[66:69]
	s_setprio 0
	s_barrier
	s_add_i32 s33, s63, s35
	v_lshl_add_u64 v[162:163], s[14:15], 0, v[132:133]
	s_mov_b32 m0, s33
	ds_read_b128 v[206:209], v172 offset:16384
	ds_read_b128 v[210:213], v172 offset:17408
	ds_read_b128 v[214:217], v172 offset:18432
	ds_read_b128 v[218:221], v172 offset:19456
	ds_read_b128 v[222:225], v172 offset:20480
	ds_read_b128 v[226:229], v172 offset:21504
	ds_read_b128 v[230:233], v172 offset:22528
	ds_read_b128 v[234:237], v172 offset:23552
	global_load_lds_dwordx4 v[162:163], off
	s_add_i32 m0, s33, 0x2000
	s_add_u32 s54, s14, 0x40000
	v_lshl_add_u64 v[178:179], s[14:15], 0, v[136:137]
	s_addc_u32 s55, s15, 0
	s_add_i32 s33, s64, s35
	global_load_lds_dwordx4 v[178:179], off
	v_lshl_add_u64 v[238:239], s[54:55], 0, v[132:133]
	s_mov_b32 m0, s33
	v_lshl_add_u64 v[240:241], s[42:43], 0, v[134:135]
	global_load_lds_dwordx4 v[238:239], off
	v_lshl_add_u64 v[238:239], s[54:55], 0, v[136:137]
	s_add_i32 m0, s33, 0x2000
	s_nop 0
	global_load_lds_dwordx4 v[238:239], off
	v_lshl_add_u64 v[238:239], s[42:43], 0, v[130:131]
	s_mov_b32 m0, s48
	s_nop 0
	global_load_lds_dwordx4 v[238:239], off
	s_mov_b32 m0, s49
	s_nop 0
	global_load_lds_dwordx4 v[240:241], off
	s_waitcnt vmcnt(8)
	s_waitcnt lgkmcnt(0)
	s_barrier
	s_setprio 1
	s_waitcnt lgkmcnt(0)
	v_mfma_f32_16x16x32_bf16 v[62:65], v[158:161], v[206:209], 0
	v_mfma_f32_16x16x32_bf16 v[58:61], v[182:185], v[206:209], 0
	v_mfma_f32_16x16x32_bf16 v[46:49], v[158:161], v[214:217], 0
	v_mfma_f32_16x16x32_bf16 v[42:45], v[182:185], v[214:217], 0
	v_mfma_f32_16x16x32_bf16 v[30:33], v[158:161], v[222:225], 0
	v_mfma_f32_16x16x32_bf16 v[26:29], v[182:185], v[222:225], 0
	v_mfma_f32_16x16x32_bf16 v[14:17], v[158:161], v[230:233], 0
	v_mfma_f32_16x16x32_bf16 v[10:13], v[182:185], v[230:233], 0
	v_mfma_f32_16x16x32_bf16 v[62:65], v[174:177], v[210:213], v[62:65]
	v_mfma_f32_16x16x32_bf16 v[58:61], v[186:189], v[210:213], v[58:61]
	v_mfma_f32_16x16x32_bf16 v[46:49], v[174:177], v[218:221], v[46:49]
	v_mfma_f32_16x16x32_bf16 v[42:45], v[186:189], v[218:221], v[42:45]
	v_mfma_f32_16x16x32_bf16 v[30:33], v[174:177], v[226:229], v[30:33]
	v_mfma_f32_16x16x32_bf16 v[26:29], v[186:189], v[226:229], v[26:29]
	v_mfma_f32_16x16x32_bf16 v[14:17], v[174:177], v[234:237], v[14:17]
	v_mfma_f32_16x16x32_bf16 v[10:13], v[186:189], v[234:237], v[10:13]
	s_setprio 0
	s_setprio 1
	v_mfma_f32_16x16x32_bf16 v[54:57], v[190:193], v[206:209], 0
	v_mfma_f32_16x16x32_bf16 v[50:53], v[198:201], v[206:209], 0
	v_mfma_f32_16x16x32_bf16 v[38:41], v[190:193], v[214:217], 0
	v_mfma_f32_16x16x32_bf16 v[34:37], v[198:201], v[214:217], 0
	v_mfma_f32_16x16x32_bf16 v[22:25], v[190:193], v[222:225], 0
	v_mfma_f32_16x16x32_bf16 v[18:21], v[198:201], v[222:225], 0
	v_mfma_f32_16x16x32_bf16 v[6:9], v[190:193], v[230:233], 0
	v_mfma_f32_16x16x32_bf16 v[2:5], v[198:201], v[230:233], 0
	v_mfma_f32_16x16x32_bf16 v[54:57], v[194:197], v[210:213], v[54:57]
	v_mfma_f32_16x16x32_bf16 v[50:53], v[202:205], v[210:213], v[50:53]
	v_mfma_f32_16x16x32_bf16 v[38:41], v[194:197], v[218:221], v[38:41]
	v_mfma_f32_16x16x32_bf16 v[34:37], v[202:205], v[218:221], v[34:37]
	v_mfma_f32_16x16x32_bf16 v[22:25], v[194:197], v[226:229], v[22:25]
	v_mfma_f32_16x16x32_bf16 v[18:21], v[202:205], v[226:229], v[18:21]
	v_mfma_f32_16x16x32_bf16 v[6:9], v[194:197], v[234:237], v[6:9]
	v_mfma_f32_16x16x32_bf16 v[2:5], v[202:205], v[234:237], v[2:5]
	s_setprio 0
	s_barrier
	s_add_i32 s33, 0, 0x18000
	v_add_u32_e32 v138, s33, v165
	s_add_i32 s51, 0, 0x1c000
	ds_read_b128 v[158:161], v138
	ds_read_b128 v[174:177], v138 offset:1024
	ds_read_b128 v[182:185], v138 offset:2048
	ds_read_b128 v[186:189], v138 offset:3072
	v_add_u32_e32 v138, s51, v165
	ds_read_b128 v[190:193], v138
	ds_read_b128 v[194:197], v138 offset:1024
	ds_read_b128 v[198:201], v138 offset:2048
	ds_read_b128 v[202:205], v138 offset:3072
	s_add_u32 s42, s42, 0x40000
	s_addc_u32 s43, s43, 0
	s_mov_b32 m0, s52
	v_lshl_add_u64 v[242:243], s[42:43], 0, v[130:131]
	ds_read_b128 v[206:209], v172 offset:32768
	ds_read_b128 v[210:213], v172 offset:33792
	ds_read_b128 v[214:217], v172 offset:34816
	ds_read_b128 v[218:221], v172 offset:35840
	ds_read_b128 v[222:225], v172 offset:36864
	ds_read_b128 v[226:229], v172 offset:37888
	ds_read_b128 v[230:233], v172 offset:38912
	ds_read_b128 v[234:237], v172 offset:39936
	global_load_lds_dwordx4 v[242:243], off
	v_lshl_add_u64 v[242:243], s[42:43], 0, v[134:135]
	s_mov_b32 m0, s53
	s_nop 0
	global_load_lds_dwordx4 v[242:243], off
	s_waitcnt vmcnt(8)
	s_waitcnt lgkmcnt(0)
	s_barrier
	s_setprio 1
	s_waitcnt lgkmcnt(0)
	v_mfma_f32_16x16x32_bf16 v[126:129], v[158:161], v[206:209], v[126:129]
	v_mfma_f32_16x16x32_bf16 v[122:125], v[182:185], v[206:209], v[122:125]
	v_mfma_f32_16x16x32_bf16 v[110:113], v[158:161], v[214:217], v[110:113]
	v_mfma_f32_16x16x32_bf16 v[106:109], v[182:185], v[214:217], v[106:109]
	v_mfma_f32_16x16x32_bf16 v[94:97], v[158:161], v[222:225], v[94:97]
	v_mfma_f32_16x16x32_bf16 v[90:93], v[182:185], v[222:225], v[90:93]
	v_mfma_f32_16x16x32_bf16 v[78:81], v[158:161], v[230:233], v[78:81]
	v_mfma_f32_16x16x32_bf16 v[74:77], v[182:185], v[230:233], v[74:77]
	v_mfma_f32_16x16x32_bf16 v[126:129], v[174:177], v[210:213], v[126:129]
	v_mfma_f32_16x16x32_bf16 v[122:125], v[186:189], v[210:213], v[122:125]
	v_mfma_f32_16x16x32_bf16 v[110:113], v[174:177], v[218:221], v[110:113]
	v_mfma_f32_16x16x32_bf16 v[106:109], v[186:189], v[218:221], v[106:109]
	v_mfma_f32_16x16x32_bf16 v[94:97], v[174:177], v[226:229], v[94:97]
	v_mfma_f32_16x16x32_bf16 v[90:93], v[186:189], v[226:229], v[90:93]
	v_mfma_f32_16x16x32_bf16 v[78:81], v[174:177], v[234:237], v[78:81]
	v_mfma_f32_16x16x32_bf16 v[74:77], v[186:189], v[234:237], v[74:77]
	s_setprio 0
	s_setprio 1
	v_mfma_f32_16x16x32_bf16 v[118:121], v[190:193], v[206:209], v[118:121]
	v_mfma_f32_16x16x32_bf16 v[114:117], v[198:201], v[206:209], v[114:117]
	v_mfma_f32_16x16x32_bf16 v[102:105], v[190:193], v[214:217], v[102:105]
	v_mfma_f32_16x16x32_bf16 v[98:101], v[198:201], v[214:217], v[98:101]
	v_mfma_f32_16x16x32_bf16 v[86:89], v[190:193], v[222:225], v[86:89]
	v_mfma_f32_16x16x32_bf16 v[82:85], v[198:201], v[222:225], v[82:85]
	v_mfma_f32_16x16x32_bf16 v[70:73], v[190:193], v[230:233], v[70:73]
	v_mfma_f32_16x16x32_bf16 v[66:69], v[198:201], v[230:233], v[66:69]
	v_mfma_f32_16x16x32_bf16 v[118:121], v[194:197], v[210:213], v[118:121]
	v_mfma_f32_16x16x32_bf16 v[114:117], v[202:205], v[210:213], v[114:117]
	v_mfma_f32_16x16x32_bf16 v[102:105], v[194:197], v[218:221], v[102:105]
	v_mfma_f32_16x16x32_bf16 v[98:101], v[202:205], v[218:221], v[98:101]
	v_mfma_f32_16x16x32_bf16 v[86:89], v[194:197], v[226:229], v[86:89]
	v_mfma_f32_16x16x32_bf16 v[82:85], v[202:205], v[226:229], v[82:85]
	v_mfma_f32_16x16x32_bf16 v[70:73], v[194:197], v[234:237], v[70:73]
	v_mfma_f32_16x16x32_bf16 v[66:69], v[202:205], v[234:237], v[66:69]
	s_setprio 0
	s_barrier
	s_add_i32 s33, s33, s35
	v_lshl_add_u64 v[162:163], v[162:163], 0, s[20:21]
	s_mov_b32 m0, s33
	ds_read_b128 v[206:209], v172 offset:49152
	ds_read_b128 v[210:213], v172 offset:50176
	ds_read_b128 v[214:217], v172 offset:51200
	ds_read_b128 v[218:221], v172 offset:52224
	ds_read_b128 v[222:225], v172 offset:53248
	ds_read_b128 v[226:229], v172 offset:54272
	ds_read_b128 v[230:233], v172 offset:55296
	ds_read_b128 v[234:237], v172 offset:56320
	global_load_lds_dwordx4 v[162:163], off
	s_add_i32 m0, s33, 0x2000
	s_add_u32 s14, s14, 0x40080
	v_lshl_add_u64 v[162:163], v[178:179], 0, s[20:21]
	s_addc_u32 s15, s15, 0
	s_add_i32 s33, s51, s35
	global_load_lds_dwordx4 v[162:163], off
	v_lshl_add_u64 v[162:163], s[14:15], 0, v[132:133]
	s_mov_b32 m0, s33
	s_nop 0
	global_load_lds_dwordx4 v[162:163], off
	v_lshl_add_u64 v[162:163], s[14:15], 0, v[136:137]
	s_add_i32 m0, s33, 0x2000
	s_nop 0
	global_load_lds_dwordx4 v[162:163], off
	v_lshl_add_u64 v[162:163], v[238:239], 0, s[20:21]
	s_mov_b32 m0, s58
	s_nop 0
	global_load_lds_dwordx4 v[162:163], off
	v_lshl_add_u64 v[162:163], v[240:241], 0, s[20:21]
	s_mov_b32 m0, s59
	s_nop 0
	global_load_lds_dwordx4 v[162:163], off
	s_waitcnt vmcnt(8)
	s_waitcnt lgkmcnt(0)
	s_barrier
	s_setprio 1
	s_waitcnt lgkmcnt(0)
	v_mfma_f32_16x16x32_bf16 v[62:65], v[158:161], v[206:209], v[62:65]
	v_mfma_f32_16x16x32_bf16 v[58:61], v[182:185], v[206:209], v[58:61]
	v_mfma_f32_16x16x32_bf16 v[46:49], v[158:161], v[214:217], v[46:49]
	v_mfma_f32_16x16x32_bf16 v[42:45], v[182:185], v[214:217], v[42:45]
	v_mfma_f32_16x16x32_bf16 v[30:33], v[158:161], v[222:225], v[30:33]
	v_mfma_f32_16x16x32_bf16 v[26:29], v[182:185], v[222:225], v[26:29]
	v_mfma_f32_16x16x32_bf16 v[14:17], v[158:161], v[230:233], v[14:17]
	v_mfma_f32_16x16x32_bf16 v[10:13], v[182:185], v[230:233], v[10:13]
	v_mfma_f32_16x16x32_bf16 v[62:65], v[174:177], v[210:213], v[62:65]
	v_mfma_f32_16x16x32_bf16 v[58:61], v[186:189], v[210:213], v[58:61]
	v_mfma_f32_16x16x32_bf16 v[46:49], v[174:177], v[218:221], v[46:49]
	v_mfma_f32_16x16x32_bf16 v[42:45], v[186:189], v[218:221], v[42:45]
	v_mfma_f32_16x16x32_bf16 v[30:33], v[174:177], v[226:229], v[30:33]
	v_mfma_f32_16x16x32_bf16 v[26:29], v[186:189], v[226:229], v[26:29]
	v_mfma_f32_16x16x32_bf16 v[14:17], v[174:177], v[234:237], v[14:17]
	v_mfma_f32_16x16x32_bf16 v[10:13], v[186:189], v[234:237], v[10:13]
	s_setprio 0
	s_setprio 1
	v_mfma_f32_16x16x32_bf16 v[54:57], v[190:193], v[206:209], v[54:57]
	v_mfma_f32_16x16x32_bf16 v[50:53], v[198:201], v[206:209], v[50:53]
	v_mfma_f32_16x16x32_bf16 v[38:41], v[190:193], v[214:217], v[38:41]
	v_mfma_f32_16x16x32_bf16 v[34:37], v[198:201], v[214:217], v[34:37]
	v_mfma_f32_16x16x32_bf16 v[22:25], v[190:193], v[222:225], v[22:25]
	v_mfma_f32_16x16x32_bf16 v[18:21], v[198:201], v[222:225], v[18:21]
	v_mfma_f32_16x16x32_bf16 v[6:9], v[190:193], v[230:233], v[6:9]
	v_mfma_f32_16x16x32_bf16 v[2:5], v[198:201], v[230:233], v[2:5]
	v_mfma_f32_16x16x32_bf16 v[54:57], v[194:197], v[210:213], v[54:57]
	v_mfma_f32_16x16x32_bf16 v[50:53], v[202:205], v[210:213], v[50:53]
	v_mfma_f32_16x16x32_bf16 v[38:41], v[194:197], v[218:221], v[38:41]
	v_mfma_f32_16x16x32_bf16 v[34:37], v[202:205], v[218:221], v[34:37]
	v_mfma_f32_16x16x32_bf16 v[22:25], v[194:197], v[226:229], v[22:25]
	v_mfma_f32_16x16x32_bf16 v[18:21], v[202:205], v[226:229], v[18:21]
	v_mfma_f32_16x16x32_bf16 v[6:9], v[194:197], v[234:237], v[6:9]
	v_mfma_f32_16x16x32_bf16 v[2:5], v[202:205], v[234:237], v[2:5]
	s_setprio 0
	s_barrier
	s_add_i32 s86, s86, 2
	s_add_u32 s40, s40, 0x100
	s_addc_u32 s41, s41, 0
	s_add_u32 s74, s74, 0x100
	s_addc_u32 s75, s75, 0

.LBB0_753:
	s_ashr_i32 s17, s16, 31
	s_lshl_b64 s[20:21], s[16:17], 19
	s_add_u32 s20, s8, s20
	s_addc_u32 s21, s9, s21
	s_and_b64 s[24:25], s[24:25], exec
	s_cselect_b32 s17, s21, s15
	s_cselect_b32 s52, s20, s14
	s_add_u32 s22, s22, 0x48080
	s_addc_u32 s23, s23, 0
	s_add_u32 s53, s14, 0x100

	s_addc_u32 s56, s15, 0
	s_mov_b32 s57, -2


	ds_read_b128 v[86:89], v82
	ds_read_b128 v[90:93], v82 offset:1024
	ds_read_b128 v[94:97], v82 offset:2048
	ds_read_b128 v[98:101], v82 offset:3072
	s_add_u32 s14, s22, 0xfffb8080
	s_addc_u32 s15, s23, -1
	s_cmp_eq_u32 s57, 12
	s_cselect_b32 s25, s19, s15
	s_cselect_b32 s24, s18, s14
	s_cselect_b32 s15, s17, s56
	s_cselect_b32 s14, s52, s53
	s_mov_b32 m0, s38
	v_lshl_add_u64 v[134:135], s[22:23], 0, v[76:77]
	ds_read_b128 v[102:105], v83
	ds_read_b128 v[106:109], v83 offset:1024
	ds_read_b128 v[110:113], v83 offset:2048
	ds_read_b128 v[114:117], v83 offset:3072
	ds_read_b128 v[118:121], v83 offset:4096
	ds_read_b128 v[122:125], v83 offset:5120
	ds_read_b128 v[126:129], v83 offset:6144
	ds_read_b128 v[130:133], v83 offset:7168
	global_load_lds_dwordx4 v[134:135], off
	v_lshl_add_u64 v[134:135], s[22:23], 0, v[78:79]
	s_mov_b32 m0, s39
	s_nop 0
	global_load_lds_dwordx4 v[134:135], off
	s_waitcnt vmcnt(8)
	s_waitcnt lgkmcnt(0)
	s_barrier
	s_setprio 1
	s_waitcnt lgkmcnt(0)
	v_mfma_f32_16x16x32_bf16 v[62:65], v[86:89], v[102:105], 0
	v_mfma_f32_16x16x32_bf16 v[58:61], v[94:97], v[102:105], 0
	v_mfma_f32_16x16x32_bf16 v[54:57], v[86:89], v[110:113], 0
	v_mfma_f32_16x16x32_bf16 v[50:53], v[94:97], v[110:113], 0
	v_mfma_f32_16x16x32_bf16 v[46:49], v[86:89], v[118:121], 0
	v_mfma_f32_16x16x32_bf16 v[42:45], v[94:97], v[118:121], 0
	v_mfma_f32_16x16x32_bf16 v[38:41], v[86:89], v[126:129], 0
	v_mfma_f32_16x16x32_bf16 v[34:37], v[94:97], v[126:129], 0
	v_mfma_f32_16x16x32_bf16 v[62:65], v[90:93], v[106:109], v[62:65]
	v_mfma_f32_16x16x32_bf16 v[58:61], v[98:101], v[106:109], v[58:61]
	v_mfma_f32_16x16x32_bf16 v[54:57], v[90:93], v[114:117], v[54:57]
	v_mfma_f32_16x16x32_bf16 v[50:53], v[98:101], v[114:117], v[50:53]
	v_mfma_f32_16x16x32_bf16 v[46:49], v[90:93], v[122:125], v[46:49]
	v_mfma_f32_16x16x32_bf16 v[42:45], v[98:101], v[122:125], v[42:45]
	v_mfma_f32_16x16x32_bf16 v[38:41], v[90:93], v[130:133], v[38:41]
	v_mfma_f32_16x16x32_bf16 v[34:37], v[98:101], v[130:133], v[34:37]
	s_setprio 0
	s_setprio 1
	s_setprio 0
	s_barrier
	s_mov_b32 m0, s40
	v_lshl_add_u64 v[134:135], s[14:15], 0, v[70:71]
	s_add_u32 s54, s14, 0x40000
	ds_read_b128 v[102:105], v83 offset:16384
	ds_read_b128 v[106:109], v83 offset:17408
	ds_read_b128 v[110:113], v83 offset:18432
	ds_read_b128 v[114:117], v83 offset:19456
	ds_read_b128 v[118:121], v83 offset:20480
	ds_read_b128 v[122:125], v83 offset:21504
	ds_read_b128 v[126:129], v83 offset:22528
	ds_read_b128 v[130:133], v83 offset:23552
	global_load_lds_dwordx4 v[134:135], off
	v_lshl_add_u64 v[136:137], s[14:15], 0, v[66:67]
	s_mov_b32 m0, s41
	s_addc_u32 s55, s15, 0
	global_load_lds_dwordx4 v[136:137], off
	v_lshl_add_u64 v[138:139], s[54:55], 0, v[70:71]
	s_mov_b32 m0, s26
	v_lshl_add_u64 v[140:141], s[24:25], 0, v[68:69]
	global_load_lds_dwordx4 v[138:139], off
	v_lshl_add_u64 v[138:139], s[54:55], 0, v[66:67]
	s_mov_b32 m0, s27
	s_nop 0
	global_load_lds_dwordx4 v[138:139], off
	v_lshl_add_u64 v[138:139], s[24:25], 0, v[72:73]
	s_mov_b32 m0, s7
	s_nop 0
	global_load_lds_dwordx4 v[138:139], off
	s_mov_b32 m0, s28
	s_nop 0
	global_load_lds_dwordx4 v[140:141], off
	s_waitcnt vmcnt(8)
	s_waitcnt lgkmcnt(0)
	s_barrier
	s_setprio 1
	s_waitcnt lgkmcnt(0)
	v_mfma_f32_16x16x32_bf16 v[30:33], v[86:89], v[102:105], 0
	v_mfma_f32_16x16x32_bf16 v[26:29], v[94:97], v[102:105], 0
	v_mfma_f32_16x16x32_bf16 v[22:25], v[86:89], v[110:113], 0
	v_mfma_f32_16x16x32_bf16 v[18:21], v[94:97], v[110:113], 0
	v_mfma_f32_16x16x32_bf16 v[14:17], v[86:89], v[118:121], 0
	v_mfma_f32_16x16x32_bf16 v[10:13], v[94:97], v[118:121], 0
	v_mfma_f32_16x16x32_bf16 v[6:9], v[86:89], v[126:129], 0
	v_mfma_f32_16x16x32_bf16 v[2:5], v[94:97], v[126:129], 0
	v_mfma_f32_16x16x32_bf16 v[30:33], v[90:93], v[106:109], v[30:33]
	v_mfma_f32_16x16x32_bf16 v[26:29], v[98:101], v[106:109], v[26:29]
	v_mfma_f32_16x16x32_bf16 v[22:25], v[90:93], v[114:117], v[22:25]
	v_mfma_f32_16x16x32_bf16 v[18:21], v[98:101], v[114:117], v[18:21]
	v_mfma_f32_16x16x32_bf16 v[14:17], v[90:93], v[122:125], v[14:17]
	v_mfma_f32_16x16x32_bf16 v[10:13], v[98:101], v[122:125], v[10:13]
	v_mfma_f32_16x16x32_bf16 v[6:9], v[90:93], v[130:133], v[6:9]
	v_mfma_f32_16x16x32_bf16 v[2:5], v[98:101], v[130:133], v[2:5]
	s_setprio 0
	s_setprio 1
	s_setprio 0
	s_barrier
	ds_read_b128 v[86:89], v84
	ds_read_b128 v[90:93], v84 offset:1024
	ds_read_b128 v[94:97], v84 offset:2048
	ds_read_b128 v[98:101], v84 offset:3072
	s_add_u32 s24, s24, 0x48000
	s_addc_u32 s25, s25, 0
	s_mov_b32 m0, s29
	v_lshl_add_u64 v[142:143], s[24:25], 0, v[72:73]
	ds_read_b128 v[102:105], v83 offset:32768
	ds_read_b128 v[106:109], v83 offset:33792
	ds_read_b128 v[110:113], v83 offset:34816
	ds_read_b128 v[114:117], v83 offset:35840
	ds_read_b128 v[118:121], v83 offset:36864
	ds_read_b128 v[122:125], v83 offset:37888
	ds_read_b128 v[126:129], v83 offset:38912
	ds_read_b128 v[130:133], v83 offset:39936
	global_load_lds_dwordx4 v[142:143], off
	v_lshl_add_u64 v[142:143], s[24:25], 0, v[68:69]
	s_mov_b32 m0, s30
	s_nop 0
	global_load_lds_dwordx4 v[142:143], off
	s_waitcnt vmcnt(8)
	s_waitcnt lgkmcnt(0)
	s_barrier
	s_setprio 1
	s_waitcnt lgkmcnt(0)
	v_mfma_f32_16x16x32_bf16 v[62:65], v[86:89], v[102:105], v[62:65]
	v_mfma_f32_16x16x32_bf16 v[58:61], v[94:97], v[102:105], v[58:61]
	v_mfma_f32_16x16x32_bf16 v[54:57], v[86:89], v[110:113], v[54:57]
	v_mfma_f32_16x16x32_bf16 v[50:53], v[94:97], v[110:113], v[50:53]
	v_mfma_f32_16x16x32_bf16 v[46:49], v[86:89], v[118:121], v[46:49]
	v_mfma_f32_16x16x32_bf16 v[42:45], v[94:97], v[118:121], v[42:45]
	v_mfma_f32_16x16x32_bf16 v[38:41], v[86:89], v[126:129], v[38:41]
	v_mfma_f32_16x16x32_bf16 v[34:37], v[94:97], v[126:129], v[34:37]
	v_mfma_f32_16x16x32_bf16 v[62:65], v[90:93], v[106:109], v[62:65]
	v_mfma_f32_16x16x32_bf16 v[58:61], v[98:101], v[106:109], v[58:61]
	v_mfma_f32_16x16x32_bf16 v[54:57], v[90:93], v[114:117], v[54:57]
	v_mfma_f32_16x16x32_bf16 v[50:53], v[98:101], v[114:117], v[50:53]
	v_mfma_f32_16x16x32_bf16 v[46:49], v[90:93], v[122:125], v[46:49]
	v_mfma_f32_16x16x32_bf16 v[42:45], v[98:101], v[122:125], v[42:45]
	v_mfma_f32_16x16x32_bf16 v[38:41], v[90:93], v[130:133], v[38:41]
	v_mfma_f32_16x16x32_bf16 v[34:37], v[98:101], v[130:133], v[34:37]
	s_setprio 0
	s_setprio 1
	s_setprio 0
	s_barrier
	s_mov_b32 m0, s42
	v_lshl_add_u64 v[134:135], v[134:135], 0, s[10:11]
	s_add_u32 s14, s14, 0x40080
	ds_read_b128 v[102:105], v83 offset:49152
	ds_read_b128 v[106:109], v83 offset:50176
	ds_read_b128 v[110:113], v83 offset:51200
	ds_read_b128 v[114:117], v83 offset:52224
	ds_read_b128 v[118:121], v83 offset:53248
	ds_read_b128 v[122:125], v83 offset:54272
	ds_read_b128 v[126:129], v83 offset:55296
	ds_read_b128 v[130:133], v83 offset:56320
	global_load_lds_dwordx4 v[134:135], off
	v_lshl_add_u64 v[134:135], v[136:137], 0, s[10:11]
	s_mov_b32 m0, s43
	s_addc_u32 s15, s15, 0
	global_load_lds_dwordx4 v[134:135], off
	v_lshl_add_u64 v[134:135], s[14:15], 0, v[70:71]
	s_mov_b32 m0, s36
	s_nop 0
	global_load_lds_dwordx4 v[134:135], off
	v_lshl_add_u64 v[134:135], s[14:15], 0, v[66:67]
	s_mov_b32 m0, s37
	s_nop 0
	global_load_lds_dwordx4 v[134:135], off
	v_lshl_add_u64 v[134:135], v[138:139], 0, s[10:11]
	s_mov_b32 m0, s34
	s_nop 0
	global_load_lds_dwordx4 v[134:135], off
	v_lshl_add_u64 v[134:135], v[140:141], 0, s[10:11]
	s_mov_b32 m0, s35
	s_nop 0
	global_load_lds_dwordx4 v[134:135], off
	s_waitcnt vmcnt(8)
	s_waitcnt lgkmcnt(0)
	s_barrier
	s_setprio 1
	s_waitcnt lgkmcnt(0)
	v_mfma_f32_16x16x32_bf16 v[30:33], v[86:89], v[102:105], v[30:33]
	v_mfma_f32_16x16x32_bf16 v[26:29], v[94:97], v[102:105], v[26:29]
	v_mfma_f32_16x16x32_bf16 v[22:25], v[86:89], v[110:113], v[22:25]
	v_mfma_f32_16x16x32_bf16 v[18:21], v[94:97], v[110:113], v[18:21]
	v_mfma_f32_16x16x32_bf16 v[14:17], v[86:89], v[118:121], v[14:17]
	v_mfma_f32_16x16x32_bf16 v[10:13], v[94:97], v[118:121], v[10:13]
	v_mfma_f32_16x16x32_bf16 v[6:9], v[86:89], v[126:129], v[6:9]
	v_mfma_f32_16x16x32_bf16 v[2:5], v[94:97], v[126:129], v[2:5]
	v_mfma_f32_16x16x32_bf16 v[30:33], v[90:93], v[106:109], v[30:33]
	v_mfma_f32_16x16x32_bf16 v[26:29], v[98:101], v[106:109], v[26:29]
	v_mfma_f32_16x16x32_bf16 v[22:25], v[90:93], v[114:117], v[22:25]
	v_mfma_f32_16x16x32_bf16 v[18:21], v[98:101], v[114:117], v[18:21]
	v_mfma_f32_16x16x32_bf16 v[14:17], v[90:93], v[122:125], v[14:17]
	v_mfma_f32_16x16x32_bf16 v[10:13], v[98:101], v[122:125], v[10:13]
	v_mfma_f32_16x16x32_bf16 v[6:9], v[90:93], v[130:133], v[6:9]
	v_mfma_f32_16x16x32_bf16 v[2:5], v[98:101], v[130:133], v[2:5]
	s_setprio 0
	s_setprio 1
	s_setprio 0
	s_barrier
	s_add_i32 s57, s57, 2
	s_add_u32 s22, s22, 0x100
	s_addc_u32 s23, s23, 0
	s_add_u32 s53, s53, 0x100
	s_addc_u32 s56, s56, 0

.LBB0_861:
	s_add_u32 s16, s16, 0x48080
	s_addc_u32 s17, s17, 0
	s_add_u32 s49, s18, 0x100

	s_addc_u32 s52, s19, 0
	s_mov_b32 s53, -2


	ds_read_b128 v[152:155], v146
	ds_read_b128 v[156:159], v146 offset:1024
	ds_read_b128 v[160:163], v146 offset:2048
	ds_read_b128 v[164:167], v146 offset:3072
	ds_read_b128 v[168:171], v147
	ds_read_b128 v[172:175], v147 offset:1024
	ds_read_b128 v[176:179], v147 offset:2048
	ds_read_b128 v[182:185], v147 offset:3072
	s_add_u32 s18, s16, 0xfffb8080
	s_addc_u32 s19, s17, -1
	s_cmp_eq_u32 s53, 14
	s_cselect_b32 s21, s13, s19
	s_cselect_b32 s20, s12, s18
	s_cselect_b32 s19, s15, s52
	s_cselect_b32 s18, s14, s49
	s_mov_b32 m0, s29
	v_lshl_add_u64 v[218:219], s[16:17], 0, v[140:141]
	ds_read_b128 v[186:189], v148
	ds_read_b128 v[190:193], v148 offset:1024
	ds_read_b128 v[194:197], v148 offset:2048
	ds_read_b128 v[198:201], v148 offset:3072
	ds_read_b128 v[202:205], v148 offset:4096
	ds_read_b128 v[206:209], v148 offset:5120
	ds_read_b128 v[210:213], v148 offset:6144
	ds_read_b128 v[214:217], v148 offset:7168
	global_load_lds_dwordx4 v[218:219], off
	v_lshl_add_u64 v[218:219], s[16:17], 0, v[142:143]
	s_mov_b32 m0, s30
	s_nop 0
	global_load_lds_dwordx4 v[218:219], off
	s_waitcnt vmcnt(8)
	s_waitcnt lgkmcnt(0)
	s_barrier
	s_setprio 1
	s_waitcnt lgkmcnt(0)
	v_mfma_f32_16x16x32_bf16 v[126:129], v[152:155], v[186:189], 0
	v_mfma_f32_16x16x32_bf16 v[122:125], v[160:163], v[186:189], 0
	v_mfma_f32_16x16x32_bf16 v[110:113], v[152:155], v[194:197], 0
	v_mfma_f32_16x16x32_bf16 v[106:109], v[160:163], v[194:197], 0
	v_mfma_f32_16x16x32_bf16 v[94:97], v[152:155], v[202:205], 0
	v_mfma_f32_16x16x32_bf16 v[90:93], v[160:163], v[202:205], 0
	v_mfma_f32_16x16x32_bf16 v[78:81], v[152:155], v[210:213], 0
	v_mfma_f32_16x16x32_bf16 v[74:77], v[160:163], v[210:213], 0
	v_mfma_f32_16x16x32_bf16 v[126:129], v[156:159], v[190:193], v[126:129]
	v_mfma_f32_16x16x32_bf16 v[122:125], v[164:167], v[190:193], v[122:125]
	v_mfma_f32_16x16x32_bf16 v[110:113], v[156:159], v[198:201], v[110:113]
	v_mfma_f32_16x16x32_bf16 v[106:109], v[164:167], v[198:201], v[106:109]
	v_mfma_f32_16x16x32_bf16 v[94:97], v[156:159], v[206:209], v[94:97]
	v_mfma_f32_16x16x32_bf16 v[90:93], v[164:167], v[206:209], v[90:93]
	v_mfma_f32_16x16x32_bf16 v[78:81], v[156:159], v[214:217], v[78:81]
	v_mfma_f32_16x16x32_bf16 v[74:77], v[164:167], v[214:217], v[74:77]
	s_setprio 0
	s_setprio 1
	v_mfma_f32_16x16x32_bf16 v[118:121], v[168:171], v[186:189], 0
	v_mfma_f32_16x16x32_bf16 v[114:117], v[176:179], v[186:189], 0
	v_mfma_f32_16x16x32_bf16 v[102:105], v[168:171], v[194:197], 0
	v_mfma_f32_16x16x32_bf16 v[98:101], v[176:179], v[194:197], 0
	v_mfma_f32_16x16x32_bf16 v[86:89], v[168:171], v[202:205], 0
	v_mfma_f32_16x16x32_bf16 v[82:85], v[176:179], v[202:205], 0
	v_mfma_f32_16x16x32_bf16 v[70:73], v[168:171], v[210:213], 0
	v_mfma_f32_16x16x32_bf16 v[66:69], v[176:179], v[210:213], 0
	v_mfma_f32_16x16x32_bf16 v[118:121], v[172:175], v[190:193], v[118:121]
	v_mfma_f32_16x16x32_bf16 v[114:117], v[182:185], v[190:193], v[114:117]
	v_mfma_f32_16x16x32_bf16 v[102:105], v[172:175], v[198:201], v[102:105]
	v_mfma_f32_16x16x32_bf16 v[98:101], v[182:185], v[198:201], v[98:101]
	v_mfma_f32_16x16x32_bf16 v[86:89], v[172:175], v[206:209], v[86:89]
	v_mfma_f32_16x16x32_bf16 v[82:85], v[182:185], v[206:209], v[82:85]
	v_mfma_f32_16x16x32_bf16 v[70:73], v[172:175], v[214:217], v[70:73]
	v_mfma_f32_16x16x32_bf16 v[66:69], v[182:185], v[214:217], v[66:69]
	s_setprio 0
	s_barrier
	s_mov_b32 m0, s31
	v_lshl_add_u64 v[218:219], s[18:19], 0, v[134:135]
	s_add_u32 s54, s18, 0x48000
	ds_read_b128 v[186:189], v148 offset:16384
	ds_read_b128 v[190:193], v148 offset:17408
	ds_read_b128 v[194:197], v148 offset:18432
	ds_read_b128 v[198:201], v148 offset:19456
	ds_read_b128 v[202:205], v148 offset:20480
	ds_read_b128 v[206:209], v148 offset:21504
	ds_read_b128 v[210:213], v148 offset:22528
	ds_read_b128 v[214:217], v148 offset:23552
	global_load_lds_dwordx4 v[218:219], off
	v_lshl_add_u64 v[220:221], s[18:19], 0, v[130:131]
	s_mov_b32 m0, s34
	s_addc_u32 s55, s19, 0
	global_load_lds_dwordx4 v[220:221], off
	v_lshl_add_u64 v[222:223], s[54:55], 0, v[134:135]
	s_mov_b32 m0, s35
	v_lshl_add_u64 v[224:225], s[20:21], 0, v[132:133]
	global_load_lds_dwordx4 v[222:223], off
	v_lshl_add_u64 v[222:223], s[54:55], 0, v[130:131]
	s_mov_b32 m0, s36
	s_nop 0
	global_load_lds_dwordx4 v[222:223], off
	v_lshl_add_u64 v[222:223], s[20:21], 0, v[136:137]
	s_mov_b32 m0, s22
	s_nop 0
	global_load_lds_dwordx4 v[222:223], off
	s_mov_b32 m0, s23
	s_nop 0
	global_load_lds_dwordx4 v[224:225], off
	s_waitcnt vmcnt(8)
	s_waitcnt lgkmcnt(0)
	s_barrier
	s_setprio 1
	s_waitcnt lgkmcnt(0)
	v_mfma_f32_16x16x32_bf16 v[62:65], v[152:155], v[186:189], 0
	v_mfma_f32_16x16x32_bf16 v[58:61], v[160:163], v[186:189], 0
	v_mfma_f32_16x16x32_bf16 v[46:49], v[152:155], v[194:197], 0
	v_mfma_f32_16x16x32_bf16 v[42:45], v[160:163], v[194:197], 0
	v_mfma_f32_16x16x32_bf16 v[30:33], v[152:155], v[202:205], 0
	v_mfma_f32_16x16x32_bf16 v[26:29], v[160:163], v[202:205], 0
	v_mfma_f32_16x16x32_bf16 v[14:17], v[152:155], v[210:213], 0
	v_mfma_f32_16x16x32_bf16 v[10:13], v[160:163], v[210:213], 0
	v_mfma_f32_16x16x32_bf16 v[62:65], v[156:159], v[190:193], v[62:65]
	v_mfma_f32_16x16x32_bf16 v[58:61], v[164:167], v[190:193], v[58:61]
	v_mfma_f32_16x16x32_bf16 v[46:49], v[156:159], v[198:201], v[46:49]
	v_mfma_f32_16x16x32_bf16 v[42:45], v[164:167], v[198:201], v[42:45]
	v_mfma_f32_16x16x32_bf16 v[30:33], v[156:159], v[206:209], v[30:33]
	v_mfma_f32_16x16x32_bf16 v[26:29], v[164:167], v[206:209], v[26:29]
	v_mfma_f32_16x16x32_bf16 v[14:17], v[156:159], v[214:217], v[14:17]
	v_mfma_f32_16x16x32_bf16 v[10:13], v[164:167], v[214:217], v[10:13]
	s_setprio 0
	s_setprio 1
	v_mfma_f32_16x16x32_bf16 v[54:57], v[168:171], v[186:189], 0
	v_mfma_f32_16x16x32_bf16 v[50:53], v[176:179], v[186:189], 0
	v_mfma_f32_16x16x32_bf16 v[38:41], v[168:171], v[194:197], 0
	v_mfma_f32_16x16x32_bf16 v[34:37], v[176:179], v[194:197], 0
	v_mfma_f32_16x16x32_bf16 v[22:25], v[168:171], v[202:205], 0
	v_mfma_f32_16x16x32_bf16 v[18:21], v[176:179], v[202:205], 0
	v_mfma_f32_16x16x32_bf16 v[6:9], v[168:171], v[210:213], 0
	v_mfma_f32_16x16x32_bf16 v[2:5], v[176:179], v[210:213], 0
	v_mfma_f32_16x16x32_bf16 v[54:57], v[172:175], v[190:193], v[54:57]
	v_mfma_f32_16x16x32_bf16 v[50:53], v[182:185], v[190:193], v[50:53]
	v_mfma_f32_16x16x32_bf16 v[38:41], v[172:175], v[198:201], v[38:41]
	v_mfma_f32_16x16x32_bf16 v[34:37], v[182:185], v[198:201], v[34:37]
	v_mfma_f32_16x16x32_bf16 v[22:25], v[172:175], v[206:209], v[22:25]
	v_mfma_f32_16x16x32_bf16 v[18:21], v[182:185], v[206:209], v[18:21]
	v_mfma_f32_16x16x32_bf16 v[6:9], v[172:175], v[214:217], v[6:9]
	v_mfma_f32_16x16x32_bf16 v[2:5], v[182:185], v[214:217], v[2:5]
	s_setprio 0
	s_barrier
	ds_read_b128 v[152:155], v150
	ds_read_b128 v[156:159], v150 offset:1024
	ds_read_b128 v[160:163], v150 offset:2048
	ds_read_b128 v[164:167], v150 offset:3072
	ds_read_b128 v[168:171], v151
	ds_read_b128 v[172:175], v151 offset:1024
	ds_read_b128 v[176:179], v151 offset:2048
	ds_read_b128 v[182:185], v151 offset:3072
	s_add_u32 s20, s20, 0x48000
	s_addc_u32 s21, s21, 0
	s_mov_b32 m0, s24
	v_lshl_add_u64 v[226:227], s[20:21], 0, v[136:137]
	ds_read_b128 v[186:189], v148 offset:32768
	ds_read_b128 v[190:193], v148 offset:33792
	ds_read_b128 v[194:197], v148 offset:34816
	ds_read_b128 v[198:201], v148 offset:35840
	ds_read_b128 v[202:205], v148 offset:36864
	ds_read_b128 v[206:209], v148 offset:37888
	ds_read_b128 v[210:213], v148 offset:38912
	ds_read_b128 v[214:217], v148 offset:39936
	global_load_lds_dwordx4 v[226:227], off
	v_lshl_add_u64 v[226:227], s[20:21], 0, v[132:133]
	s_mov_b32 m0, s25
	s_nop 0
	global_load_lds_dwordx4 v[226:227], off
	s_waitcnt vmcnt(8)
	s_waitcnt lgkmcnt(0)
	s_barrier
	s_setprio 1
	s_waitcnt lgkmcnt(0)
	v_mfma_f32_16x16x32_bf16 v[126:129], v[152:155], v[186:189], v[126:129]
	v_mfma_f32_16x16x32_bf16 v[122:125], v[160:163], v[186:189], v[122:125]
	v_mfma_f32_16x16x32_bf16 v[110:113], v[152:155], v[194:197], v[110:113]
	v_mfma_f32_16x16x32_bf16 v[106:109], v[160:163], v[194:197], v[106:109]
	v_mfma_f32_16x16x32_bf16 v[94:97], v[152:155], v[202:205], v[94:97]
	v_mfma_f32_16x16x32_bf16 v[90:93], v[160:163], v[202:205], v[90:93]
	v_mfma_f32_16x16x32_bf16 v[78:81], v[152:155], v[210:213], v[78:81]
	v_mfma_f32_16x16x32_bf16 v[74:77], v[160:163], v[210:213], v[74:77]
	v_mfma_f32_16x16x32_bf16 v[126:129], v[156:159], v[190:193], v[126:129]
	v_mfma_f32_16x16x32_bf16 v[122:125], v[164:167], v[190:193], v[122:125]
	v_mfma_f32_16x16x32_bf16 v[110:113], v[156:159], v[198:201], v[110:113]
	v_mfma_f32_16x16x32_bf16 v[106:109], v[164:167], v[198:201], v[106:109]
	v_mfma_f32_16x16x32_bf16 v[94:97], v[156:159], v[206:209], v[94:97]
	v_mfma_f32_16x16x32_bf16 v[90:93], v[164:167], v[206:209], v[90:93]
	v_mfma_f32_16x16x32_bf16 v[78:81], v[156:159], v[214:217], v[78:81]
	v_mfma_f32_16x16x32_bf16 v[74:77], v[164:167], v[214:217], v[74:77]
	s_setprio 0
	s_setprio 1
	v_mfma_f32_16x16x32_bf16 v[118:121], v[168:171], v[186:189], v[118:121]
	v_mfma_f32_16x16x32_bf16 v[114:117], v[176:179], v[186:189], v[114:117]
	v_mfma_f32_16x16x32_bf16 v[102:105], v[168:171], v[194:197], v[102:105]
	v_mfma_f32_16x16x32_bf16 v[98:101], v[176:179], v[194:197], v[98:101]
	v_mfma_f32_16x16x32_bf16 v[86:89], v[168:171], v[202:205], v[86:89]
	v_mfma_f32_16x16x32_bf16 v[82:85], v[176:179], v[202:205], v[82:85]
	v_mfma_f32_16x16x32_bf16 v[70:73], v[168:171], v[210:213], v[70:73]
	v_mfma_f32_16x16x32_bf16 v[66:69], v[176:179], v[210:213], v[66:69]
	v_mfma_f32_16x16x32_bf16 v[118:121], v[172:175], v[190:193], v[118:121]
	v_mfma_f32_16x16x32_bf16 v[114:117], v[182:185], v[190:193], v[114:117]
	v_mfma_f32_16x16x32_bf16 v[102:105], v[172:175], v[198:201], v[102:105]
	v_mfma_f32_16x16x32_bf16 v[98:101], v[182:185], v[198:201], v[98:101]
	v_mfma_f32_16x16x32_bf16 v[86:89], v[172:175], v[206:209], v[86:89]
	v_mfma_f32_16x16x32_bf16 v[82:85], v[182:185], v[206:209], v[82:85]
	v_mfma_f32_16x16x32_bf16 v[70:73], v[172:175], v[214:217], v[70:73]
	v_mfma_f32_16x16x32_bf16 v[66:69], v[182:185], v[214:217], v[66:69]
	s_setprio 0
	s_barrier
	s_mov_b32 m0, s37
	v_lshl_add_u64 v[218:219], v[218:219], 0, s[8:9]
	s_add_u32 s18, s18, 0x48080
	ds_read_b128 v[186:189], v148 offset:49152
	ds_read_b128 v[190:193], v148 offset:50176
	ds_read_b128 v[194:197], v148 offset:51200
	ds_read_b128 v[198:201], v148 offset:52224
	ds_read_b128 v[202:205], v148 offset:53248
	ds_read_b128 v[206:209], v148 offset:54272
	ds_read_b128 v[210:213], v148 offset:55296
	ds_read_b128 v[214:217], v148 offset:56320
	global_load_lds_dwordx4 v[218:219], off
	v_lshl_add_u64 v[218:219], v[220:221], 0, s[8:9]
	s_mov_b32 m0, s38
	s_addc_u32 s19, s19, 0
	global_load_lds_dwordx4 v[218:219], off
	v_lshl_add_u64 v[218:219], s[18:19], 0, v[134:135]
	s_mov_b32 m0, s39
	s_nop 0
	global_load_lds_dwordx4 v[218:219], off
	v_lshl_add_u64 v[218:219], s[18:19], 0, v[130:131]
	s_mov_b32 m0, s40
	s_nop 0
	global_load_lds_dwordx4 v[218:219], off
	v_lshl_add_u64 v[218:219], v[222:223], 0, s[8:9]
	s_mov_b32 m0, s27
	s_nop 0
	global_load_lds_dwordx4 v[218:219], off
	v_lshl_add_u64 v[218:219], v[224:225], 0, s[8:9]
	s_mov_b32 m0, s28
	s_nop 0
	global_load_lds_dwordx4 v[218:219], off
	s_waitcnt vmcnt(8)
	s_waitcnt lgkmcnt(0)
	s_barrier
	s_setprio 1
	s_waitcnt lgkmcnt(0)
	v_mfma_f32_16x16x32_bf16 v[62:65], v[152:155], v[186:189], v[62:65]
	v_mfma_f32_16x16x32_bf16 v[58:61], v[160:163], v[186:189], v[58:61]
	v_mfma_f32_16x16x32_bf16 v[46:49], v[152:155], v[194:197], v[46:49]
	v_mfma_f32_16x16x32_bf16 v[42:45], v[160:163], v[194:197], v[42:45]
	v_mfma_f32_16x16x32_bf16 v[30:33], v[152:155], v[202:205], v[30:33]
	v_mfma_f32_16x16x32_bf16 v[26:29], v[160:163], v[202:205], v[26:29]
	v_mfma_f32_16x16x32_bf16 v[14:17], v[152:155], v[210:213], v[14:17]
	v_mfma_f32_16x16x32_bf16 v[10:13], v[160:163], v[210:213], v[10:13]
	v_mfma_f32_16x16x32_bf16 v[62:65], v[156:159], v[190:193], v[62:65]
	v_mfma_f32_16x16x32_bf16 v[58:61], v[164:167], v[190:193], v[58:61]
	v_mfma_f32_16x16x32_bf16 v[46:49], v[156:159], v[198:201], v[46:49]
	v_mfma_f32_16x16x32_bf16 v[42:45], v[164:167], v[198:201], v[42:45]
	v_mfma_f32_16x16x32_bf16 v[30:33], v[156:159], v[206:209], v[30:33]
	v_mfma_f32_16x16x32_bf16 v[26:29], v[164:167], v[206:209], v[26:29]
	v_mfma_f32_16x16x32_bf16 v[14:17], v[156:159], v[214:217], v[14:17]
	v_mfma_f32_16x16x32_bf16 v[10:13], v[164:167], v[214:217], v[10:13]
	s_setprio 0
	s_setprio 1
	v_mfma_f32_16x16x32_bf16 v[54:57], v[168:171], v[186:189], v[54:57]
	v_mfma_f32_16x16x32_bf16 v[50:53], v[176:179], v[186:189], v[50:53]
	v_mfma_f32_16x16x32_bf16 v[38:41], v[168:171], v[194:197], v[38:41]
	v_mfma_f32_16x16x32_bf16 v[34:37], v[176:179], v[194:197], v[34:37]
	v_mfma_f32_16x16x32_bf16 v[22:25], v[168:171], v[202:205], v[22:25]
	v_mfma_f32_16x16x32_bf16 v[18:21], v[176:179], v[202:205], v[18:21]
	v_mfma_f32_16x16x32_bf16 v[6:9], v[168:171], v[210:213], v[6:9]
	v_mfma_f32_16x16x32_bf16 v[2:5], v[176:179], v[210:213], v[2:5]
	v_mfma_f32_16x16x32_bf16 v[54:57], v[172:175], v[190:193], v[54:57]
	v_mfma_f32_16x16x32_bf16 v[50:53], v[182:185], v[190:193], v[50:53]
	v_mfma_f32_16x16x32_bf16 v[38:41], v[172:175], v[198:201], v[38:41]
	v_mfma_f32_16x16x32_bf16 v[34:37], v[182:185], v[198:201], v[34:37]
	v_mfma_f32_16x16x32_bf16 v[22:25], v[172:175], v[206:209], v[22:25]
	v_mfma_f32_16x16x32_bf16 v[18:21], v[182:185], v[206:209], v[18:21]
	v_mfma_f32_16x16x32_bf16 v[6:9], v[172:175], v[214:217], v[6:9]
	v_mfma_f32_16x16x32_bf16 v[2:5], v[182:185], v[214:217], v[2:5]
	s_setprio 0
	s_barrier
	s_add_i32 s53, s53, 2
	s_add_u32 s16, s16, 0x100
	s_addc_u32 s17, s17, 0
	s_add_u32 s49, s49, 0x100
	s_addc_u32 s52, s52, 0

.LBB0_953:
	s_ashr_i32 s19, s18, 31
	s_lshl_b64 s[20:21], s[18:19], 18
	s_add_u32 s20, s0, s20
	s_addc_u32 s21, s1, s21
	s_and_b64 s[22:23], s[4:5], exec
	s_cselect_b32 s19, s21, s29
	s_cselect_b32 s25, s20, s28
	s_ashr_i32 s17, s16, 31
	s_lshl_b64 s[22:23], s[16:17], 18
	v_readlane_b32 s34, v244, 37
	v_readlane_b32 s35, v244, 38
	s_add_u32 s22, s34, s22
	s_addc_u32 s23, s35, s23
	s_and_b64 s[34:35], s[4:5], exec
	s_cselect_b32 s17, s23, s31
	s_cselect_b32 s52, s22, s30
	s_add_u32 s28, s28, 0x20080
	s_addc_u32 s29, s29, 0
	s_add_u32 s53, s30, 0x100

	s_addc_u32 s56, s31, 0
	s_mov_b32 s57, -2


	s_waitcnt lgkmcnt(0)


	ds_read_b128 v[146:149], v154
	ds_read_b128 v[158:161], v154 offset:1024
	ds_read_b128 v[162:165], v154 offset:2048
	ds_read_b128 v[166:169], v154 offset:3072
	ds_read_b128 v[170:173], v155
	ds_read_b128 v[174:177], v155 offset:1024
	ds_read_b128 v[182:185], v155 offset:2048
	ds_read_b128 v[186:189], v155 offset:3072
	s_add_u32 s30, s28, 0xfffe0080
	s_addc_u32 s31, s29, -1
	s_cmp_eq_u32 s57, 4
	s_cselect_b32 s35, s19, s31
	s_cselect_b32 s34, s25, s30
	s_cselect_b32 s31, s17, s56
	s_cselect_b32 s30, s52, s53
	v_lshl_add_u64 v[178:179], s[28:29], 0, v[138:139]
	s_add_i32 m0, s27, 0xc000
	ds_read_b128 v[190:193], v156
	ds_read_b128 v[194:197], v156 offset:1024
	ds_read_b128 v[198:201], v156 offset:2048
	ds_read_b128 v[202:205], v156 offset:3072
	ds_read_b128 v[206:209], v156 offset:4096
	ds_read_b128 v[210:213], v156 offset:5120
	ds_read_b128 v[214:217], v156 offset:6144
	ds_read_b128 v[218:221], v156 offset:7168
	global_load_lds_dwordx4 v[178:179], off
	v_lshl_add_u64 v[178:179], s[28:29], 0, v[140:141]
	s_add_i32 m0, s27, 0xe000
	s_nop 0
	global_load_lds_dwordx4 v[178:179], off
	s_waitcnt vmcnt(8)
	s_waitcnt lgkmcnt(0)
	s_barrier
	s_setprio 1
	s_waitcnt lgkmcnt(0)
	v_mfma_f32_16x16x32_bf16 v[118:121], v[146:149], v[190:193], 0
	v_mfma_f32_16x16x32_bf16 v[114:117], v[162:165], v[190:193], 0
	v_mfma_f32_16x16x32_bf16 v[102:105], v[146:149], v[198:201], 0
	v_mfma_f32_16x16x32_bf16 v[98:101], v[162:165], v[198:201], 0
	v_mfma_f32_16x16x32_bf16 v[86:89], v[146:149], v[206:209], 0
	v_mfma_f32_16x16x32_bf16 v[82:85], v[162:165], v[206:209], 0
	v_mfma_f32_16x16x32_bf16 v[70:73], v[146:149], v[214:217], 0
	v_mfma_f32_16x16x32_bf16 v[66:69], v[162:165], v[214:217], 0
	v_mfma_f32_16x16x32_bf16 v[118:121], v[158:161], v[194:197], v[118:121]
	v_mfma_f32_16x16x32_bf16 v[114:117], v[166:169], v[194:197], v[114:117]
	v_mfma_f32_16x16x32_bf16 v[102:105], v[158:161], v[202:205], v[102:105]
	v_mfma_f32_16x16x32_bf16 v[98:101], v[166:169], v[202:205], v[98:101]
	v_mfma_f32_16x16x32_bf16 v[86:89], v[158:161], v[210:213], v[86:89]
	v_mfma_f32_16x16x32_bf16 v[82:85], v[166:169], v[210:213], v[82:85]
	v_mfma_f32_16x16x32_bf16 v[70:73], v[158:161], v[218:221], v[70:73]
	v_mfma_f32_16x16x32_bf16 v[66:69], v[166:169], v[218:221], v[66:69]
	s_setprio 0
	s_setprio 1
	v_mfma_f32_16x16x32_bf16 v[126:129], v[170:173], v[190:193], 0
	v_mfma_f32_16x16x32_bf16 v[122:125], v[182:185], v[190:193], 0
	v_mfma_f32_16x16x32_bf16 v[110:113], v[170:173], v[198:201], 0
	v_mfma_f32_16x16x32_bf16 v[106:109], v[182:185], v[198:201], 0
	v_mfma_f32_16x16x32_bf16 v[94:97], v[170:173], v[206:209], 0
	v_mfma_f32_16x16x32_bf16 v[90:93], v[182:185], v[206:209], 0
	v_mfma_f32_16x16x32_bf16 v[78:81], v[170:173], v[214:217], 0
	v_mfma_f32_16x16x32_bf16 v[74:77], v[182:185], v[214:217], 0
	v_mfma_f32_16x16x32_bf16 v[126:129], v[174:177], v[194:197], v[126:129]
	v_mfma_f32_16x16x32_bf16 v[122:125], v[186:189], v[194:197], v[122:125]
	v_mfma_f32_16x16x32_bf16 v[110:113], v[174:177], v[202:205], v[110:113]
	v_mfma_f32_16x16x32_bf16 v[106:109], v[186:189], v[202:205], v[106:109]
	v_mfma_f32_16x16x32_bf16 v[94:97], v[174:177], v[210:213], v[94:97]
	v_mfma_f32_16x16x32_bf16 v[90:93], v[186:189], v[210:213], v[90:93]
	v_mfma_f32_16x16x32_bf16 v[78:81], v[174:177], v[218:221], v[78:81]
	v_mfma_f32_16x16x32_bf16 v[74:77], v[186:189], v[218:221], v[74:77]
	s_setprio 0
	s_barrier
	s_add_i32 s33, s48, s36
	v_lshl_add_u64 v[178:179], s[30:31], 0, v[132:133]
	s_mov_b32 m0, s33
	ds_read_b128 v[190:193], v156 offset:16384
	ds_read_b128 v[194:197], v156 offset:17408
	ds_read_b128 v[198:201], v156 offset:18432
	ds_read_b128 v[202:205], v156 offset:19456
	ds_read_b128 v[206:209], v156 offset:20480
	ds_read_b128 v[210:213], v156 offset:21504
	ds_read_b128 v[214:217], v156 offset:22528
	ds_read_b128 v[218:221], v156 offset:23552
	global_load_lds_dwordx4 v[178:179], off
	s_add_i32 m0, s33, 0x2000
	s_add_u32 s54, s30, 0x20000
	v_lshl_add_u64 v[222:223], s[30:31], 0, v[136:137]
	s_addc_u32 s55, s31, 0
	s_add_i32 s33, s49, s36
	global_load_lds_dwordx4 v[222:223], off
	v_lshl_add_u64 v[224:225], s[54:55], 0, v[132:133]
	s_mov_b32 m0, s33
	v_lshl_add_u64 v[226:227], s[34:35], 0, v[134:135]
	global_load_lds_dwordx4 v[224:225], off
	v_lshl_add_u64 v[224:225], s[54:55], 0, v[136:137]
	s_add_i32 m0, s33, 0x2000
	s_nop 0
	global_load_lds_dwordx4 v[224:225], off
	v_lshl_add_u64 v[224:225], s[34:35], 0, v[130:131]
	s_mov_b32 m0, s27
	s_nop 0
	global_load_lds_dwordx4 v[224:225], off
	s_mov_b32 m0, s37
	s_nop 0
	global_load_lds_dwordx4 v[226:227], off
	s_waitcnt vmcnt(8)
	s_waitcnt lgkmcnt(0)
	s_barrier
	s_setprio 1
	s_waitcnt lgkmcnt(0)
	v_mfma_f32_16x16x32_bf16 v[54:57], v[146:149], v[190:193], 0
	v_mfma_f32_16x16x32_bf16 v[50:53], v[162:165], v[190:193], 0
	v_mfma_f32_16x16x32_bf16 v[38:41], v[146:149], v[198:201], 0
	v_mfma_f32_16x16x32_bf16 v[34:37], v[162:165], v[198:201], 0
	v_mfma_f32_16x16x32_bf16 v[22:25], v[146:149], v[206:209], 0
	v_mfma_f32_16x16x32_bf16 v[18:21], v[162:165], v[206:209], 0
	v_mfma_f32_16x16x32_bf16 v[10:13], v[146:149], v[214:217], 0
	v_mfma_f32_16x16x32_bf16 v[2:5], v[162:165], v[214:217], 0
	v_mfma_f32_16x16x32_bf16 v[54:57], v[158:161], v[194:197], v[54:57]
	v_mfma_f32_16x16x32_bf16 v[50:53], v[166:169], v[194:197], v[50:53]
	v_mfma_f32_16x16x32_bf16 v[38:41], v[158:161], v[202:205], v[38:41]
	v_mfma_f32_16x16x32_bf16 v[34:37], v[166:169], v[202:205], v[34:37]
	v_mfma_f32_16x16x32_bf16 v[22:25], v[158:161], v[210:213], v[22:25]
	v_mfma_f32_16x16x32_bf16 v[18:21], v[166:169], v[210:213], v[18:21]
	v_mfma_f32_16x16x32_bf16 v[10:13], v[158:161], v[218:221], v[10:13]
	v_mfma_f32_16x16x32_bf16 v[2:5], v[166:169], v[218:221], v[2:5]
	s_setprio 0
	s_setprio 1
	v_mfma_f32_16x16x32_bf16 v[62:65], v[170:173], v[190:193], 0
	v_mfma_f32_16x16x32_bf16 v[58:61], v[182:185], v[190:193], 0
	v_mfma_f32_16x16x32_bf16 v[46:49], v[170:173], v[198:201], 0
	v_mfma_f32_16x16x32_bf16 v[42:45], v[182:185], v[198:201], 0
	v_mfma_f32_16x16x32_bf16 v[30:33], v[170:173], v[206:209], 0
	v_mfma_f32_16x16x32_bf16 v[26:29], v[182:185], v[206:209], 0
	v_mfma_f32_16x16x32_bf16 v[14:17], v[170:173], v[214:217], 0
	v_mfma_f32_16x16x32_bf16 v[6:9], v[182:185], v[214:217], 0
	v_mfma_f32_16x16x32_bf16 v[62:65], v[174:177], v[194:197], v[62:65]
	v_mfma_f32_16x16x32_bf16 v[58:61], v[186:189], v[194:197], v[58:61]
	v_mfma_f32_16x16x32_bf16 v[46:49], v[174:177], v[202:205], v[46:49]
	v_mfma_f32_16x16x32_bf16 v[42:45], v[186:189], v[202:205], v[42:45]
	v_mfma_f32_16x16x32_bf16 v[30:33], v[174:177], v[210:213], v[30:33]
	v_mfma_f32_16x16x32_bf16 v[26:29], v[186:189], v[210:213], v[26:29]
	v_mfma_f32_16x16x32_bf16 v[14:17], v[174:177], v[218:221], v[14:17]
	v_mfma_f32_16x16x32_bf16 v[6:9], v[186:189], v[218:221], v[6:9]
	s_setprio 0
	s_barrier
	s_add_i32 s33, 0, 0x18000
	s_add_i32 s51, 0, 0x1c000
	v_add_u32_e32 v166, s33, v152
	v_add_u32_e32 v186, s51, v152
	ds_read_b128 v[146:149], v166
	ds_read_b128 v[158:161], v166 offset:1024
	ds_read_b128 v[162:165], v166 offset:2048
	ds_read_b128 v[166:169], v166 offset:3072
	ds_read_b128 v[170:173], v186
	ds_read_b128 v[174:177], v186 offset:1024
	ds_read_b128 v[182:185], v186 offset:2048
	ds_read_b128 v[186:189], v186 offset:3072
	s_add_u32 s34, s34, 0x20000
	s_addc_u32 s35, s35, 0
	s_mov_b32 m0, s38
	v_lshl_add_u64 v[228:229], s[34:35], 0, v[130:131]
	ds_read_b128 v[190:193], v156 offset:32768
	ds_read_b128 v[194:197], v156 offset:33792
	ds_read_b128 v[198:201], v156 offset:34816
	ds_read_b128 v[202:205], v156 offset:35840
	ds_read_b128 v[206:209], v156 offset:36864
	ds_read_b128 v[210:213], v156 offset:37888
	ds_read_b128 v[214:217], v156 offset:38912
	ds_read_b128 v[218:221], v156 offset:39936
	global_load_lds_dwordx4 v[228:229], off
	v_lshl_add_u64 v[228:229], s[34:35], 0, v[134:135]
	s_mov_b32 m0, s39
	s_nop 0
	global_load_lds_dwordx4 v[228:229], off
	s_waitcnt vmcnt(8)
	s_waitcnt lgkmcnt(0)
	s_barrier
	s_setprio 1
	s_waitcnt lgkmcnt(0)
	v_mfma_f32_16x16x32_bf16 v[118:121], v[146:149], v[190:193], v[118:121]
	v_mfma_f32_16x16x32_bf16 v[114:117], v[162:165], v[190:193], v[114:117]
	v_mfma_f32_16x16x32_bf16 v[102:105], v[146:149], v[198:201], v[102:105]
	v_mfma_f32_16x16x32_bf16 v[98:101], v[162:165], v[198:201], v[98:101]
	v_mfma_f32_16x16x32_bf16 v[86:89], v[146:149], v[206:209], v[86:89]
	v_mfma_f32_16x16x32_bf16 v[82:85], v[162:165], v[206:209], v[82:85]
	v_mfma_f32_16x16x32_bf16 v[70:73], v[146:149], v[214:217], v[70:73]
	v_mfma_f32_16x16x32_bf16 v[66:69], v[162:165], v[214:217], v[66:69]
	v_mfma_f32_16x16x32_bf16 v[118:121], v[158:161], v[194:197], v[118:121]
	v_mfma_f32_16x16x32_bf16 v[114:117], v[166:169], v[194:197], v[114:117]
	v_mfma_f32_16x16x32_bf16 v[102:105], v[158:161], v[202:205], v[102:105]
	v_mfma_f32_16x16x32_bf16 v[98:101], v[166:169], v[202:205], v[98:101]
	v_mfma_f32_16x16x32_bf16 v[86:89], v[158:161], v[210:213], v[86:89]
	v_mfma_f32_16x16x32_bf16 v[82:85], v[166:169], v[210:213], v[82:85]
	v_mfma_f32_16x16x32_bf16 v[70:73], v[158:161], v[218:221], v[70:73]
	v_mfma_f32_16x16x32_bf16 v[66:69], v[166:169], v[218:221], v[66:69]
	s_setprio 0
	s_setprio 1
	v_mfma_f32_16x16x32_bf16 v[126:129], v[170:173], v[190:193], v[126:129]
	v_mfma_f32_16x16x32_bf16 v[122:125], v[182:185], v[190:193], v[122:125]
	v_mfma_f32_16x16x32_bf16 v[110:113], v[170:173], v[198:201], v[110:113]
	v_mfma_f32_16x16x32_bf16 v[106:109], v[182:185], v[198:201], v[106:109]
	v_mfma_f32_16x16x32_bf16 v[94:97], v[170:173], v[206:209], v[94:97]
	v_mfma_f32_16x16x32_bf16 v[90:93], v[182:185], v[206:209], v[90:93]
	v_mfma_f32_16x16x32_bf16 v[78:81], v[170:173], v[214:217], v[78:81]
	v_mfma_f32_16x16x32_bf16 v[74:77], v[182:185], v[214:217], v[74:77]
	v_mfma_f32_16x16x32_bf16 v[126:129], v[174:177], v[194:197], v[126:129]
	v_mfma_f32_16x16x32_bf16 v[122:125], v[186:189], v[194:197], v[122:125]
	v_mfma_f32_16x16x32_bf16 v[110:113], v[174:177], v[202:205], v[110:113]
	v_mfma_f32_16x16x32_bf16 v[106:109], v[186:189], v[202:205], v[106:109]
	v_mfma_f32_16x16x32_bf16 v[94:97], v[174:177], v[210:213], v[94:97]
	v_mfma_f32_16x16x32_bf16 v[90:93], v[186:189], v[210:213], v[90:93]
	v_mfma_f32_16x16x32_bf16 v[78:81], v[174:177], v[218:221], v[78:81]
	v_mfma_f32_16x16x32_bf16 v[74:77], v[186:189], v[218:221], v[74:77]
	s_setprio 0
	s_barrier
	s_add_i32 s33, s33, s36
	v_lshl_add_u64 v[178:179], v[178:179], 0, s[12:13]
	s_mov_b32 m0, s33
	ds_read_b128 v[190:193], v156 offset:49152
	ds_read_b128 v[194:197], v156 offset:50176
	ds_read_b128 v[198:201], v156 offset:51200
	ds_read_b128 v[202:205], v156 offset:52224
	ds_read_b128 v[206:209], v156 offset:53248
	ds_read_b128 v[210:213], v156 offset:54272
	ds_read_b128 v[214:217], v156 offset:55296
	ds_read_b128 v[218:221], v156 offset:56320
	global_load_lds_dwordx4 v[178:179], off
	s_add_i32 m0, s33, 0x2000
	s_add_u32 s30, s30, 0x20080
	v_lshl_add_u64 v[178:179], v[222:223], 0, s[12:13]
	s_addc_u32 s31, s31, 0
	s_add_i32 s33, s51, s36
	global_load_lds_dwordx4 v[178:179], off
	v_lshl_add_u64 v[178:179], s[30:31], 0, v[132:133]
	s_mov_b32 m0, s33
	s_nop 0
	global_load_lds_dwordx4 v[178:179], off
	v_lshl_add_u64 v[178:179], s[30:31], 0, v[136:137]
	s_add_i32 m0, s33, 0x2000
	s_nop 0
	global_load_lds_dwordx4 v[178:179], off
	v_lshl_add_u64 v[178:179], v[224:225], 0, s[12:13]
	s_mov_b32 m0, s41
	s_nop 0
	global_load_lds_dwordx4 v[178:179], off
	v_lshl_add_u64 v[178:179], v[226:227], 0, s[12:13]
	s_mov_b32 m0, s42
	s_nop 0
	global_load_lds_dwordx4 v[178:179], off
	s_waitcnt vmcnt(8)
	s_waitcnt lgkmcnt(0)
	s_barrier
	s_setprio 1
	s_waitcnt lgkmcnt(0)
	v_mfma_f32_16x16x32_bf16 v[54:57], v[146:149], v[190:193], v[54:57]
	v_mfma_f32_16x16x32_bf16 v[50:53], v[162:165], v[190:193], v[50:53]
	v_mfma_f32_16x16x32_bf16 v[38:41], v[146:149], v[198:201], v[38:41]
	v_mfma_f32_16x16x32_bf16 v[34:37], v[162:165], v[198:201], v[34:37]
	v_mfma_f32_16x16x32_bf16 v[22:25], v[146:149], v[206:209], v[22:25]
	v_mfma_f32_16x16x32_bf16 v[18:21], v[162:165], v[206:209], v[18:21]
	v_mfma_f32_16x16x32_bf16 v[10:13], v[146:149], v[214:217], v[10:13]
	v_mfma_f32_16x16x32_bf16 v[2:5], v[162:165], v[214:217], v[2:5]
	v_mfma_f32_16x16x32_bf16 v[54:57], v[158:161], v[194:197], v[54:57]
	v_mfma_f32_16x16x32_bf16 v[50:53], v[166:169], v[194:197], v[50:53]
	v_mfma_f32_16x16x32_bf16 v[38:41], v[158:161], v[202:205], v[38:41]
	v_mfma_f32_16x16x32_bf16 v[34:37], v[166:169], v[202:205], v[34:37]
	v_mfma_f32_16x16x32_bf16 v[22:25], v[158:161], v[210:213], v[22:25]
	v_mfma_f32_16x16x32_bf16 v[18:21], v[166:169], v[210:213], v[18:21]
	v_mfma_f32_16x16x32_bf16 v[10:13], v[158:161], v[218:221], v[10:13]
	v_mfma_f32_16x16x32_bf16 v[2:5], v[166:169], v[218:221], v[2:5]
	s_setprio 0
	s_setprio 1
	v_mfma_f32_16x16x32_bf16 v[62:65], v[170:173], v[190:193], v[62:65]
	v_mfma_f32_16x16x32_bf16 v[58:61], v[182:185], v[190:193], v[58:61]
	v_mfma_f32_16x16x32_bf16 v[46:49], v[170:173], v[198:201], v[46:49]
	v_mfma_f32_16x16x32_bf16 v[42:45], v[182:185], v[198:201], v[42:45]
	v_mfma_f32_16x16x32_bf16 v[30:33], v[170:173], v[206:209], v[30:33]
	v_mfma_f32_16x16x32_bf16 v[26:29], v[182:185], v[206:209], v[26:29]
	v_mfma_f32_16x16x32_bf16 v[14:17], v[170:173], v[214:217], v[14:17]
	v_mfma_f32_16x16x32_bf16 v[6:9], v[182:185], v[214:217], v[6:9]
	v_mfma_f32_16x16x32_bf16 v[62:65], v[174:177], v[194:197], v[62:65]
	v_mfma_f32_16x16x32_bf16 v[58:61], v[186:189], v[194:197], v[58:61]
	v_mfma_f32_16x16x32_bf16 v[46:49], v[174:177], v[202:205], v[46:49]
	v_mfma_f32_16x16x32_bf16 v[42:45], v[186:189], v[202:205], v[42:45]
	v_mfma_f32_16x16x32_bf16 v[30:33], v[174:177], v[210:213], v[30:33]
	v_mfma_f32_16x16x32_bf16 v[26:29], v[186:189], v[210:213], v[26:29]
	v_mfma_f32_16x16x32_bf16 v[14:17], v[174:177], v[218:221], v[14:17]
	v_mfma_f32_16x16x32_bf16 v[6:9], v[186:189], v[218:221], v[6:9]
	s_setprio 0
	s_barrier
	s_add_i32 s57, s57, 2
	s_add_u32 s28, s28, 0x100
	s_addc_u32 s29, s29, 0
	s_add_u32 s53, s53, 0x100
	s_addc_u32 s56, s56, 0

.LBB0_1068:
	s_ashr_i32 s17, s16, 31
	s_lshl_b64 s[18:19], s[16:17], 19
	s_add_u32 s18, s92, s18
	s_addc_u32 s19, s93, s19
	s_and_b64 s[20:21], s[2:3], exec
	s_cselect_b32 s17, s19, s27
	s_cselect_b32 s57, s18, s26
	s_ashr_i32 s15, s14, 31
	s_lshl_b64 s[20:21], s[14:15], 19
	s_add_u32 s20, s6, s20
	s_addc_u32 s21, s7, s21
	s_and_b64 s[30:31], s[2:3], exec
	s_cselect_b32 s15, s21, s29
	s_cselect_b32 s58, s20, s28
	s_add_u32 s26, s26, 0x40080
	s_addc_u32 s27, s27, 0
	s_add_u32 s59, s28, 0x100

	s_addc_u32 s60, s29, 0
	s_mov_b32 s61, -2


	ds_read_b128 v[160:163], v156
	ds_read_b128 v[164:167], v156 offset:1024
	ds_read_b128 v[168:171], v156 offset:2048
	ds_read_b128 v[172:175], v156 offset:3072
	ds_read_b128 v[176:179], v157
	ds_read_b128 v[182:185], v157 offset:1024
	ds_read_b128 v[186:189], v157 offset:2048
	ds_read_b128 v[190:193], v157 offset:3072
	s_add_u32 s28, s26, 0xfffc0080
	s_addc_u32 s29, s27, -1
	s_cmp_eq_u32 s61, 12
	s_cselect_b32 s31, s17, s29
	s_cselect_b32 s30, s57, s28
	s_cselect_b32 s29, s15, s60
	s_cselect_b32 s28, s58, s59
	v_lshl_add_u64 v[226:227], s[26:27], 0, v[144:145]
	s_add_i32 m0, s25, 0xc000
	ds_read_b128 v[194:197], v158
	ds_read_b128 v[198:201], v158 offset:1024
	ds_read_b128 v[202:205], v158 offset:2048
	ds_read_b128 v[206:209], v158 offset:3072
	ds_read_b128 v[210:213], v158 offset:4096
	ds_read_b128 v[214:217], v158 offset:5120
	ds_read_b128 v[218:221], v158 offset:6144
	ds_read_b128 v[222:225], v158 offset:7168
	global_load_lds_dwordx4 v[226:227], off
	v_lshl_add_u64 v[226:227], s[26:27], 0, v[146:147]
	s_add_i32 m0, s25, 0xe000
	s_nop 0
	global_load_lds_dwordx4 v[226:227], off
	s_waitcnt vmcnt(8)
	s_waitcnt lgkmcnt(0)
	s_barrier
	s_setprio 1
	s_waitcnt lgkmcnt(0)
	v_mfma_f32_16x16x32_bf16 v[126:129], v[160:163], v[194:197], 0
	v_mfma_f32_16x16x32_bf16 v[118:121], v[168:171], v[194:197], 0
	v_mfma_f32_16x16x32_bf16 v[110:113], v[160:163], v[202:205], 0
	v_mfma_f32_16x16x32_bf16 v[102:105], v[168:171], v[202:205], 0
	v_mfma_f32_16x16x32_bf16 v[94:97], v[160:163], v[210:213], 0
	v_mfma_f32_16x16x32_bf16 v[86:89], v[168:171], v[210:213], 0
	v_mfma_f32_16x16x32_bf16 v[78:81], v[160:163], v[218:221], 0
	v_mfma_f32_16x16x32_bf16 v[70:73], v[168:171], v[218:221], 0
	v_mfma_f32_16x16x32_bf16 v[126:129], v[164:167], v[198:201], v[126:129]
	v_mfma_f32_16x16x32_bf16 v[118:121], v[172:175], v[198:201], v[118:121]
	v_mfma_f32_16x16x32_bf16 v[110:113], v[164:167], v[206:209], v[110:113]
	v_mfma_f32_16x16x32_bf16 v[102:105], v[172:175], v[206:209], v[102:105]
	v_mfma_f32_16x16x32_bf16 v[94:97], v[164:167], v[214:217], v[94:97]
	v_mfma_f32_16x16x32_bf16 v[86:89], v[172:175], v[214:217], v[86:89]
	v_mfma_f32_16x16x32_bf16 v[78:81], v[164:167], v[222:225], v[78:81]
	v_mfma_f32_16x16x32_bf16 v[70:73], v[172:175], v[222:225], v[70:73]
	s_setprio 0
	s_setprio 1
	v_mfma_f32_16x16x32_bf16 v[122:125], v[176:179], v[194:197], 0
	v_mfma_f32_16x16x32_bf16 v[114:117], v[186:189], v[194:197], 0
	v_mfma_f32_16x16x32_bf16 v[106:109], v[176:179], v[202:205], 0
	v_mfma_f32_16x16x32_bf16 v[98:101], v[186:189], v[202:205], 0
	v_mfma_f32_16x16x32_bf16 v[90:93], v[176:179], v[210:213], 0
	v_mfma_f32_16x16x32_bf16 v[82:85], v[186:189], v[210:213], 0
	v_mfma_f32_16x16x32_bf16 v[74:77], v[176:179], v[218:221], 0
	v_mfma_f32_16x16x32_bf16 v[66:69], v[186:189], v[218:221], 0
	v_mfma_f32_16x16x32_bf16 v[122:125], v[182:185], v[198:201], v[122:125]
	v_mfma_f32_16x16x32_bf16 v[114:117], v[190:193], v[198:201], v[114:117]
	v_mfma_f32_16x16x32_bf16 v[106:109], v[182:185], v[206:209], v[106:109]
	v_mfma_f32_16x16x32_bf16 v[98:101], v[190:193], v[206:209], v[98:101]
	v_mfma_f32_16x16x32_bf16 v[90:93], v[182:185], v[214:217], v[90:93]
	v_mfma_f32_16x16x32_bf16 v[82:85], v[190:193], v[214:217], v[82:85]
	v_mfma_f32_16x16x32_bf16 v[74:77], v[182:185], v[222:225], v[74:77]
	v_mfma_f32_16x16x32_bf16 v[66:69], v[190:193], v[222:225], v[66:69]
	s_setprio 0
	s_barrier
	s_add_i32 s33, s48, s23
	v_lshl_add_u64 v[226:227], s[28:29], 0, v[132:133]
	s_mov_b32 m0, s33
	ds_read_b128 v[194:197], v158 offset:16384
	ds_read_b128 v[198:201], v158 offset:17408
	ds_read_b128 v[202:205], v158 offset:18432
	ds_read_b128 v[206:209], v158 offset:19456
	ds_read_b128 v[210:213], v158 offset:20480
	ds_read_b128 v[214:217], v158 offset:21504
	ds_read_b128 v[218:221], v158 offset:22528
	ds_read_b128 v[222:225], v158 offset:23552
	global_load_lds_dwordx4 v[226:227], off
	s_add_i32 m0, s33, 0x2000
	s_add_u32 s54, s28, 0x40000
	v_lshl_add_u64 v[228:229], s[28:29], 0, v[136:137]
	s_addc_u32 s55, s29, 0
	s_add_i32 s33, s49, s23
	global_load_lds_dwordx4 v[228:229], off
	v_lshl_add_u64 v[230:231], s[54:55], 0, v[132:133]
	s_mov_b32 m0, s33
	v_lshl_add_u64 v[232:233], s[30:31], 0, v[134:135]
	global_load_lds_dwordx4 v[230:231], off
	v_lshl_add_u64 v[230:231], s[54:55], 0, v[136:137]
	s_add_i32 m0, s33, 0x2000
	s_nop 0
	global_load_lds_dwordx4 v[230:231], off
	v_lshl_add_u64 v[230:231], s[30:31], 0, v[130:131]
	s_mov_b32 m0, s25
	s_nop 0
	global_load_lds_dwordx4 v[230:231], off
	s_mov_b32 m0, s35
	s_nop 0
	global_load_lds_dwordx4 v[232:233], off
	s_waitcnt vmcnt(8)
	s_waitcnt lgkmcnt(0)
	s_barrier
	s_setprio 1
	s_waitcnt lgkmcnt(0)
	v_mfma_f32_16x16x32_bf16 v[62:65], v[160:163], v[194:197], 0
	v_mfma_f32_16x16x32_bf16 v[54:57], v[168:171], v[194:197], 0
	v_mfma_f32_16x16x32_bf16 v[46:49], v[160:163], v[202:205], 0
	v_mfma_f32_16x16x32_bf16 v[38:41], v[168:171], v[202:205], 0
	v_mfma_f32_16x16x32_bf16 v[30:33], v[160:163], v[210:213], 0
	v_mfma_f32_16x16x32_bf16 v[22:25], v[168:171], v[210:213], 0
	v_mfma_f32_16x16x32_bf16 v[14:17], v[160:163], v[218:221], 0
	v_mfma_f32_16x16x32_bf16 v[6:9], v[168:171], v[218:221], 0
	v_mfma_f32_16x16x32_bf16 v[62:65], v[164:167], v[198:201], v[62:65]
	v_mfma_f32_16x16x32_bf16 v[54:57], v[172:175], v[198:201], v[54:57]
	v_mfma_f32_16x16x32_bf16 v[46:49], v[164:167], v[206:209], v[46:49]
	v_mfma_f32_16x16x32_bf16 v[38:41], v[172:175], v[206:209], v[38:41]
	v_mfma_f32_16x16x32_bf16 v[30:33], v[164:167], v[214:217], v[30:33]
	v_mfma_f32_16x16x32_bf16 v[22:25], v[172:175], v[214:217], v[22:25]
	v_mfma_f32_16x16x32_bf16 v[14:17], v[164:167], v[222:225], v[14:17]
	v_mfma_f32_16x16x32_bf16 v[6:9], v[172:175], v[222:225], v[6:9]
	s_setprio 0
	s_setprio 1
	v_mfma_f32_16x16x32_bf16 v[58:61], v[176:179], v[194:197], 0
	v_mfma_f32_16x16x32_bf16 v[50:53], v[186:189], v[194:197], 0
	v_mfma_f32_16x16x32_bf16 v[42:45], v[176:179], v[202:205], 0
	v_mfma_f32_16x16x32_bf16 v[34:37], v[186:189], v[202:205], 0
	v_mfma_f32_16x16x32_bf16 v[26:29], v[176:179], v[210:213], 0
	v_mfma_f32_16x16x32_bf16 v[18:21], v[186:189], v[210:213], 0
	v_mfma_f32_16x16x32_bf16 v[10:13], v[176:179], v[218:221], 0
	v_mfma_f32_16x16x32_bf16 v[2:5], v[186:189], v[218:221], 0
	v_mfma_f32_16x16x32_bf16 v[58:61], v[182:185], v[198:201], v[58:61]
	v_mfma_f32_16x16x32_bf16 v[50:53], v[190:193], v[198:201], v[50:53]
	v_mfma_f32_16x16x32_bf16 v[42:45], v[182:185], v[206:209], v[42:45]
	v_mfma_f32_16x16x32_bf16 v[34:37], v[190:193], v[206:209], v[34:37]
	v_mfma_f32_16x16x32_bf16 v[26:29], v[182:185], v[214:217], v[26:29]
	v_mfma_f32_16x16x32_bf16 v[18:21], v[190:193], v[214:217], v[18:21]
	v_mfma_f32_16x16x32_bf16 v[10:13], v[182:185], v[222:225], v[10:13]
	v_mfma_f32_16x16x32_bf16 v[2:5], v[190:193], v[222:225], v[2:5]
	s_setprio 0
	s_barrier
	s_add_i32 s33, 0, 0x18000
	s_add_i32 s51, 0, 0x1c000
	v_add_u32_e32 v172, s33, v154
	v_add_u32_e32 v190, s51, v154
	ds_read_b128 v[160:163], v172
	ds_read_b128 v[164:167], v172 offset:1024
	ds_read_b128 v[168:171], v172 offset:2048
	ds_read_b128 v[172:175], v172 offset:3072
	ds_read_b128 v[176:179], v190
	ds_read_b128 v[182:185], v190 offset:1024
	ds_read_b128 v[186:189], v190 offset:2048
	ds_read_b128 v[190:193], v190 offset:3072
	s_add_u32 s30, s30, 0x40000
	s_addc_u32 s31, s31, 0
	s_mov_b32 m0, s36
	v_lshl_add_u64 v[234:235], s[30:31], 0, v[130:131]
	ds_read_b128 v[194:197], v158 offset:32768
	ds_read_b128 v[198:201], v158 offset:33792
	ds_read_b128 v[202:205], v158 offset:34816
	ds_read_b128 v[206:209], v158 offset:35840
	ds_read_b128 v[210:213], v158 offset:36864
	ds_read_b128 v[214:217], v158 offset:37888
	ds_read_b128 v[218:221], v158 offset:38912
	ds_read_b128 v[222:225], v158 offset:39936
	global_load_lds_dwordx4 v[234:235], off
	v_lshl_add_u64 v[234:235], s[30:31], 0, v[134:135]
	s_mov_b32 m0, s37
	s_nop 0
	global_load_lds_dwordx4 v[234:235], off
	s_waitcnt vmcnt(8)
	s_waitcnt lgkmcnt(0)
	s_barrier
	s_setprio 1
	s_waitcnt lgkmcnt(0)
	v_mfma_f32_16x16x32_bf16 v[126:129], v[160:163], v[194:197], v[126:129]
	v_mfma_f32_16x16x32_bf16 v[118:121], v[168:171], v[194:197], v[118:121]
	v_mfma_f32_16x16x32_bf16 v[110:113], v[160:163], v[202:205], v[110:113]
	v_mfma_f32_16x16x32_bf16 v[102:105], v[168:171], v[202:205], v[102:105]
	v_mfma_f32_16x16x32_bf16 v[94:97], v[160:163], v[210:213], v[94:97]
	v_mfma_f32_16x16x32_bf16 v[86:89], v[168:171], v[210:213], v[86:89]
	v_mfma_f32_16x16x32_bf16 v[78:81], v[160:163], v[218:221], v[78:81]
	v_mfma_f32_16x16x32_bf16 v[70:73], v[168:171], v[218:221], v[70:73]
	v_mfma_f32_16x16x32_bf16 v[126:129], v[164:167], v[198:201], v[126:129]
	v_mfma_f32_16x16x32_bf16 v[118:121], v[172:175], v[198:201], v[118:121]
	v_mfma_f32_16x16x32_bf16 v[110:113], v[164:167], v[206:209], v[110:113]
	v_mfma_f32_16x16x32_bf16 v[102:105], v[172:175], v[206:209], v[102:105]
	v_mfma_f32_16x16x32_bf16 v[94:97], v[164:167], v[214:217], v[94:97]
	v_mfma_f32_16x16x32_bf16 v[86:89], v[172:175], v[214:217], v[86:89]
	v_mfma_f32_16x16x32_bf16 v[78:81], v[164:167], v[222:225], v[78:81]
	v_mfma_f32_16x16x32_bf16 v[70:73], v[172:175], v[222:225], v[70:73]
	s_setprio 0
	s_setprio 1
	v_mfma_f32_16x16x32_bf16 v[122:125], v[176:179], v[194:197], v[122:125]
	v_mfma_f32_16x16x32_bf16 v[114:117], v[186:189], v[194:197], v[114:117]
	v_mfma_f32_16x16x32_bf16 v[106:109], v[176:179], v[202:205], v[106:109]
	v_mfma_f32_16x16x32_bf16 v[98:101], v[186:189], v[202:205], v[98:101]
	v_mfma_f32_16x16x32_bf16 v[90:93], v[176:179], v[210:213], v[90:93]
	v_mfma_f32_16x16x32_bf16 v[82:85], v[186:189], v[210:213], v[82:85]
	v_mfma_f32_16x16x32_bf16 v[74:77], v[176:179], v[218:221], v[74:77]
	v_mfma_f32_16x16x32_bf16 v[66:69], v[186:189], v[218:221], v[66:69]
	v_mfma_f32_16x16x32_bf16 v[122:125], v[182:185], v[198:201], v[122:125]
	v_mfma_f32_16x16x32_bf16 v[114:117], v[190:193], v[198:201], v[114:117]
	v_mfma_f32_16x16x32_bf16 v[106:109], v[182:185], v[206:209], v[106:109]
	v_mfma_f32_16x16x32_bf16 v[98:101], v[190:193], v[206:209], v[98:101]
	v_mfma_f32_16x16x32_bf16 v[90:93], v[182:185], v[214:217], v[90:93]
	v_mfma_f32_16x16x32_bf16 v[82:85], v[190:193], v[214:217], v[82:85]
	v_mfma_f32_16x16x32_bf16 v[74:77], v[182:185], v[222:225], v[74:77]
	v_mfma_f32_16x16x32_bf16 v[66:69], v[190:193], v[222:225], v[66:69]
	s_setprio 0
	s_barrier
	s_add_i32 s30, s33, s23
	v_lshl_add_u64 v[226:227], v[226:227], 0, s[12:13]
	s_mov_b32 m0, s30
	ds_read_b128 v[194:197], v158 offset:49152
	ds_read_b128 v[198:201], v158 offset:50176
	ds_read_b128 v[202:205], v158 offset:51200
	ds_read_b128 v[206:209], v158 offset:52224
	ds_read_b128 v[210:213], v158 offset:53248
	ds_read_b128 v[214:217], v158 offset:54272
	ds_read_b128 v[218:221], v158 offset:55296
	ds_read_b128 v[222:225], v158 offset:56320
	global_load_lds_dwordx4 v[226:227], off
	s_add_i32 m0, s30, 0x2000
	s_add_u32 s28, s28, 0x40080
	v_lshl_add_u64 v[226:227], v[228:229], 0, s[12:13]
	s_addc_u32 s29, s29, 0
	s_add_i32 s30, s51, s23
	global_load_lds_dwordx4 v[226:227], off
	v_lshl_add_u64 v[226:227], s[28:29], 0, v[132:133]
	s_mov_b32 m0, s30
	s_nop 0
	global_load_lds_dwordx4 v[226:227], off
	v_lshl_add_u64 v[226:227], s[28:29], 0, v[136:137]
	s_add_i32 m0, s30, 0x2000
	s_nop 0
	global_load_lds_dwordx4 v[226:227], off
	v_lshl_add_u64 v[226:227], v[230:231], 0, s[12:13]
	s_mov_b32 m0, s40
	s_nop 0
	global_load_lds_dwordx4 v[226:227], off
	v_lshl_add_u64 v[226:227], v[232:233], 0, s[12:13]
	s_mov_b32 m0, s41
	s_nop 0
	global_load_lds_dwordx4 v[226:227], off
	s_waitcnt vmcnt(8)
	s_waitcnt lgkmcnt(0)
	s_barrier
	s_setprio 1
	s_waitcnt lgkmcnt(0)
	v_mfma_f32_16x16x32_bf16 v[62:65], v[160:163], v[194:197], v[62:65]
	v_mfma_f32_16x16x32_bf16 v[54:57], v[168:171], v[194:197], v[54:57]
	v_mfma_f32_16x16x32_bf16 v[46:49], v[160:163], v[202:205], v[46:49]
	v_mfma_f32_16x16x32_bf16 v[38:41], v[168:171], v[202:205], v[38:41]
	v_mfma_f32_16x16x32_bf16 v[30:33], v[160:163], v[210:213], v[30:33]
	v_mfma_f32_16x16x32_bf16 v[22:25], v[168:171], v[210:213], v[22:25]
	v_mfma_f32_16x16x32_bf16 v[14:17], v[160:163], v[218:221], v[14:17]
	v_mfma_f32_16x16x32_bf16 v[6:9], v[168:171], v[218:221], v[6:9]
	v_mfma_f32_16x16x32_bf16 v[62:65], v[164:167], v[198:201], v[62:65]
	v_mfma_f32_16x16x32_bf16 v[54:57], v[172:175], v[198:201], v[54:57]
	v_mfma_f32_16x16x32_bf16 v[46:49], v[164:167], v[206:209], v[46:49]
	v_mfma_f32_16x16x32_bf16 v[38:41], v[172:175], v[206:209], v[38:41]
	v_mfma_f32_16x16x32_bf16 v[30:33], v[164:167], v[214:217], v[30:33]
	v_mfma_f32_16x16x32_bf16 v[22:25], v[172:175], v[214:217], v[22:25]
	v_mfma_f32_16x16x32_bf16 v[14:17], v[164:167], v[222:225], v[14:17]
	v_mfma_f32_16x16x32_bf16 v[6:9], v[172:175], v[222:225], v[6:9]
	s_setprio 0
	s_setprio 1
	v_mfma_f32_16x16x32_bf16 v[58:61], v[176:179], v[194:197], v[58:61]
	v_mfma_f32_16x16x32_bf16 v[50:53], v[186:189], v[194:197], v[50:53]
	v_mfma_f32_16x16x32_bf16 v[42:45], v[176:179], v[202:205], v[42:45]
	v_mfma_f32_16x16x32_bf16 v[34:37], v[186:189], v[202:205], v[34:37]
	v_mfma_f32_16x16x32_bf16 v[26:29], v[176:179], v[210:213], v[26:29]
	v_mfma_f32_16x16x32_bf16 v[18:21], v[186:189], v[210:213], v[18:21]
	v_mfma_f32_16x16x32_bf16 v[10:13], v[176:179], v[218:221], v[10:13]
	v_mfma_f32_16x16x32_bf16 v[2:5], v[186:189], v[218:221], v[2:5]
	v_mfma_f32_16x16x32_bf16 v[58:61], v[182:185], v[198:201], v[58:61]
	v_mfma_f32_16x16x32_bf16 v[50:53], v[190:193], v[198:201], v[50:53]
	v_mfma_f32_16x16x32_bf16 v[42:45], v[182:185], v[206:209], v[42:45]
	v_mfma_f32_16x16x32_bf16 v[34:37], v[190:193], v[206:209], v[34:37]
	v_mfma_f32_16x16x32_bf16 v[26:29], v[182:185], v[214:217], v[26:29]
	v_mfma_f32_16x16x32_bf16 v[18:21], v[190:193], v[214:217], v[18:21]
	v_mfma_f32_16x16x32_bf16 v[10:13], v[182:185], v[222:225], v[10:13]
	v_mfma_f32_16x16x32_bf16 v[2:5], v[190:193], v[222:225], v[2:5]
	s_setprio 0
	s_barrier
	s_add_i32 s61, s61, 2
	s_add_u32 s26, s26, 0x100
	s_addc_u32 s27, s27, 0
	s_add_u32 s59, s59, 0x100
	s_addc_u32 s60, s60, 0

.LBB0_1176:
	s_add_u32 s20, s20, 0xc000
	s_addc_u32 s21, s21, 0
	s_add_u32 s49, s22, 0x100

	s_addc_u32 s52, s23, 0
	s_mov_b32 s53, -2
	s_waitcnt lgkmcnt(0)


	ds_read_b128 v[146:149], v154
	ds_read_b128 v[158:161], v154 offset:1024
	ds_read_b128 v[162:165], v154 offset:2048
	ds_read_b128 v[166:169], v154 offset:3072
	ds_read_b128 v[170:173], v155
	ds_read_b128 v[174:177], v155 offset:1024
	ds_read_b128 v[182:185], v155 offset:2048
	ds_read_b128 v[186:189], v155 offset:3072
	s_add_u32 s22, s20, 0x4000
	s_addc_u32 s23, s21, 0
	s_cmp_eq_u32 s53, 40
	s_cselect_b32 s26, s6, s22
	s_cselect_b32 s27, s7, s23
	s_cselect_b32 s24, s18, s49
	s_cselect_b32 s25, s19, s52
	s_add_u32 s22, s26, 0x8000
	s_addc_u32 s23, s27, 0
	v_lshl_add_u64 v[178:179], s[20:21], 0, v[138:139]
	s_add_i32 m0, s29, 0xc000
	ds_read_b128 v[190:193], v156
	ds_read_b128 v[194:197], v156 offset:1024
	ds_read_b128 v[198:201], v156 offset:2048
	ds_read_b128 v[202:205], v156 offset:3072
	ds_read_b128 v[206:209], v156 offset:4096
	ds_read_b128 v[210:213], v156 offset:5120
	ds_read_b128 v[214:217], v156 offset:6144
	ds_read_b128 v[218:221], v156 offset:7168
	global_load_lds_dwordx4 v[178:179], off
	v_lshl_add_u64 v[178:179], s[20:21], 0, v[140:141]
	s_add_i32 m0, s29, 0xe000
	s_nop 0
	global_load_lds_dwordx4 v[178:179], off
	s_waitcnt vmcnt(8)
	s_waitcnt lgkmcnt(0)
	s_barrier
	s_setprio 1
	s_waitcnt lgkmcnt(0)
	v_mfma_f32_16x16x32_bf16 v[126:129], v[146:149], v[190:193], 0
	v_mfma_f32_16x16x32_bf16 v[122:125], v[162:165], v[190:193], 0
	v_mfma_f32_16x16x32_bf16 v[110:113], v[146:149], v[198:201], 0
	v_mfma_f32_16x16x32_bf16 v[106:109], v[162:165], v[198:201], 0
	v_mfma_f32_16x16x32_bf16 v[94:97], v[146:149], v[206:209], 0
	v_mfma_f32_16x16x32_bf16 v[90:93], v[162:165], v[206:209], 0
	v_mfma_f32_16x16x32_bf16 v[78:81], v[146:149], v[214:217], 0
	v_mfma_f32_16x16x32_bf16 v[74:77], v[162:165], v[214:217], 0
	v_mfma_f32_16x16x32_bf16 v[126:129], v[158:161], v[194:197], v[126:129]
	v_mfma_f32_16x16x32_bf16 v[122:125], v[166:169], v[194:197], v[122:125]
	v_mfma_f32_16x16x32_bf16 v[110:113], v[158:161], v[202:205], v[110:113]
	v_mfma_f32_16x16x32_bf16 v[106:109], v[166:169], v[202:205], v[106:109]
	v_mfma_f32_16x16x32_bf16 v[94:97], v[158:161], v[210:213], v[94:97]
	v_mfma_f32_16x16x32_bf16 v[90:93], v[166:169], v[210:213], v[90:93]
	v_mfma_f32_16x16x32_bf16 v[78:81], v[158:161], v[218:221], v[78:81]
	v_mfma_f32_16x16x32_bf16 v[74:77], v[166:169], v[218:221], v[74:77]
	s_setprio 0
	s_setprio 1
	v_mfma_f32_16x16x32_bf16 v[118:121], v[170:173], v[190:193], 0
	v_mfma_f32_16x16x32_bf16 v[114:117], v[182:185], v[190:193], 0
	v_mfma_f32_16x16x32_bf16 v[102:105], v[170:173], v[198:201], 0
	v_mfma_f32_16x16x32_bf16 v[98:101], v[182:185], v[198:201], 0
	v_mfma_f32_16x16x32_bf16 v[86:89], v[170:173], v[206:209], 0
	v_mfma_f32_16x16x32_bf16 v[82:85], v[182:185], v[206:209], 0
	v_mfma_f32_16x16x32_bf16 v[70:73], v[170:173], v[214:217], 0
	v_mfma_f32_16x16x32_bf16 v[66:69], v[182:185], v[214:217], 0
	v_mfma_f32_16x16x32_bf16 v[118:121], v[174:177], v[194:197], v[118:121]
	v_mfma_f32_16x16x32_bf16 v[114:117], v[186:189], v[194:197], v[114:117]
	v_mfma_f32_16x16x32_bf16 v[102:105], v[174:177], v[202:205], v[102:105]
	v_mfma_f32_16x16x32_bf16 v[98:101], v[186:189], v[202:205], v[98:101]
	v_mfma_f32_16x16x32_bf16 v[86:89], v[174:177], v[210:213], v[86:89]
	v_mfma_f32_16x16x32_bf16 v[82:85], v[186:189], v[210:213], v[82:85]
	v_mfma_f32_16x16x32_bf16 v[70:73], v[174:177], v[218:221], v[70:73]
	v_mfma_f32_16x16x32_bf16 v[66:69], v[186:189], v[218:221], v[66:69]
	s_setprio 0
	s_barrier
	s_add_i32 s33, s41, s28
	v_lshl_add_u64 v[178:179], s[24:25], 0, v[132:133]
	s_mov_b32 m0, s33
	ds_read_b128 v[190:193], v156 offset:16384
	ds_read_b128 v[194:197], v156 offset:17408
	ds_read_b128 v[198:201], v156 offset:18432
	ds_read_b128 v[202:205], v156 offset:19456
	ds_read_b128 v[206:209], v156 offset:20480
	ds_read_b128 v[210:213], v156 offset:21504
	ds_read_b128 v[214:217], v156 offset:22528
	ds_read_b128 v[218:221], v156 offset:23552
	global_load_lds_dwordx4 v[178:179], off
	s_add_i32 m0, s33, 0x2000
	s_add_u32 s54, s24, 0xb0000
	v_lshl_add_u64 v[222:223], s[24:25], 0, v[136:137]
	s_addc_u32 s55, s25, 0
	s_add_i32 s33, s42, s28
	global_load_lds_dwordx4 v[222:223], off
	v_lshl_add_u64 v[224:225], s[54:55], 0, v[132:133]
	s_mov_b32 m0, s33
	s_nop 0
	global_load_lds_dwordx4 v[224:225], off
	v_lshl_add_u64 v[224:225], s[54:55], 0, v[136:137]
	s_add_i32 m0, s33, 0x2000
	s_nop 0
	global_load_lds_dwordx4 v[224:225], off
	v_lshl_add_u64 v[224:225], s[26:27], 0, v[130:131]
	s_mov_b32 m0, s29
	s_nop 0
	global_load_lds_dwordx4 v[224:225], off
	v_lshl_add_u64 v[224:225], s[26:27], 0, v[134:135]
	s_mov_b32 m0, s30
	s_nop 0
	global_load_lds_dwordx4 v[224:225], off
	s_waitcnt vmcnt(8)
	s_waitcnt lgkmcnt(0)
	s_barrier
	s_setprio 1
	s_waitcnt lgkmcnt(0)
	v_mfma_f32_16x16x32_bf16 v[62:65], v[146:149], v[190:193], 0
	v_mfma_f32_16x16x32_bf16 v[58:61], v[162:165], v[190:193], 0
	v_mfma_f32_16x16x32_bf16 v[46:49], v[146:149], v[198:201], 0
	v_mfma_f32_16x16x32_bf16 v[42:45], v[162:165], v[198:201], 0
	v_mfma_f32_16x16x32_bf16 v[30:33], v[146:149], v[206:209], 0
	v_mfma_f32_16x16x32_bf16 v[26:29], v[162:165], v[206:209], 0
	v_mfma_f32_16x16x32_bf16 v[14:17], v[146:149], v[214:217], 0
	v_mfma_f32_16x16x32_bf16 v[10:13], v[162:165], v[214:217], 0
	v_mfma_f32_16x16x32_bf16 v[62:65], v[158:161], v[194:197], v[62:65]
	v_mfma_f32_16x16x32_bf16 v[58:61], v[166:169], v[194:197], v[58:61]
	v_mfma_f32_16x16x32_bf16 v[46:49], v[158:161], v[202:205], v[46:49]
	v_mfma_f32_16x16x32_bf16 v[42:45], v[166:169], v[202:205], v[42:45]
	v_mfma_f32_16x16x32_bf16 v[30:33], v[158:161], v[210:213], v[30:33]
	v_mfma_f32_16x16x32_bf16 v[26:29], v[166:169], v[210:213], v[26:29]
	v_mfma_f32_16x16x32_bf16 v[14:17], v[158:161], v[218:221], v[14:17]
	v_mfma_f32_16x16x32_bf16 v[10:13], v[166:169], v[218:221], v[10:13]
	s_setprio 0
	s_setprio 1
	v_mfma_f32_16x16x32_bf16 v[54:57], v[170:173], v[190:193], 0
	v_mfma_f32_16x16x32_bf16 v[50:53], v[182:185], v[190:193], 0
	v_mfma_f32_16x16x32_bf16 v[38:41], v[170:173], v[198:201], 0
	v_mfma_f32_16x16x32_bf16 v[34:37], v[182:185], v[198:201], 0
	v_mfma_f32_16x16x32_bf16 v[22:25], v[170:173], v[206:209], 0
	v_mfma_f32_16x16x32_bf16 v[18:21], v[182:185], v[206:209], 0
	v_mfma_f32_16x16x32_bf16 v[6:9], v[170:173], v[214:217], 0
	v_mfma_f32_16x16x32_bf16 v[2:5], v[182:185], v[214:217], 0
	v_mfma_f32_16x16x32_bf16 v[54:57], v[174:177], v[194:197], v[54:57]
	v_mfma_f32_16x16x32_bf16 v[50:53], v[186:189], v[194:197], v[50:53]
	v_mfma_f32_16x16x32_bf16 v[38:41], v[174:177], v[202:205], v[38:41]
	v_mfma_f32_16x16x32_bf16 v[34:37], v[186:189], v[202:205], v[34:37]
	v_mfma_f32_16x16x32_bf16 v[22:25], v[174:177], v[210:213], v[22:25]
	v_mfma_f32_16x16x32_bf16 v[18:21], v[186:189], v[210:213], v[18:21]
	v_mfma_f32_16x16x32_bf16 v[6:9], v[174:177], v[218:221], v[6:9]
	v_mfma_f32_16x16x32_bf16 v[2:5], v[186:189], v[218:221], v[2:5]
	s_setprio 0
	s_barrier
	s_add_i32 s33, 0, 0x18000
	s_add_i32 s51, 0, 0x1c000
	v_add_u32_e32 v166, s33, v152
	v_add_u32_e32 v186, s51, v152
	ds_read_b128 v[146:149], v166
	ds_read_b128 v[158:161], v166 offset:1024
	ds_read_b128 v[162:165], v166 offset:2048
	ds_read_b128 v[166:169], v166 offset:3072
	ds_read_b128 v[170:173], v186
	ds_read_b128 v[174:177], v186 offset:1024
	ds_read_b128 v[182:185], v186 offset:2048
	ds_read_b128 v[186:189], v186 offset:3072
	s_add_u32 s26, s26, 0x4000
	s_addc_u32 s27, s27, 0
	s_mov_b32 m0, s31
	v_lshl_add_u64 v[224:225], s[26:27], 0, v[130:131]
	ds_read_b128 v[190:193], v156 offset:32768
	ds_read_b128 v[194:197], v156 offset:33792
	ds_read_b128 v[198:201], v156 offset:34816
	ds_read_b128 v[202:205], v156 offset:35840
	ds_read_b128 v[206:209], v156 offset:36864
	ds_read_b128 v[210:213], v156 offset:37888
	ds_read_b128 v[214:217], v156 offset:38912
	ds_read_b128 v[218:221], v156 offset:39936
	global_load_lds_dwordx4 v[224:225], off
	v_lshl_add_u64 v[224:225], s[26:27], 0, v[134:135]
	s_mov_b32 m0, s34
	s_nop 0
	global_load_lds_dwordx4 v[224:225], off
	s_waitcnt vmcnt(8)
	s_waitcnt lgkmcnt(0)
	s_barrier
	s_setprio 1
	s_waitcnt lgkmcnt(0)
	v_mfma_f32_16x16x32_bf16 v[126:129], v[146:149], v[190:193], v[126:129]
	v_mfma_f32_16x16x32_bf16 v[122:125], v[162:165], v[190:193], v[122:125]
	v_mfma_f32_16x16x32_bf16 v[110:113], v[146:149], v[198:201], v[110:113]
	v_mfma_f32_16x16x32_bf16 v[106:109], v[162:165], v[198:201], v[106:109]
	v_mfma_f32_16x16x32_bf16 v[94:97], v[146:149], v[206:209], v[94:97]
	v_mfma_f32_16x16x32_bf16 v[90:93], v[162:165], v[206:209], v[90:93]
	v_mfma_f32_16x16x32_bf16 v[78:81], v[146:149], v[214:217], v[78:81]
	v_mfma_f32_16x16x32_bf16 v[74:77], v[162:165], v[214:217], v[74:77]
	v_mfma_f32_16x16x32_bf16 v[126:129], v[158:161], v[194:197], v[126:129]
	v_mfma_f32_16x16x32_bf16 v[122:125], v[166:169], v[194:197], v[122:125]
	v_mfma_f32_16x16x32_bf16 v[110:113], v[158:161], v[202:205], v[110:113]
	v_mfma_f32_16x16x32_bf16 v[106:109], v[166:169], v[202:205], v[106:109]
	v_mfma_f32_16x16x32_bf16 v[94:97], v[158:161], v[210:213], v[94:97]
	v_mfma_f32_16x16x32_bf16 v[90:93], v[166:169], v[210:213], v[90:93]
	v_mfma_f32_16x16x32_bf16 v[78:81], v[158:161], v[218:221], v[78:81]
	v_mfma_f32_16x16x32_bf16 v[74:77], v[166:169], v[218:221], v[74:77]
	s_setprio 0
	s_setprio 1
	v_mfma_f32_16x16x32_bf16 v[118:121], v[170:173], v[190:193], v[118:121]
	v_mfma_f32_16x16x32_bf16 v[114:117], v[182:185], v[190:193], v[114:117]
	v_mfma_f32_16x16x32_bf16 v[102:105], v[170:173], v[198:201], v[102:105]
	v_mfma_f32_16x16x32_bf16 v[98:101], v[182:185], v[198:201], v[98:101]
	v_mfma_f32_16x16x32_bf16 v[86:89], v[170:173], v[206:209], v[86:89]
	v_mfma_f32_16x16x32_bf16 v[82:85], v[182:185], v[206:209], v[82:85]
	v_mfma_f32_16x16x32_bf16 v[70:73], v[170:173], v[214:217], v[70:73]
	v_mfma_f32_16x16x32_bf16 v[66:69], v[182:185], v[214:217], v[66:69]
	v_mfma_f32_16x16x32_bf16 v[118:121], v[174:177], v[194:197], v[118:121]
	v_mfma_f32_16x16x32_bf16 v[114:117], v[186:189], v[194:197], v[114:117]
	v_mfma_f32_16x16x32_bf16 v[102:105], v[174:177], v[202:205], v[102:105]
	v_mfma_f32_16x16x32_bf16 v[98:101], v[186:189], v[202:205], v[98:101]
	v_mfma_f32_16x16x32_bf16 v[86:89], v[174:177], v[210:213], v[86:89]
	v_mfma_f32_16x16x32_bf16 v[82:85], v[186:189], v[210:213], v[82:85]
	v_mfma_f32_16x16x32_bf16 v[70:73], v[174:177], v[218:221], v[70:73]
	v_mfma_f32_16x16x32_bf16 v[66:69], v[186:189], v[218:221], v[66:69]
	s_setprio 0
	s_barrier
	s_add_i32 s26, s33, s28
	v_lshl_add_u64 v[178:179], v[178:179], 0, s[14:15]
	s_mov_b32 m0, s26
	ds_read_b128 v[190:193], v156 offset:49152
	ds_read_b128 v[194:197], v156 offset:50176
	ds_read_b128 v[198:201], v156 offset:51200
	ds_read_b128 v[202:205], v156 offset:52224
	ds_read_b128 v[206:209], v156 offset:53248
	ds_read_b128 v[210:213], v156 offset:54272
	ds_read_b128 v[214:217], v156 offset:55296
	ds_read_b128 v[218:221], v156 offset:56320
	global_load_lds_dwordx4 v[178:179], off
	s_add_i32 m0, s26, 0x2000
	s_add_u32 s24, s24, 0xb0080
	v_lshl_add_u64 v[178:179], v[222:223], 0, s[14:15]
	s_addc_u32 s25, s25, 0
	s_add_i32 s26, s51, s28
	global_load_lds_dwordx4 v[178:179], off
	v_lshl_add_u64 v[178:179], s[24:25], 0, v[132:133]
	s_mov_b32 m0, s26
	s_nop 0
	global_load_lds_dwordx4 v[178:179], off
	v_lshl_add_u64 v[178:179], s[24:25], 0, v[136:137]
	s_add_i32 m0, s26, 0x2000
	s_nop 0
	global_load_lds_dwordx4 v[178:179], off
	v_lshl_add_u64 v[178:179], s[22:23], 0, v[130:131]
	s_mov_b32 m0, s36
	s_nop 0
	global_load_lds_dwordx4 v[178:179], off
	v_lshl_add_u64 v[178:179], s[22:23], 0, v[134:135]
	s_mov_b32 m0, s37
	s_nop 0
	global_load_lds_dwordx4 v[178:179], off
	s_waitcnt vmcnt(8)
	s_waitcnt lgkmcnt(0)
	s_barrier
	s_setprio 1
	s_waitcnt lgkmcnt(0)
	v_mfma_f32_16x16x32_bf16 v[62:65], v[146:149], v[190:193], v[62:65]
	v_mfma_f32_16x16x32_bf16 v[58:61], v[162:165], v[190:193], v[58:61]
	v_mfma_f32_16x16x32_bf16 v[46:49], v[146:149], v[198:201], v[46:49]
	v_mfma_f32_16x16x32_bf16 v[42:45], v[162:165], v[198:201], v[42:45]
	v_mfma_f32_16x16x32_bf16 v[30:33], v[146:149], v[206:209], v[30:33]
	v_mfma_f32_16x16x32_bf16 v[26:29], v[162:165], v[206:209], v[26:29]
	v_mfma_f32_16x16x32_bf16 v[14:17], v[146:149], v[214:217], v[14:17]
	v_mfma_f32_16x16x32_bf16 v[10:13], v[162:165], v[214:217], v[10:13]
	v_mfma_f32_16x16x32_bf16 v[62:65], v[158:161], v[194:197], v[62:65]
	v_mfma_f32_16x16x32_bf16 v[58:61], v[166:169], v[194:197], v[58:61]
	v_mfma_f32_16x16x32_bf16 v[46:49], v[158:161], v[202:205], v[46:49]
	v_mfma_f32_16x16x32_bf16 v[42:45], v[166:169], v[202:205], v[42:45]
	v_mfma_f32_16x16x32_bf16 v[30:33], v[158:161], v[210:213], v[30:33]
	v_mfma_f32_16x16x32_bf16 v[26:29], v[166:169], v[210:213], v[26:29]
	v_mfma_f32_16x16x32_bf16 v[14:17], v[158:161], v[218:221], v[14:17]
	v_mfma_f32_16x16x32_bf16 v[10:13], v[166:169], v[218:221], v[10:13]
	s_setprio 0
	s_setprio 1
	v_mfma_f32_16x16x32_bf16 v[54:57], v[170:173], v[190:193], v[54:57]
	v_mfma_f32_16x16x32_bf16 v[50:53], v[182:185], v[190:193], v[50:53]
	v_mfma_f32_16x16x32_bf16 v[38:41], v[170:173], v[198:201], v[38:41]
	v_mfma_f32_16x16x32_bf16 v[34:37], v[182:185], v[198:201], v[34:37]
	v_mfma_f32_16x16x32_bf16 v[22:25], v[170:173], v[206:209], v[22:25]
	v_mfma_f32_16x16x32_bf16 v[18:21], v[182:185], v[206:209], v[18:21]
	v_mfma_f32_16x16x32_bf16 v[6:9], v[170:173], v[214:217], v[6:9]
	v_mfma_f32_16x16x32_bf16 v[2:5], v[182:185], v[214:217], v[2:5]
	v_mfma_f32_16x16x32_bf16 v[54:57], v[174:177], v[194:197], v[54:57]
	v_mfma_f32_16x16x32_bf16 v[50:53], v[186:189], v[194:197], v[50:53]
	v_mfma_f32_16x16x32_bf16 v[38:41], v[174:177], v[202:205], v[38:41]
	v_mfma_f32_16x16x32_bf16 v[34:37], v[186:189], v[202:205], v[34:37]
	v_mfma_f32_16x16x32_bf16 v[22:25], v[174:177], v[210:213], v[22:25]
	v_mfma_f32_16x16x32_bf16 v[18:21], v[186:189], v[210:213], v[18:21]
	v_mfma_f32_16x16x32_bf16 v[6:9], v[174:177], v[218:221], v[6:9]
	v_mfma_f32_16x16x32_bf16 v[2:5], v[186:189], v[218:221], v[2:5]
	s_setprio 0
	s_barrier
	s_add_i32 s53, s53, 2
	s_add_u32 s20, s20, 0x10000
	s_addc_u32 s21, s21, 0
	s_add_u32 s49, s49, 0x100
	s_addc_u32 s52, s52, 0

.LBB0_1360:
	s_ashr_i32 s17, s16, 31
	s_lshl_b64 s[18:19], s[16:17], 19
	s_add_u32 s18, s92, s18
	s_addc_u32 s19, s93, s19
	s_and_b64 s[20:21], s[2:3], exec
	s_cselect_b32 s17, s19, s27
	s_cselect_b32 s57, s18, s26
	s_ashr_i32 s7, s6, 31
	s_lshl_b64 s[20:21], s[6:7], 19
	s_add_u32 s20, s35, s20
	s_addc_u32 s21, s36, s21
	s_and_b64 s[30:31], s[2:3], exec
	s_cselect_b32 s7, s21, s29
	s_cselect_b32 s58, s20, s28
	s_add_u32 s26, s26, 0x40080
	s_addc_u32 s27, s27, 0
	s_add_u32 s59, s28, 0x100

	s_addc_u32 s60, s29, 0
	s_mov_b32 s61, -2


	ds_read_b128 v[160:163], v156
	ds_read_b128 v[164:167], v156 offset:1024
	ds_read_b128 v[168:171], v156 offset:2048
	ds_read_b128 v[172:175], v156 offset:3072
	ds_read_b128 v[176:179], v157
	ds_read_b128 v[182:185], v157 offset:1024
	ds_read_b128 v[186:189], v157 offset:2048
	ds_read_b128 v[190:193], v157 offset:3072
	s_add_u32 s28, s26, 0xfffc0080
	s_addc_u32 s29, s27, -1
	s_cmp_eq_u32 s61, 12
	s_cselect_b32 s31, s17, s29
	s_cselect_b32 s30, s57, s28
	s_cselect_b32 s29, s7, s60
	s_cselect_b32 s28, s58, s59
	v_lshl_add_u64 v[226:227], s[26:27], 0, v[136:137]
	s_add_i32 m0, s25, 0xc000
	ds_read_b128 v[194:197], v158
	ds_read_b128 v[198:201], v158 offset:1024
	ds_read_b128 v[202:205], v158 offset:2048
	ds_read_b128 v[206:209], v158 offset:3072
	ds_read_b128 v[210:213], v158 offset:4096
	ds_read_b128 v[214:217], v158 offset:5120
	ds_read_b128 v[218:221], v158 offset:6144
	ds_read_b128 v[222:225], v158 offset:7168
	global_load_lds_dwordx4 v[226:227], off
	v_lshl_add_u64 v[226:227], s[26:27], 0, v[138:139]
	s_add_i32 m0, s25, 0xe000
	s_nop 0
	global_load_lds_dwordx4 v[226:227], off
	s_waitcnt vmcnt(8)
	s_waitcnt lgkmcnt(0)
	s_barrier
	s_setprio 1
	s_waitcnt lgkmcnt(0)
	v_mfma_f32_16x16x32_bf16 v[126:129], v[160:163], v[194:197], 0
	v_mfma_f32_16x16x32_bf16 v[118:121], v[168:171], v[194:197], 0
	v_mfma_f32_16x16x32_bf16 v[110:113], v[160:163], v[202:205], 0
	v_mfma_f32_16x16x32_bf16 v[102:105], v[168:171], v[202:205], 0
	v_mfma_f32_16x16x32_bf16 v[94:97], v[160:163], v[210:213], 0
	v_mfma_f32_16x16x32_bf16 v[86:89], v[168:171], v[210:213], 0
	v_mfma_f32_16x16x32_bf16 v[78:81], v[160:163], v[218:221], 0
	v_mfma_f32_16x16x32_bf16 v[70:73], v[168:171], v[218:221], 0
	v_mfma_f32_16x16x32_bf16 v[126:129], v[164:167], v[198:201], v[126:129]
	v_mfma_f32_16x16x32_bf16 v[118:121], v[172:175], v[198:201], v[118:121]
	v_mfma_f32_16x16x32_bf16 v[110:113], v[164:167], v[206:209], v[110:113]
	v_mfma_f32_16x16x32_bf16 v[102:105], v[172:175], v[206:209], v[102:105]
	v_mfma_f32_16x16x32_bf16 v[94:97], v[164:167], v[214:217], v[94:97]
	v_mfma_f32_16x16x32_bf16 v[86:89], v[172:175], v[214:217], v[86:89]
	v_mfma_f32_16x16x32_bf16 v[78:81], v[164:167], v[222:225], v[78:81]
	v_mfma_f32_16x16x32_bf16 v[70:73], v[172:175], v[222:225], v[70:73]
	s_setprio 0
	s_setprio 1
	v_mfma_f32_16x16x32_bf16 v[122:125], v[176:179], v[194:197], 0
	v_mfma_f32_16x16x32_bf16 v[114:117], v[186:189], v[194:197], 0
	v_mfma_f32_16x16x32_bf16 v[106:109], v[176:179], v[202:205], 0
	v_mfma_f32_16x16x32_bf16 v[98:101], v[186:189], v[202:205], 0
	v_mfma_f32_16x16x32_bf16 v[90:93], v[176:179], v[210:213], 0
	v_mfma_f32_16x16x32_bf16 v[82:85], v[186:189], v[210:213], 0
	v_mfma_f32_16x16x32_bf16 v[74:77], v[176:179], v[218:221], 0
	v_mfma_f32_16x16x32_bf16 v[66:69], v[186:189], v[218:221], 0
	v_mfma_f32_16x16x32_bf16 v[122:125], v[182:185], v[198:201], v[122:125]
	v_mfma_f32_16x16x32_bf16 v[114:117], v[190:193], v[198:201], v[114:117]
	v_mfma_f32_16x16x32_bf16 v[106:109], v[182:185], v[206:209], v[106:109]
	v_mfma_f32_16x16x32_bf16 v[98:101], v[190:193], v[206:209], v[98:101]
	v_mfma_f32_16x16x32_bf16 v[90:93], v[182:185], v[214:217], v[90:93]
	v_mfma_f32_16x16x32_bf16 v[82:85], v[190:193], v[214:217], v[82:85]
	v_mfma_f32_16x16x32_bf16 v[74:77], v[182:185], v[222:225], v[74:77]
	v_mfma_f32_16x16x32_bf16 v[66:69], v[190:193], v[222:225], v[66:69]
	s_setprio 0
	s_barrier
	s_add_i32 s33, s52, s23
	v_lshl_add_u64 v[226:227], s[28:29], 0, v[148:149]
	s_mov_b32 m0, s33
	ds_read_b128 v[194:197], v158 offset:16384
	ds_read_b128 v[198:201], v158 offset:17408
	ds_read_b128 v[202:205], v158 offset:18432
	ds_read_b128 v[206:209], v158 offset:19456
	ds_read_b128 v[210:213], v158 offset:20480
	ds_read_b128 v[214:217], v158 offset:21504
	ds_read_b128 v[218:221], v158 offset:22528
	ds_read_b128 v[222:225], v158 offset:23552
	global_load_lds_dwordx4 v[226:227], off
	s_add_i32 m0, s33, 0x2000
	s_add_u32 s62, s28, 0x40000
	v_lshl_add_u64 v[228:229], s[28:29], 0, v[152:153]
	s_addc_u32 s63, s29, 0
	s_add_i32 s33, s53, s23
	global_load_lds_dwordx4 v[228:229], off
	v_lshl_add_u64 v[230:231], s[62:63], 0, v[148:149]
	s_mov_b32 m0, s33
	v_lshl_add_u64 v[232:233], s[30:31], 0, v[150:151]
	global_load_lds_dwordx4 v[230:231], off
	v_lshl_add_u64 v[230:231], s[62:63], 0, v[152:153]
	s_add_i32 m0, s33, 0x2000
	s_nop 0
	global_load_lds_dwordx4 v[230:231], off
	v_lshl_add_u64 v[230:231], s[30:31], 0, v[146:147]
	s_mov_b32 m0, s25
	s_nop 0
	global_load_lds_dwordx4 v[230:231], off
	s_mov_b32 m0, s37
	s_nop 0
	global_load_lds_dwordx4 v[232:233], off
	s_waitcnt vmcnt(8)
	s_waitcnt lgkmcnt(0)
	s_barrier
	s_setprio 1
	s_waitcnt lgkmcnt(0)
	v_mfma_f32_16x16x32_bf16 v[62:65], v[160:163], v[194:197], 0
	v_mfma_f32_16x16x32_bf16 v[54:57], v[168:171], v[194:197], 0
	v_mfma_f32_16x16x32_bf16 v[46:49], v[160:163], v[202:205], 0
	v_mfma_f32_16x16x32_bf16 v[38:41], v[168:171], v[202:205], 0
	v_mfma_f32_16x16x32_bf16 v[30:33], v[160:163], v[210:213], 0
	v_mfma_f32_16x16x32_bf16 v[22:25], v[168:171], v[210:213], 0
	v_mfma_f32_16x16x32_bf16 v[14:17], v[160:163], v[218:221], 0
	v_mfma_f32_16x16x32_bf16 v[6:9], v[168:171], v[218:221], 0
	v_mfma_f32_16x16x32_bf16 v[62:65], v[164:167], v[198:201], v[62:65]
	v_mfma_f32_16x16x32_bf16 v[54:57], v[172:175], v[198:201], v[54:57]
	v_mfma_f32_16x16x32_bf16 v[46:49], v[164:167], v[206:209], v[46:49]
	v_mfma_f32_16x16x32_bf16 v[38:41], v[172:175], v[206:209], v[38:41]
	v_mfma_f32_16x16x32_bf16 v[30:33], v[164:167], v[214:217], v[30:33]
	v_mfma_f32_16x16x32_bf16 v[22:25], v[172:175], v[214:217], v[22:25]
	v_mfma_f32_16x16x32_bf16 v[14:17], v[164:167], v[222:225], v[14:17]
	v_mfma_f32_16x16x32_bf16 v[6:9], v[172:175], v[222:225], v[6:9]
	s_setprio 0
	s_setprio 1
	v_mfma_f32_16x16x32_bf16 v[58:61], v[176:179], v[194:197], 0
	v_mfma_f32_16x16x32_bf16 v[50:53], v[186:189], v[194:197], 0
	v_mfma_f32_16x16x32_bf16 v[42:45], v[176:179], v[202:205], 0
	v_mfma_f32_16x16x32_bf16 v[34:37], v[186:189], v[202:205], 0
	v_mfma_f32_16x16x32_bf16 v[26:29], v[176:179], v[210:213], 0
	v_mfma_f32_16x16x32_bf16 v[18:21], v[186:189], v[210:213], 0
	v_mfma_f32_16x16x32_bf16 v[10:13], v[176:179], v[218:221], 0
	v_mfma_f32_16x16x32_bf16 v[2:5], v[186:189], v[218:221], 0
	v_mfma_f32_16x16x32_bf16 v[58:61], v[182:185], v[198:201], v[58:61]
	v_mfma_f32_16x16x32_bf16 v[50:53], v[190:193], v[198:201], v[50:53]
	v_mfma_f32_16x16x32_bf16 v[42:45], v[182:185], v[206:209], v[42:45]
	v_mfma_f32_16x16x32_bf16 v[34:37], v[190:193], v[206:209], v[34:37]
	v_mfma_f32_16x16x32_bf16 v[26:29], v[182:185], v[214:217], v[26:29]
	v_mfma_f32_16x16x32_bf16 v[18:21], v[190:193], v[214:217], v[18:21]
	v_mfma_f32_16x16x32_bf16 v[10:13], v[182:185], v[222:225], v[10:13]
	v_mfma_f32_16x16x32_bf16 v[2:5], v[190:193], v[222:225], v[2:5]
	s_setprio 0
	s_barrier
	s_add_i32 s33, 0, 0x18000
	v_add_u32_e32 v130, s33, v154
	s_add_i32 s51, 0, 0x1c000
	ds_read_b128 v[160:163], v130
	ds_read_b128 v[164:167], v130 offset:1024
	ds_read_b128 v[168:171], v130 offset:2048
	ds_read_b128 v[172:175], v130 offset:3072
	v_add_u32_e32 v130, s51, v154
	ds_read_b128 v[176:179], v130
	ds_read_b128 v[182:185], v130 offset:1024
	ds_read_b128 v[186:189], v130 offset:2048
	ds_read_b128 v[190:193], v130 offset:3072
	s_add_u32 s30, s30, 0x40000
	s_addc_u32 s31, s31, 0
	s_mov_b32 m0, s38
	v_lshl_add_u64 v[234:235], s[30:31], 0, v[146:147]
	ds_read_b128 v[194:197], v158 offset:32768
	ds_read_b128 v[198:201], v158 offset:33792
	ds_read_b128 v[202:205], v158 offset:34816
	ds_read_b128 v[206:209], v158 offset:35840
	ds_read_b128 v[210:213], v158 offset:36864
	ds_read_b128 v[214:217], v158 offset:37888
	ds_read_b128 v[218:221], v158 offset:38912
	ds_read_b128 v[222:225], v158 offset:39936
	global_load_lds_dwordx4 v[234:235], off
	v_lshl_add_u64 v[234:235], s[30:31], 0, v[150:151]
	s_mov_b32 m0, s39
	s_nop 0
	global_load_lds_dwordx4 v[234:235], off
	s_waitcnt vmcnt(8)
	s_waitcnt lgkmcnt(0)
	s_barrier
	s_setprio 1
	s_waitcnt lgkmcnt(0)
	v_mfma_f32_16x16x32_bf16 v[126:129], v[160:163], v[194:197], v[126:129]
	v_mfma_f32_16x16x32_bf16 v[118:121], v[168:171], v[194:197], v[118:121]
	v_mfma_f32_16x16x32_bf16 v[110:113], v[160:163], v[202:205], v[110:113]
	v_mfma_f32_16x16x32_bf16 v[102:105], v[168:171], v[202:205], v[102:105]
	v_mfma_f32_16x16x32_bf16 v[94:97], v[160:163], v[210:213], v[94:97]
	v_mfma_f32_16x16x32_bf16 v[86:89], v[168:171], v[210:213], v[86:89]
	v_mfma_f32_16x16x32_bf16 v[78:81], v[160:163], v[218:221], v[78:81]
	v_mfma_f32_16x16x32_bf16 v[70:73], v[168:171], v[218:221], v[70:73]
	v_mfma_f32_16x16x32_bf16 v[126:129], v[164:167], v[198:201], v[126:129]
	v_mfma_f32_16x16x32_bf16 v[118:121], v[172:175], v[198:201], v[118:121]
	v_mfma_f32_16x16x32_bf16 v[110:113], v[164:167], v[206:209], v[110:113]
	v_mfma_f32_16x16x32_bf16 v[102:105], v[172:175], v[206:209], v[102:105]
	v_mfma_f32_16x16x32_bf16 v[94:97], v[164:167], v[214:217], v[94:97]
	v_mfma_f32_16x16x32_bf16 v[86:89], v[172:175], v[214:217], v[86:89]
	v_mfma_f32_16x16x32_bf16 v[78:81], v[164:167], v[222:225], v[78:81]
	v_mfma_f32_16x16x32_bf16 v[70:73], v[172:175], v[222:225], v[70:73]
	s_setprio 0
	s_setprio 1
	v_mfma_f32_16x16x32_bf16 v[122:125], v[176:179], v[194:197], v[122:125]
	v_mfma_f32_16x16x32_bf16 v[114:117], v[186:189], v[194:197], v[114:117]
	v_mfma_f32_16x16x32_bf16 v[106:109], v[176:179], v[202:205], v[106:109]
	v_mfma_f32_16x16x32_bf16 v[98:101], v[186:189], v[202:205], v[98:101]
	v_mfma_f32_16x16x32_bf16 v[90:93], v[176:179], v[210:213], v[90:93]
	v_mfma_f32_16x16x32_bf16 v[82:85], v[186:189], v[210:213], v[82:85]
	v_mfma_f32_16x16x32_bf16 v[74:77], v[176:179], v[218:221], v[74:77]
	v_mfma_f32_16x16x32_bf16 v[66:69], v[186:189], v[218:221], v[66:69]
	v_mfma_f32_16x16x32_bf16 v[122:125], v[182:185], v[198:201], v[122:125]
	v_mfma_f32_16x16x32_bf16 v[114:117], v[190:193], v[198:201], v[114:117]
	v_mfma_f32_16x16x32_bf16 v[106:109], v[182:185], v[206:209], v[106:109]
	v_mfma_f32_16x16x32_bf16 v[98:101], v[190:193], v[206:209], v[98:101]
	v_mfma_f32_16x16x32_bf16 v[90:93], v[182:185], v[214:217], v[90:93]
	v_mfma_f32_16x16x32_bf16 v[82:85], v[190:193], v[214:217], v[82:85]
	v_mfma_f32_16x16x32_bf16 v[74:77], v[182:185], v[222:225], v[74:77]
	v_mfma_f32_16x16x32_bf16 v[66:69], v[190:193], v[222:225], v[66:69]
	s_setprio 0
	s_barrier
	s_add_i32 s30, s33, s23
	v_lshl_add_u64 v[226:227], v[226:227], 0, s[14:15]
	s_mov_b32 m0, s30
	ds_read_b128 v[194:197], v158 offset:49152
	ds_read_b128 v[198:201], v158 offset:50176
	ds_read_b128 v[202:205], v158 offset:51200
	ds_read_b128 v[206:209], v158 offset:52224
	ds_read_b128 v[210:213], v158 offset:53248
	ds_read_b128 v[214:217], v158 offset:54272
	ds_read_b128 v[218:221], v158 offset:55296
	ds_read_b128 v[222:225], v158 offset:56320
	global_load_lds_dwordx4 v[226:227], off
	s_add_i32 m0, s30, 0x2000
	s_add_u32 s28, s28, 0x40080
	v_lshl_add_u64 v[226:227], v[228:229], 0, s[14:15]
	s_addc_u32 s29, s29, 0
	s_add_i32 s30, s51, s23
	global_load_lds_dwordx4 v[226:227], off
	v_lshl_add_u64 v[226:227], s[28:29], 0, v[148:149]
	s_mov_b32 m0, s30
	s_nop 0
	global_load_lds_dwordx4 v[226:227], off
	v_lshl_add_u64 v[226:227], s[28:29], 0, v[152:153]
	s_add_i32 m0, s30, 0x2000
	s_nop 0
	global_load_lds_dwordx4 v[226:227], off
	v_lshl_add_u64 v[226:227], v[230:231], 0, s[14:15]
	s_mov_b32 m0, s42
	s_nop 0
	global_load_lds_dwordx4 v[226:227], off
	v_lshl_add_u64 v[226:227], v[232:233], 0, s[14:15]
	s_mov_b32 m0, s43
	s_nop 0
	global_load_lds_dwordx4 v[226:227], off
	s_waitcnt vmcnt(8)
	s_waitcnt lgkmcnt(0)
	s_barrier
	s_setprio 1
	s_waitcnt lgkmcnt(0)
	v_mfma_f32_16x16x32_bf16 v[62:65], v[160:163], v[194:197], v[62:65]
	v_mfma_f32_16x16x32_bf16 v[54:57], v[168:171], v[194:197], v[54:57]
	v_mfma_f32_16x16x32_bf16 v[46:49], v[160:163], v[202:205], v[46:49]
	v_mfma_f32_16x16x32_bf16 v[38:41], v[168:171], v[202:205], v[38:41]
	v_mfma_f32_16x16x32_bf16 v[30:33], v[160:163], v[210:213], v[30:33]
	v_mfma_f32_16x16x32_bf16 v[22:25], v[168:171], v[210:213], v[22:25]
	v_mfma_f32_16x16x32_bf16 v[14:17], v[160:163], v[218:221], v[14:17]
	v_mfma_f32_16x16x32_bf16 v[6:9], v[168:171], v[218:221], v[6:9]
	v_mfma_f32_16x16x32_bf16 v[62:65], v[164:167], v[198:201], v[62:65]
	v_mfma_f32_16x16x32_bf16 v[54:57], v[172:175], v[198:201], v[54:57]
	v_mfma_f32_16x16x32_bf16 v[46:49], v[164:167], v[206:209], v[46:49]
	v_mfma_f32_16x16x32_bf16 v[38:41], v[172:175], v[206:209], v[38:41]
	v_mfma_f32_16x16x32_bf16 v[30:33], v[164:167], v[214:217], v[30:33]
	v_mfma_f32_16x16x32_bf16 v[22:25], v[172:175], v[214:217], v[22:25]
	v_mfma_f32_16x16x32_bf16 v[14:17], v[164:167], v[222:225], v[14:17]
	v_mfma_f32_16x16x32_bf16 v[6:9], v[172:175], v[222:225], v[6:9]
	s_setprio 0
	s_setprio 1
	v_mfma_f32_16x16x32_bf16 v[58:61], v[176:179], v[194:197], v[58:61]
	v_mfma_f32_16x16x32_bf16 v[50:53], v[186:189], v[194:197], v[50:53]
	v_mfma_f32_16x16x32_bf16 v[42:45], v[176:179], v[202:205], v[42:45]
	v_mfma_f32_16x16x32_bf16 v[34:37], v[186:189], v[202:205], v[34:37]
	v_mfma_f32_16x16x32_bf16 v[26:29], v[176:179], v[210:213], v[26:29]
	v_mfma_f32_16x16x32_bf16 v[18:21], v[186:189], v[210:213], v[18:21]
	v_mfma_f32_16x16x32_bf16 v[10:13], v[176:179], v[218:221], v[10:13]
	v_mfma_f32_16x16x32_bf16 v[2:5], v[186:189], v[218:221], v[2:5]
	v_mfma_f32_16x16x32_bf16 v[58:61], v[182:185], v[198:201], v[58:61]
	v_mfma_f32_16x16x32_bf16 v[50:53], v[190:193], v[198:201], v[50:53]
	v_mfma_f32_16x16x32_bf16 v[42:45], v[182:185], v[206:209], v[42:45]
	v_mfma_f32_16x16x32_bf16 v[34:37], v[190:193], v[206:209], v[34:37]
	v_mfma_f32_16x16x32_bf16 v[26:29], v[182:185], v[214:217], v[26:29]
	v_mfma_f32_16x16x32_bf16 v[18:21], v[190:193], v[214:217], v[18:21]
	v_mfma_f32_16x16x32_bf16 v[10:13], v[182:185], v[222:225], v[10:13]
	v_mfma_f32_16x16x32_bf16 v[2:5], v[190:193], v[222:225], v[2:5]
	s_setprio 0
	s_barrier
	s_add_i32 s61, s61, 2
	s_add_u32 s26, s26, 0x100
	s_addc_u32 s27, s27, 0
	s_add_u32 s59, s59, 0x100
	s_addc_u32 s60, s60, 0

.LBB0_1461:
	s_add_u32 s22, s22, 0xc000
	s_addc_u32 s23, s23, 0
	s_add_u32 s55, s24, 0x100

	s_addc_u32 s56, s25, 0
	s_mov_b32 s57, -2
	s_waitcnt lgkmcnt(0)


	ds_read_b128 v[146:149], v152
	ds_read_b128 v[156:159], v152 offset:1024
	ds_read_b128 v[160:163], v152 offset:2048
	ds_read_b128 v[164:167], v152 offset:3072
	ds_read_b128 v[168:171], v153
	ds_read_b128 v[172:175], v153 offset:1024
	ds_read_b128 v[176:179], v153 offset:2048
	ds_read_b128 v[182:185], v153 offset:3072
	s_add_u32 s24, s22, 0x4000
	s_addc_u32 s25, s23, 0
	s_cmp_eq_u32 s57, 40
	s_cselect_b32 s28, s6, s24
	s_cselect_b32 s29, s7, s25
	s_cselect_b32 s26, s20, s55
	s_cselect_b32 s27, s21, s56
	s_add_u32 s24, s28, 0x8000
	s_addc_u32 s25, s29, 0
	v_lshl_add_u64 v[218:219], s[22:23], 0, v[138:139]
	s_add_i32 m0, s35, 0xc000
	ds_read_b128 v[186:189], v154
	ds_read_b128 v[190:193], v154 offset:1024
	ds_read_b128 v[194:197], v154 offset:2048
	ds_read_b128 v[198:201], v154 offset:3072
	ds_read_b128 v[202:205], v154 offset:4096
	ds_read_b128 v[206:209], v154 offset:5120
	ds_read_b128 v[210:213], v154 offset:6144
	ds_read_b128 v[214:217], v154 offset:7168
	global_load_lds_dwordx4 v[218:219], off
	v_lshl_add_u64 v[218:219], s[22:23], 0, v[140:141]
	s_add_i32 m0, s35, 0xe000
	s_nop 0
	global_load_lds_dwordx4 v[218:219], off
	s_waitcnt vmcnt(8)
	s_waitcnt lgkmcnt(0)
	s_barrier
	s_setprio 1
	s_waitcnt lgkmcnt(0)
	v_mfma_f32_16x16x32_bf16 v[126:129], v[146:149], v[186:189], 0
	v_mfma_f32_16x16x32_bf16 v[122:125], v[160:163], v[186:189], 0
	v_mfma_f32_16x16x32_bf16 v[110:113], v[146:149], v[194:197], 0
	v_mfma_f32_16x16x32_bf16 v[106:109], v[160:163], v[194:197], 0
	v_mfma_f32_16x16x32_bf16 v[94:97], v[146:149], v[202:205], 0
	v_mfma_f32_16x16x32_bf16 v[90:93], v[160:163], v[202:205], 0
	v_mfma_f32_16x16x32_bf16 v[78:81], v[146:149], v[210:213], 0
	v_mfma_f32_16x16x32_bf16 v[74:77], v[160:163], v[210:213], 0
	v_mfma_f32_16x16x32_bf16 v[126:129], v[156:159], v[190:193], v[126:129]
	v_mfma_f32_16x16x32_bf16 v[122:125], v[164:167], v[190:193], v[122:125]
	v_mfma_f32_16x16x32_bf16 v[110:113], v[156:159], v[198:201], v[110:113]
	v_mfma_f32_16x16x32_bf16 v[106:109], v[164:167], v[198:201], v[106:109]
	v_mfma_f32_16x16x32_bf16 v[94:97], v[156:159], v[206:209], v[94:97]
	v_mfma_f32_16x16x32_bf16 v[90:93], v[164:167], v[206:209], v[90:93]
	v_mfma_f32_16x16x32_bf16 v[78:81], v[156:159], v[214:217], v[78:81]
	v_mfma_f32_16x16x32_bf16 v[74:77], v[164:167], v[214:217], v[74:77]
	s_setprio 0
	s_setprio 1
	v_mfma_f32_16x16x32_bf16 v[118:121], v[168:171], v[186:189], 0
	v_mfma_f32_16x16x32_bf16 v[114:117], v[176:179], v[186:189], 0
	v_mfma_f32_16x16x32_bf16 v[102:105], v[168:171], v[194:197], 0
	v_mfma_f32_16x16x32_bf16 v[98:101], v[176:179], v[194:197], 0
	v_mfma_f32_16x16x32_bf16 v[86:89], v[168:171], v[202:205], 0
	v_mfma_f32_16x16x32_bf16 v[82:85], v[176:179], v[202:205], 0
	v_mfma_f32_16x16x32_bf16 v[70:73], v[168:171], v[210:213], 0
	v_mfma_f32_16x16x32_bf16 v[66:69], v[176:179], v[210:213], 0
	v_mfma_f32_16x16x32_bf16 v[118:121], v[172:175], v[190:193], v[118:121]
	v_mfma_f32_16x16x32_bf16 v[114:117], v[182:185], v[190:193], v[114:117]
	v_mfma_f32_16x16x32_bf16 v[102:105], v[172:175], v[198:201], v[102:105]
	v_mfma_f32_16x16x32_bf16 v[98:101], v[182:185], v[198:201], v[98:101]
	v_mfma_f32_16x16x32_bf16 v[86:89], v[172:175], v[206:209], v[86:89]
	v_mfma_f32_16x16x32_bf16 v[82:85], v[182:185], v[206:209], v[82:85]
	v_mfma_f32_16x16x32_bf16 v[70:73], v[172:175], v[214:217], v[70:73]
	v_mfma_f32_16x16x32_bf16 v[66:69], v[182:185], v[214:217], v[66:69]
	s_setprio 0
	s_barrier
	s_add_i32 s33, s47, s34
	v_lshl_add_u64 v[218:219], s[26:27], 0, v[132:133]
	s_mov_b32 m0, s33
	ds_read_b128 v[186:189], v154 offset:16384
	ds_read_b128 v[190:193], v154 offset:17408
	ds_read_b128 v[194:197], v154 offset:18432
	ds_read_b128 v[198:201], v154 offset:19456
	ds_read_b128 v[202:205], v154 offset:20480
	ds_read_b128 v[206:209], v154 offset:21504
	ds_read_b128 v[210:213], v154 offset:22528
	ds_read_b128 v[214:217], v154 offset:23552
	global_load_lds_dwordx4 v[218:219], off
	s_add_i32 m0, s33, 0x2000
	s_add_u32 s58, s26, 0xb0000
	v_lshl_add_u64 v[220:221], s[26:27], 0, v[136:137]
	s_addc_u32 s59, s27, 0
	s_add_i32 s33, s48, s34
	global_load_lds_dwordx4 v[220:221], off
	v_lshl_add_u64 v[222:223], s[58:59], 0, v[132:133]
	s_mov_b32 m0, s33
	s_nop 0
	global_load_lds_dwordx4 v[222:223], off
	v_lshl_add_u64 v[222:223], s[58:59], 0, v[136:137]
	s_add_i32 m0, s33, 0x2000
	s_nop 0
	global_load_lds_dwordx4 v[222:223], off
	v_lshl_add_u64 v[222:223], s[28:29], 0, v[130:131]
	s_mov_b32 m0, s35
	s_nop 0
	global_load_lds_dwordx4 v[222:223], off
	v_lshl_add_u64 v[222:223], s[28:29], 0, v[134:135]
	s_mov_b32 m0, s36
	s_nop 0
	global_load_lds_dwordx4 v[222:223], off
	s_waitcnt vmcnt(8)
	s_waitcnt lgkmcnt(0)
	s_barrier
	s_setprio 1
	s_waitcnt lgkmcnt(0)
	v_mfma_f32_16x16x32_bf16 v[62:65], v[146:149], v[186:189], 0
	v_mfma_f32_16x16x32_bf16 v[58:61], v[160:163], v[186:189], 0
	v_mfma_f32_16x16x32_bf16 v[46:49], v[146:149], v[194:197], 0
	v_mfma_f32_16x16x32_bf16 v[42:45], v[160:163], v[194:197], 0
	v_mfma_f32_16x16x32_bf16 v[30:33], v[146:149], v[202:205], 0
	v_mfma_f32_16x16x32_bf16 v[26:29], v[160:163], v[202:205], 0
	v_mfma_f32_16x16x32_bf16 v[14:17], v[146:149], v[210:213], 0
	v_mfma_f32_16x16x32_bf16 v[10:13], v[160:163], v[210:213], 0
	v_mfma_f32_16x16x32_bf16 v[62:65], v[156:159], v[190:193], v[62:65]
	v_mfma_f32_16x16x32_bf16 v[58:61], v[164:167], v[190:193], v[58:61]
	v_mfma_f32_16x16x32_bf16 v[46:49], v[156:159], v[198:201], v[46:49]
	v_mfma_f32_16x16x32_bf16 v[42:45], v[164:167], v[198:201], v[42:45]
	v_mfma_f32_16x16x32_bf16 v[30:33], v[156:159], v[206:209], v[30:33]
	v_mfma_f32_16x16x32_bf16 v[26:29], v[164:167], v[206:209], v[26:29]
	v_mfma_f32_16x16x32_bf16 v[14:17], v[156:159], v[214:217], v[14:17]
	v_mfma_f32_16x16x32_bf16 v[10:13], v[164:167], v[214:217], v[10:13]
	s_setprio 0
	s_setprio 1
	v_mfma_f32_16x16x32_bf16 v[54:57], v[168:171], v[186:189], 0
	v_mfma_f32_16x16x32_bf16 v[50:53], v[176:179], v[186:189], 0
	v_mfma_f32_16x16x32_bf16 v[38:41], v[168:171], v[194:197], 0
	v_mfma_f32_16x16x32_bf16 v[34:37], v[176:179], v[194:197], 0
	v_mfma_f32_16x16x32_bf16 v[22:25], v[168:171], v[202:205], 0
	v_mfma_f32_16x16x32_bf16 v[18:21], v[176:179], v[202:205], 0
	v_mfma_f32_16x16x32_bf16 v[6:9], v[168:171], v[210:213], 0
	v_mfma_f32_16x16x32_bf16 v[2:5], v[176:179], v[210:213], 0
	v_mfma_f32_16x16x32_bf16 v[54:57], v[172:175], v[190:193], v[54:57]
	v_mfma_f32_16x16x32_bf16 v[50:53], v[182:185], v[190:193], v[50:53]
	v_mfma_f32_16x16x32_bf16 v[38:41], v[172:175], v[198:201], v[38:41]
	v_mfma_f32_16x16x32_bf16 v[34:37], v[182:185], v[198:201], v[34:37]
	v_mfma_f32_16x16x32_bf16 v[22:25], v[172:175], v[206:209], v[22:25]
	v_mfma_f32_16x16x32_bf16 v[18:21], v[182:185], v[206:209], v[18:21]
	v_mfma_f32_16x16x32_bf16 v[6:9], v[172:175], v[214:217], v[6:9]
	v_mfma_f32_16x16x32_bf16 v[2:5], v[182:185], v[214:217], v[2:5]
	s_setprio 0
	s_barrier
	s_add_i32 s33, 0, 0x18000
	s_add_i32 s51, 0, 0x1c000
	v_add_u32_e32 v164, s33, v150
	v_add_u32_e32 v182, s51, v150
	ds_read_b128 v[146:149], v164
	ds_read_b128 v[156:159], v164 offset:1024
	ds_read_b128 v[160:163], v164 offset:2048
	ds_read_b128 v[164:167], v164 offset:3072
	ds_read_b128 v[168:171], v182
	ds_read_b128 v[172:175], v182 offset:1024
	ds_read_b128 v[176:179], v182 offset:2048
	ds_read_b128 v[182:185], v182 offset:3072
	s_add_u32 s28, s28, 0x4000
	s_addc_u32 s29, s29, 0
	s_mov_b32 m0, s37
	v_lshl_add_u64 v[222:223], s[28:29], 0, v[130:131]
	ds_read_b128 v[186:189], v154 offset:32768
	ds_read_b128 v[190:193], v154 offset:33792
	ds_read_b128 v[194:197], v154 offset:34816
	ds_read_b128 v[198:201], v154 offset:35840
	ds_read_b128 v[202:205], v154 offset:36864
	ds_read_b128 v[206:209], v154 offset:37888
	ds_read_b128 v[210:213], v154 offset:38912
	ds_read_b128 v[214:217], v154 offset:39936
	global_load_lds_dwordx4 v[222:223], off
	v_lshl_add_u64 v[222:223], s[28:29], 0, v[134:135]
	s_mov_b32 m0, s38
	s_nop 0
	global_load_lds_dwordx4 v[222:223], off
	s_waitcnt vmcnt(8)
	s_waitcnt lgkmcnt(0)
	s_barrier
	s_setprio 1
	s_waitcnt lgkmcnt(0)
	v_mfma_f32_16x16x32_bf16 v[126:129], v[146:149], v[186:189], v[126:129]
	v_mfma_f32_16x16x32_bf16 v[122:125], v[160:163], v[186:189], v[122:125]
	v_mfma_f32_16x16x32_bf16 v[110:113], v[146:149], v[194:197], v[110:113]
	v_mfma_f32_16x16x32_bf16 v[106:109], v[160:163], v[194:197], v[106:109]
	v_mfma_f32_16x16x32_bf16 v[94:97], v[146:149], v[202:205], v[94:97]
	v_mfma_f32_16x16x32_bf16 v[90:93], v[160:163], v[202:205], v[90:93]
	v_mfma_f32_16x16x32_bf16 v[78:81], v[146:149], v[210:213], v[78:81]
	v_mfma_f32_16x16x32_bf16 v[74:77], v[160:163], v[210:213], v[74:77]
	v_mfma_f32_16x16x32_bf16 v[126:129], v[156:159], v[190:193], v[126:129]
	v_mfma_f32_16x16x32_bf16 v[122:125], v[164:167], v[190:193], v[122:125]
	v_mfma_f32_16x16x32_bf16 v[110:113], v[156:159], v[198:201], v[110:113]
	v_mfma_f32_16x16x32_bf16 v[106:109], v[164:167], v[198:201], v[106:109]
	v_mfma_f32_16x16x32_bf16 v[94:97], v[156:159], v[206:209], v[94:97]
	v_mfma_f32_16x16x32_bf16 v[90:93], v[164:167], v[206:209], v[90:93]
	v_mfma_f32_16x16x32_bf16 v[78:81], v[156:159], v[214:217], v[78:81]
	v_mfma_f32_16x16x32_bf16 v[74:77], v[164:167], v[214:217], v[74:77]
	s_setprio 0
	s_setprio 1
	v_mfma_f32_16x16x32_bf16 v[118:121], v[168:171], v[186:189], v[118:121]
	v_mfma_f32_16x16x32_bf16 v[114:117], v[176:179], v[186:189], v[114:117]
	v_mfma_f32_16x16x32_bf16 v[102:105], v[168:171], v[194:197], v[102:105]
	v_mfma_f32_16x16x32_bf16 v[98:101], v[176:179], v[194:197], v[98:101]
	v_mfma_f32_16x16x32_bf16 v[86:89], v[168:171], v[202:205], v[86:89]
	v_mfma_f32_16x16x32_bf16 v[82:85], v[176:179], v[202:205], v[82:85]
	v_mfma_f32_16x16x32_bf16 v[70:73], v[168:171], v[210:213], v[70:73]
	v_mfma_f32_16x16x32_bf16 v[66:69], v[176:179], v[210:213], v[66:69]
	v_mfma_f32_16x16x32_bf16 v[118:121], v[172:175], v[190:193], v[118:121]
	v_mfma_f32_16x16x32_bf16 v[114:117], v[182:185], v[190:193], v[114:117]
	v_mfma_f32_16x16x32_bf16 v[102:105], v[172:175], v[198:201], v[102:105]
	v_mfma_f32_16x16x32_bf16 v[98:101], v[182:185], v[198:201], v[98:101]
	v_mfma_f32_16x16x32_bf16 v[86:89], v[172:175], v[206:209], v[86:89]
	v_mfma_f32_16x16x32_bf16 v[82:85], v[182:185], v[206:209], v[82:85]
	v_mfma_f32_16x16x32_bf16 v[70:73], v[172:175], v[214:217], v[70:73]
	v_mfma_f32_16x16x32_bf16 v[66:69], v[182:185], v[214:217], v[66:69]
	s_setprio 0
	s_barrier
	s_add_i32 s28, s33, s34
	v_lshl_add_u64 v[218:219], v[218:219], 0, s[16:17]
	s_mov_b32 m0, s28
	ds_read_b128 v[186:189], v154 offset:49152
	ds_read_b128 v[190:193], v154 offset:50176
	ds_read_b128 v[194:197], v154 offset:51200
	ds_read_b128 v[198:201], v154 offset:52224
	ds_read_b128 v[202:205], v154 offset:53248
	ds_read_b128 v[206:209], v154 offset:54272
	ds_read_b128 v[210:213], v154 offset:55296
	ds_read_b128 v[214:217], v154 offset:56320
	global_load_lds_dwordx4 v[218:219], off
	s_add_i32 m0, s28, 0x2000
	s_add_u32 s26, s26, 0xb0080
	v_lshl_add_u64 v[218:219], v[220:221], 0, s[16:17]
	s_addc_u32 s27, s27, 0
	s_add_i32 s28, s51, s34
	global_load_lds_dwordx4 v[218:219], off
	v_lshl_add_u64 v[218:219], s[26:27], 0, v[132:133]
	s_mov_b32 m0, s28
	s_nop 0
	global_load_lds_dwordx4 v[218:219], off
	v_lshl_add_u64 v[218:219], s[26:27], 0, v[136:137]
	s_add_i32 m0, s28, 0x2000
	s_nop 0
	global_load_lds_dwordx4 v[218:219], off
	v_lshl_add_u64 v[218:219], s[24:25], 0, v[130:131]
	s_mov_b32 m0, s40
	s_nop 0
	global_load_lds_dwordx4 v[218:219], off
	v_lshl_add_u64 v[218:219], s[24:25], 0, v[134:135]
	s_mov_b32 m0, s41
	s_nop 0
	global_load_lds_dwordx4 v[218:219], off
	s_waitcnt vmcnt(8)
	s_waitcnt lgkmcnt(0)
	s_barrier
	s_setprio 1
	s_waitcnt lgkmcnt(0)
	v_mfma_f32_16x16x32_bf16 v[62:65], v[146:149], v[186:189], v[62:65]
	v_mfma_f32_16x16x32_bf16 v[58:61], v[160:163], v[186:189], v[58:61]
	v_mfma_f32_16x16x32_bf16 v[46:49], v[146:149], v[194:197], v[46:49]
	v_mfma_f32_16x16x32_bf16 v[42:45], v[160:163], v[194:197], v[42:45]
	v_mfma_f32_16x16x32_bf16 v[30:33], v[146:149], v[202:205], v[30:33]
	v_mfma_f32_16x16x32_bf16 v[26:29], v[160:163], v[202:205], v[26:29]
	v_mfma_f32_16x16x32_bf16 v[14:17], v[146:149], v[210:213], v[14:17]
	v_mfma_f32_16x16x32_bf16 v[10:13], v[160:163], v[210:213], v[10:13]
	v_mfma_f32_16x16x32_bf16 v[62:65], v[156:159], v[190:193], v[62:65]
	v_mfma_f32_16x16x32_bf16 v[58:61], v[164:167], v[190:193], v[58:61]
	v_mfma_f32_16x16x32_bf16 v[46:49], v[156:159], v[198:201], v[46:49]
	v_mfma_f32_16x16x32_bf16 v[42:45], v[164:167], v[198:201], v[42:45]
	v_mfma_f32_16x16x32_bf16 v[30:33], v[156:159], v[206:209], v[30:33]
	v_mfma_f32_16x16x32_bf16 v[26:29], v[164:167], v[206:209], v[26:29]
	v_mfma_f32_16x16x32_bf16 v[14:17], v[156:159], v[214:217], v[14:17]
	v_mfma_f32_16x16x32_bf16 v[10:13], v[164:167], v[214:217], v[10:13]
	s_setprio 0
	s_setprio 1
	v_mfma_f32_16x16x32_bf16 v[54:57], v[168:171], v[186:189], v[54:57]
	v_mfma_f32_16x16x32_bf16 v[50:53], v[176:179], v[186:189], v[50:53]
	v_mfma_f32_16x16x32_bf16 v[38:41], v[168:171], v[194:197], v[38:41]
	v_mfma_f32_16x16x32_bf16 v[34:37], v[176:179], v[194:197], v[34:37]
	v_mfma_f32_16x16x32_bf16 v[22:25], v[168:171], v[202:205], v[22:25]
	v_mfma_f32_16x16x32_bf16 v[18:21], v[176:179], v[202:205], v[18:21]
	v_mfma_f32_16x16x32_bf16 v[6:9], v[168:171], v[210:213], v[6:9]
	v_mfma_f32_16x16x32_bf16 v[2:5], v[176:179], v[210:213], v[2:5]
	v_mfma_f32_16x16x32_bf16 v[54:57], v[172:175], v[190:193], v[54:57]
	v_mfma_f32_16x16x32_bf16 v[50:53], v[182:185], v[190:193], v[50:53]
	v_mfma_f32_16x16x32_bf16 v[38:41], v[172:175], v[198:201], v[38:41]
	v_mfma_f32_16x16x32_bf16 v[34:37], v[182:185], v[198:201], v[34:37]
	v_mfma_f32_16x16x32_bf16 v[22:25], v[172:175], v[206:209], v[22:25]
	v_mfma_f32_16x16x32_bf16 v[18:21], v[182:185], v[206:209], v[18:21]
	v_mfma_f32_16x16x32_bf16 v[6:9], v[172:175], v[214:217], v[6:9]
	v_mfma_f32_16x16x32_bf16 v[2:5], v[182:185], v[214:217], v[2:5]
	s_setprio 0
	s_barrier
	s_add_i32 s57, s57, 2
	s_add_u32 s22, s22, 0x10000
	s_addc_u32 s23, s23, 0
	s_add_u32 s55, s55, 0x100
	s_addc_u32 s56, s56, 0

.LBB0_1833:
	s_ashr_i32 s19, s18, 31
	s_lshl_b64 s[20:21], s[18:19], 19
	s_add_u32 s20, s0, s20
	s_addc_u32 s21, s1, s21
	s_and_b64 s[22:23], s[4:5], exec
	s_cselect_b32 s19, s21, s31
	s_cselect_b32 s25, s20, s30
	s_ashr_i32 s17, s16, 31
	s_lshl_b64 s[22:23], s[16:17], 19
	v_readlane_b32 s34, v244, 43
	v_readlane_b32 s35, v244, 44
	s_add_u32 s22, s34, s22
	s_addc_u32 s23, s35, s23
	s_and_b64 s[34:35], s[4:5], exec
	s_cselect_b32 s17, s23, s29
	s_cselect_b32 s52, s22, s28
	s_add_u32 s53, s28, 0x100
	s_addc_u32 s54, s29, 0
	s_add_u32 s28, s30, 0x40080

	s_addc_u32 s29, s31, 0
	s_mov_b32 s55, -2
	s_waitcnt lgkmcnt(0)


	ds_read_b128 v[146:149], v152
	ds_read_b128 v[156:159], v152 offset:1024
	ds_read_b128 v[160:163], v152 offset:2048
	ds_read_b128 v[164:167], v152 offset:3072
	ds_read_b128 v[168:171], v153
	ds_read_b128 v[172:175], v153 offset:1024
	ds_read_b128 v[176:179], v153 offset:2048
	ds_read_b128 v[182:185], v153 offset:3072
	s_add_u32 s30, s28, 0xfffc0080
	s_addc_u32 s31, s29, -1
	s_cmp_eq_u32 s55, 12
	s_cselect_b32 s35, s19, s31
	s_cselect_b32 s34, s25, s30
	s_cselect_b32 s31, s17, s54
	s_cselect_b32 s30, s52, s53
	v_lshl_add_u64 v[218:219], s[28:29], 0, v[138:139]
	s_add_i32 m0, s27, 0xc000
	ds_read_b128 v[186:189], v154
	ds_read_b128 v[190:193], v154 offset:1024
	ds_read_b128 v[194:197], v154 offset:2048
	ds_read_b128 v[198:201], v154 offset:3072
	ds_read_b128 v[202:205], v154 offset:4096
	ds_read_b128 v[206:209], v154 offset:5120
	ds_read_b128 v[210:213], v154 offset:6144
	ds_read_b128 v[214:217], v154 offset:7168
	global_load_lds_dwordx4 v[218:219], off
	v_lshl_add_u64 v[218:219], s[28:29], 0, v[140:141]
	s_add_i32 m0, s27, 0xe000
	s_nop 0
	global_load_lds_dwordx4 v[218:219], off
	s_waitcnt vmcnt(8)
	s_waitcnt lgkmcnt(0)
	s_barrier
	s_setprio 1
	s_waitcnt lgkmcnt(0)
	v_mfma_f32_16x16x32_bf16 v[126:129], v[146:149], v[186:189], 0
	v_mfma_f32_16x16x32_bf16 v[122:125], v[160:163], v[186:189], 0
	v_mfma_f32_16x16x32_bf16 v[110:113], v[146:149], v[194:197], 0
	v_mfma_f32_16x16x32_bf16 v[106:109], v[160:163], v[194:197], 0
	v_mfma_f32_16x16x32_bf16 v[94:97], v[146:149], v[202:205], 0
	v_mfma_f32_16x16x32_bf16 v[90:93], v[160:163], v[202:205], 0
	v_mfma_f32_16x16x32_bf16 v[78:81], v[146:149], v[210:213], 0
	v_mfma_f32_16x16x32_bf16 v[74:77], v[160:163], v[210:213], 0
	v_mfma_f32_16x16x32_bf16 v[126:129], v[156:159], v[190:193], v[126:129]
	v_mfma_f32_16x16x32_bf16 v[122:125], v[164:167], v[190:193], v[122:125]
	v_mfma_f32_16x16x32_bf16 v[110:113], v[156:159], v[198:201], v[110:113]
	v_mfma_f32_16x16x32_bf16 v[106:109], v[164:167], v[198:201], v[106:109]
	v_mfma_f32_16x16x32_bf16 v[94:97], v[156:159], v[206:209], v[94:97]
	v_mfma_f32_16x16x32_bf16 v[90:93], v[164:167], v[206:209], v[90:93]
	v_mfma_f32_16x16x32_bf16 v[78:81], v[156:159], v[214:217], v[78:81]
	v_mfma_f32_16x16x32_bf16 v[74:77], v[164:167], v[214:217], v[74:77]
	s_setprio 0
	s_setprio 1
	v_mfma_f32_16x16x32_bf16 v[118:121], v[168:171], v[186:189], 0
	v_mfma_f32_16x16x32_bf16 v[114:117], v[176:179], v[186:189], 0
	v_mfma_f32_16x16x32_bf16 v[102:105], v[168:171], v[194:197], 0
	v_mfma_f32_16x16x32_bf16 v[98:101], v[176:179], v[194:197], 0
	v_mfma_f32_16x16x32_bf16 v[86:89], v[168:171], v[202:205], 0
	v_mfma_f32_16x16x32_bf16 v[82:85], v[176:179], v[202:205], 0
	v_mfma_f32_16x16x32_bf16 v[70:73], v[168:171], v[210:213], 0
	v_mfma_f32_16x16x32_bf16 v[66:69], v[176:179], v[210:213], 0
	v_mfma_f32_16x16x32_bf16 v[118:121], v[172:175], v[190:193], v[118:121]
	v_mfma_f32_16x16x32_bf16 v[114:117], v[182:185], v[190:193], v[114:117]
	v_mfma_f32_16x16x32_bf16 v[102:105], v[172:175], v[198:201], v[102:105]
	v_mfma_f32_16x16x32_bf16 v[98:101], v[182:185], v[198:201], v[98:101]
	v_mfma_f32_16x16x32_bf16 v[86:89], v[172:175], v[206:209], v[86:89]
	v_mfma_f32_16x16x32_bf16 v[82:85], v[182:185], v[206:209], v[82:85]
	v_mfma_f32_16x16x32_bf16 v[70:73], v[172:175], v[214:217], v[70:73]
	v_mfma_f32_16x16x32_bf16 v[66:69], v[182:185], v[214:217], v[66:69]
	s_setprio 0
	s_barrier
	s_add_i32 s33, s48, s36
	v_lshl_add_u64 v[218:219], s[30:31], 0, v[132:133]
	s_mov_b32 m0, s33
	ds_read_b128 v[186:189], v154 offset:16384
	ds_read_b128 v[190:193], v154 offset:17408
	ds_read_b128 v[194:197], v154 offset:18432
	ds_read_b128 v[198:201], v154 offset:19456
	ds_read_b128 v[202:205], v154 offset:20480
	ds_read_b128 v[206:209], v154 offset:21504
	ds_read_b128 v[210:213], v154 offset:22528
	ds_read_b128 v[214:217], v154 offset:23552
	global_load_lds_dwordx4 v[218:219], off
	s_add_i32 m0, s33, 0x2000
	s_add_u32 s56, s30, 0x40000
	v_lshl_add_u64 v[220:221], s[30:31], 0, v[136:137]
	s_addc_u32 s57, s31, 0
	s_add_i32 s33, s49, s36
	global_load_lds_dwordx4 v[220:221], off
	v_lshl_add_u64 v[222:223], s[56:57], 0, v[132:133]
	s_mov_b32 m0, s33
	v_lshl_add_u64 v[224:225], s[34:35], 0, v[134:135]
	global_load_lds_dwordx4 v[222:223], off
	v_lshl_add_u64 v[222:223], s[56:57], 0, v[136:137]
	s_add_i32 m0, s33, 0x2000
	s_nop 0
	global_load_lds_dwordx4 v[222:223], off
	v_lshl_add_u64 v[222:223], s[34:35], 0, v[130:131]
	s_mov_b32 m0, s27
	s_nop 0
	global_load_lds_dwordx4 v[222:223], off
	s_mov_b32 m0, s37
	s_nop 0
	global_load_lds_dwordx4 v[224:225], off
	s_waitcnt vmcnt(8)
	s_waitcnt lgkmcnt(0)
	s_barrier
	s_setprio 1
	s_waitcnt lgkmcnt(0)
	v_mfma_f32_16x16x32_bf16 v[62:65], v[146:149], v[186:189], 0
	v_mfma_f32_16x16x32_bf16 v[58:61], v[160:163], v[186:189], 0
	v_mfma_f32_16x16x32_bf16 v[46:49], v[146:149], v[194:197], 0
	v_mfma_f32_16x16x32_bf16 v[42:45], v[160:163], v[194:197], 0
	v_mfma_f32_16x16x32_bf16 v[30:33], v[146:149], v[202:205], 0
	v_mfma_f32_16x16x32_bf16 v[26:29], v[160:163], v[202:205], 0
	v_mfma_f32_16x16x32_bf16 v[14:17], v[146:149], v[210:213], 0
	v_mfma_f32_16x16x32_bf16 v[10:13], v[160:163], v[210:213], 0
	v_mfma_f32_16x16x32_bf16 v[62:65], v[156:159], v[190:193], v[62:65]
	v_mfma_f32_16x16x32_bf16 v[58:61], v[164:167], v[190:193], v[58:61]
	v_mfma_f32_16x16x32_bf16 v[46:49], v[156:159], v[198:201], v[46:49]
	v_mfma_f32_16x16x32_bf16 v[42:45], v[164:167], v[198:201], v[42:45]
	v_mfma_f32_16x16x32_bf16 v[30:33], v[156:159], v[206:209], v[30:33]
	v_mfma_f32_16x16x32_bf16 v[26:29], v[164:167], v[206:209], v[26:29]
	v_mfma_f32_16x16x32_bf16 v[14:17], v[156:159], v[214:217], v[14:17]
	v_mfma_f32_16x16x32_bf16 v[10:13], v[164:167], v[214:217], v[10:13]
	s_setprio 0
	s_setprio 1
	v_mfma_f32_16x16x32_bf16 v[54:57], v[168:171], v[186:189], 0
	v_mfma_f32_16x16x32_bf16 v[50:53], v[176:179], v[186:189], 0
	v_mfma_f32_16x16x32_bf16 v[38:41], v[168:171], v[194:197], 0
	v_mfma_f32_16x16x32_bf16 v[34:37], v[176:179], v[194:197], 0
	v_mfma_f32_16x16x32_bf16 v[22:25], v[168:171], v[202:205], 0
	v_mfma_f32_16x16x32_bf16 v[18:21], v[176:179], v[202:205], 0
	v_mfma_f32_16x16x32_bf16 v[6:9], v[168:171], v[210:213], 0
	v_mfma_f32_16x16x32_bf16 v[2:5], v[176:179], v[210:213], 0
	v_mfma_f32_16x16x32_bf16 v[54:57], v[172:175], v[190:193], v[54:57]
	v_mfma_f32_16x16x32_bf16 v[50:53], v[182:185], v[190:193], v[50:53]
	v_mfma_f32_16x16x32_bf16 v[38:41], v[172:175], v[198:201], v[38:41]
	v_mfma_f32_16x16x32_bf16 v[34:37], v[182:185], v[198:201], v[34:37]
	v_mfma_f32_16x16x32_bf16 v[22:25], v[172:175], v[206:209], v[22:25]
	v_mfma_f32_16x16x32_bf16 v[18:21], v[182:185], v[206:209], v[18:21]
	v_mfma_f32_16x16x32_bf16 v[6:9], v[172:175], v[214:217], v[6:9]
	v_mfma_f32_16x16x32_bf16 v[2:5], v[182:185], v[214:217], v[2:5]
	s_setprio 0
	s_barrier
	s_add_i32 s33, 0, 0x18000
	s_add_i32 s51, 0, 0x1c000
	v_add_u32_e32 v164, s33, v150
	v_add_u32_e32 v182, s51, v150
	ds_read_b128 v[146:149], v164
	ds_read_b128 v[156:159], v164 offset:1024
	ds_read_b128 v[160:163], v164 offset:2048
	ds_read_b128 v[164:167], v164 offset:3072
	ds_read_b128 v[168:171], v182
	ds_read_b128 v[172:175], v182 offset:1024
	ds_read_b128 v[176:179], v182 offset:2048
	ds_read_b128 v[182:185], v182 offset:3072
	s_add_u32 s34, s34, 0x40000
	s_addc_u32 s35, s35, 0
	s_mov_b32 m0, s38
	v_lshl_add_u64 v[226:227], s[34:35], 0, v[130:131]
	ds_read_b128 v[186:189], v154 offset:32768
	ds_read_b128 v[190:193], v154 offset:33792
	ds_read_b128 v[194:197], v154 offset:34816
	ds_read_b128 v[198:201], v154 offset:35840
	ds_read_b128 v[202:205], v154 offset:36864
	ds_read_b128 v[206:209], v154 offset:37888
	ds_read_b128 v[210:213], v154 offset:38912
	ds_read_b128 v[214:217], v154 offset:39936
	global_load_lds_dwordx4 v[226:227], off
	v_lshl_add_u64 v[226:227], s[34:35], 0, v[134:135]
	s_mov_b32 m0, s39
	s_nop 0
	global_load_lds_dwordx4 v[226:227], off
	s_waitcnt vmcnt(8)
	s_waitcnt lgkmcnt(0)
	s_barrier
	s_setprio 1
	s_waitcnt lgkmcnt(0)
	v_mfma_f32_16x16x32_bf16 v[126:129], v[146:149], v[186:189], v[126:129]
	v_mfma_f32_16x16x32_bf16 v[122:125], v[160:163], v[186:189], v[122:125]
	v_mfma_f32_16x16x32_bf16 v[110:113], v[146:149], v[194:197], v[110:113]
	v_mfma_f32_16x16x32_bf16 v[106:109], v[160:163], v[194:197], v[106:109]
	v_mfma_f32_16x16x32_bf16 v[94:97], v[146:149], v[202:205], v[94:97]
	v_mfma_f32_16x16x32_bf16 v[90:93], v[160:163], v[202:205], v[90:93]
	v_mfma_f32_16x16x32_bf16 v[78:81], v[146:149], v[210:213], v[78:81]
	v_mfma_f32_16x16x32_bf16 v[74:77], v[160:163], v[210:213], v[74:77]
	v_mfma_f32_16x16x32_bf16 v[126:129], v[156:159], v[190:193], v[126:129]
	v_mfma_f32_16x16x32_bf16 v[122:125], v[164:167], v[190:193], v[122:125]
	v_mfma_f32_16x16x32_bf16 v[110:113], v[156:159], v[198:201], v[110:113]
	v_mfma_f32_16x16x32_bf16 v[106:109], v[164:167], v[198:201], v[106:109]
	v_mfma_f32_16x16x32_bf16 v[94:97], v[156:159], v[206:209], v[94:97]
	v_mfma_f32_16x16x32_bf16 v[90:93], v[164:167], v[206:209], v[90:93]
	v_mfma_f32_16x16x32_bf16 v[78:81], v[156:159], v[214:217], v[78:81]
	v_mfma_f32_16x16x32_bf16 v[74:77], v[164:167], v[214:217], v[74:77]
	s_setprio 0
	s_setprio 1
	v_mfma_f32_16x16x32_bf16 v[118:121], v[168:171], v[186:189], v[118:121]
	v_mfma_f32_16x16x32_bf16 v[114:117], v[176:179], v[186:189], v[114:117]
	v_mfma_f32_16x16x32_bf16 v[102:105], v[168:171], v[194:197], v[102:105]
	v_mfma_f32_16x16x32_bf16 v[98:101], v[176:179], v[194:197], v[98:101]
	v_mfma_f32_16x16x32_bf16 v[86:89], v[168:171], v[202:205], v[86:89]
	v_mfma_f32_16x16x32_bf16 v[82:85], v[176:179], v[202:205], v[82:85]
	v_mfma_f32_16x16x32_bf16 v[70:73], v[168:171], v[210:213], v[70:73]
	v_mfma_f32_16x16x32_bf16 v[66:69], v[176:179], v[210:213], v[66:69]
	v_mfma_f32_16x16x32_bf16 v[118:121], v[172:175], v[190:193], v[118:121]
	v_mfma_f32_16x16x32_bf16 v[114:117], v[182:185], v[190:193], v[114:117]
	v_mfma_f32_16x16x32_bf16 v[102:105], v[172:175], v[198:201], v[102:105]
	v_mfma_f32_16x16x32_bf16 v[98:101], v[182:185], v[198:201], v[98:101]
	v_mfma_f32_16x16x32_bf16 v[86:89], v[172:175], v[206:209], v[86:89]
	v_mfma_f32_16x16x32_bf16 v[82:85], v[182:185], v[206:209], v[82:85]
	v_mfma_f32_16x16x32_bf16 v[70:73], v[172:175], v[214:217], v[70:73]
	v_mfma_f32_16x16x32_bf16 v[66:69], v[182:185], v[214:217], v[66:69]
	s_setprio 0
	s_barrier
	s_add_i32 s33, s33, s36
	v_lshl_add_u64 v[218:219], v[218:219], 0, s[12:13]
	s_mov_b32 m0, s33
	ds_read_b128 v[186:189], v154 offset:49152
	ds_read_b128 v[190:193], v154 offset:50176
	ds_read_b128 v[194:197], v154 offset:51200
	ds_read_b128 v[198:201], v154 offset:52224
	ds_read_b128 v[202:205], v154 offset:53248
	ds_read_b128 v[206:209], v154 offset:54272
	ds_read_b128 v[210:213], v154 offset:55296
	ds_read_b128 v[214:217], v154 offset:56320
	global_load_lds_dwordx4 v[218:219], off
	s_add_i32 m0, s33, 0x2000
	s_add_u32 s30, s30, 0x40080
	v_lshl_add_u64 v[218:219], v[220:221], 0, s[12:13]
	s_addc_u32 s31, s31, 0
	s_add_i32 s33, s51, s36
	global_load_lds_dwordx4 v[218:219], off
	v_lshl_add_u64 v[218:219], s[30:31], 0, v[132:133]
	s_mov_b32 m0, s33
	s_nop 0
	global_load_lds_dwordx4 v[218:219], off
	v_lshl_add_u64 v[218:219], s[30:31], 0, v[136:137]
	s_add_i32 m0, s33, 0x2000
	s_nop 0
	global_load_lds_dwordx4 v[218:219], off
	v_lshl_add_u64 v[218:219], v[222:223], 0, s[12:13]
	s_mov_b32 m0, s41
	s_nop 0
	global_load_lds_dwordx4 v[218:219], off
	v_lshl_add_u64 v[218:219], v[224:225], 0, s[12:13]
	s_mov_b32 m0, s42
	s_nop 0
	global_load_lds_dwordx4 v[218:219], off
	s_waitcnt vmcnt(8)
	s_waitcnt lgkmcnt(0)
	s_barrier
	s_setprio 1
	s_waitcnt lgkmcnt(0)
	v_mfma_f32_16x16x32_bf16 v[62:65], v[146:149], v[186:189], v[62:65]
	v_mfma_f32_16x16x32_bf16 v[58:61], v[160:163], v[186:189], v[58:61]
	v_mfma_f32_16x16x32_bf16 v[46:49], v[146:149], v[194:197], v[46:49]
	v_mfma_f32_16x16x32_bf16 v[42:45], v[160:163], v[194:197], v[42:45]
	v_mfma_f32_16x16x32_bf16 v[30:33], v[146:149], v[202:205], v[30:33]
	v_mfma_f32_16x16x32_bf16 v[26:29], v[160:163], v[202:205], v[26:29]
	v_mfma_f32_16x16x32_bf16 v[14:17], v[146:149], v[210:213], v[14:17]
	v_mfma_f32_16x16x32_bf16 v[10:13], v[160:163], v[210:213], v[10:13]
	v_mfma_f32_16x16x32_bf16 v[62:65], v[156:159], v[190:193], v[62:65]
	v_mfma_f32_16x16x32_bf16 v[58:61], v[164:167], v[190:193], v[58:61]
	v_mfma_f32_16x16x32_bf16 v[46:49], v[156:159], v[198:201], v[46:49]
	v_mfma_f32_16x16x32_bf16 v[42:45], v[164:167], v[198:201], v[42:45]
	v_mfma_f32_16x16x32_bf16 v[30:33], v[156:159], v[206:209], v[30:33]
	v_mfma_f32_16x16x32_bf16 v[26:29], v[164:167], v[206:209], v[26:29]
	v_mfma_f32_16x16x32_bf16 v[14:17], v[156:159], v[214:217], v[14:17]
	v_mfma_f32_16x16x32_bf16 v[10:13], v[164:167], v[214:217], v[10:13]
	s_setprio 0
	s_setprio 1
	v_mfma_f32_16x16x32_bf16 v[54:57], v[168:171], v[186:189], v[54:57]
	v_mfma_f32_16x16x32_bf16 v[50:53], v[176:179], v[186:189], v[50:53]
	v_mfma_f32_16x16x32_bf16 v[38:41], v[168:171], v[194:197], v[38:41]
	v_mfma_f32_16x16x32_bf16 v[34:37], v[176:179], v[194:197], v[34:37]
	v_mfma_f32_16x16x32_bf16 v[22:25], v[168:171], v[202:205], v[22:25]
	v_mfma_f32_16x16x32_bf16 v[18:21], v[176:179], v[202:205], v[18:21]
	v_mfma_f32_16x16x32_bf16 v[6:9], v[168:171], v[210:213], v[6:9]
	v_mfma_f32_16x16x32_bf16 v[2:5], v[176:179], v[210:213], v[2:5]
	v_mfma_f32_16x16x32_bf16 v[54:57], v[172:175], v[190:193], v[54:57]
	v_mfma_f32_16x16x32_bf16 v[50:53], v[182:185], v[190:193], v[50:53]
	v_mfma_f32_16x16x32_bf16 v[38:41], v[172:175], v[198:201], v[38:41]
	v_mfma_f32_16x16x32_bf16 v[34:37], v[182:185], v[198:201], v[34:37]
	v_mfma_f32_16x16x32_bf16 v[22:25], v[172:175], v[206:209], v[22:25]
	v_mfma_f32_16x16x32_bf16 v[18:21], v[182:185], v[206:209], v[18:21]
	v_mfma_f32_16x16x32_bf16 v[6:9], v[172:175], v[214:217], v[6:9]
	v_mfma_f32_16x16x32_bf16 v[2:5], v[182:185], v[214:217], v[2:5]
	s_setprio 0
	s_barrier
	s_add_i32 s55, s55, 2
	s_add_u32 s53, s53, 0x100
	s_addc_u32 s54, s54, 0
	s_add_u32 s28, s28, 0x100
	s_addc_u32 s29, s29, 0

.LBB0_1936:
	s_ashr_i32 s13, s12, 31
	s_lshl_b64 s[14:15], s[12:13], 19
	s_add_u32 s14, s92, s14
	s_addc_u32 s15, s93, s15
	s_and_b64 s[16:17], s[2:3], exec
	s_cselect_b32 s13, s15, s23
	s_cselect_b32 s53, s14, s22
	s_ashr_i32 s11, s10, 31
	s_lshl_b64 s[16:17], s[10:11], 19
	s_add_u32 s16, s29, s16
	s_addc_u32 s17, s30, s17
	s_and_b64 s[26:27], s[2:3], exec
	s_cselect_b32 s11, s17, s25
	s_cselect_b32 s54, s16, s24
	s_add_u32 s22, s22, 0x40080
	s_addc_u32 s23, s23, 0
	s_add_u32 s55, s24, 0x100

	s_addc_u32 s56, s25, 0
	s_mov_b32 s57, -2


	ds_read_b128 v[158:161], v154
	ds_read_b128 v[162:165], v154 offset:1024
	ds_read_b128 v[166:169], v154 offset:2048
	ds_read_b128 v[170:173], v154 offset:3072
	ds_read_b128 v[174:177], v155
	ds_read_b128 v[182:185], v155 offset:1024
	ds_read_b128 v[186:189], v155 offset:2048
	ds_read_b128 v[190:193], v155 offset:3072
	s_add_u32 s24, s22, 0xfffc0080
	s_addc_u32 s25, s23, -1
	s_cmp_eq_u32 s57, 12
	s_cselect_b32 s27, s13, s25
	s_cselect_b32 s26, s53, s24
	s_cselect_b32 s25, s11, s56
	s_cselect_b32 s24, s54, s55
	v_lshl_add_u64 v[178:179], s[22:23], 0, v[144:145]
	s_add_i32 m0, s21, 0xc000
	ds_read_b128 v[194:197], v156
	ds_read_b128 v[198:201], v156 offset:1024
	ds_read_b128 v[202:205], v156 offset:2048
	ds_read_b128 v[206:209], v156 offset:3072
	ds_read_b128 v[210:213], v156 offset:4096
	ds_read_b128 v[214:217], v156 offset:5120
	ds_read_b128 v[218:221], v156 offset:6144
	ds_read_b128 v[222:225], v156 offset:7168
	global_load_lds_dwordx4 v[178:179], off
	v_lshl_add_u64 v[178:179], s[22:23], 0, v[146:147]
	s_add_i32 m0, s21, 0xe000
	s_nop 0
	global_load_lds_dwordx4 v[178:179], off
	s_waitcnt vmcnt(8)
	s_waitcnt lgkmcnt(0)
	s_barrier
	s_setprio 1
	s_waitcnt lgkmcnt(0)
	v_mfma_f32_16x16x32_bf16 v[126:129], v[158:161], v[194:197], 0
	v_mfma_f32_16x16x32_bf16 v[118:121], v[166:169], v[194:197], 0
	v_mfma_f32_16x16x32_bf16 v[110:113], v[158:161], v[202:205], 0
	v_mfma_f32_16x16x32_bf16 v[102:105], v[166:169], v[202:205], 0
	v_mfma_f32_16x16x32_bf16 v[94:97], v[158:161], v[210:213], 0
	v_mfma_f32_16x16x32_bf16 v[86:89], v[166:169], v[210:213], 0
	v_mfma_f32_16x16x32_bf16 v[78:81], v[158:161], v[218:221], 0
	v_mfma_f32_16x16x32_bf16 v[70:73], v[166:169], v[218:221], 0
	v_mfma_f32_16x16x32_bf16 v[126:129], v[162:165], v[198:201], v[126:129]
	v_mfma_f32_16x16x32_bf16 v[118:121], v[170:173], v[198:201], v[118:121]
	v_mfma_f32_16x16x32_bf16 v[110:113], v[162:165], v[206:209], v[110:113]
	v_mfma_f32_16x16x32_bf16 v[102:105], v[170:173], v[206:209], v[102:105]
	v_mfma_f32_16x16x32_bf16 v[94:97], v[162:165], v[214:217], v[94:97]
	v_mfma_f32_16x16x32_bf16 v[86:89], v[170:173], v[214:217], v[86:89]
	v_mfma_f32_16x16x32_bf16 v[78:81], v[162:165], v[222:225], v[78:81]
	v_mfma_f32_16x16x32_bf16 v[70:73], v[170:173], v[222:225], v[70:73]
	s_setprio 0
	s_setprio 1
	v_mfma_f32_16x16x32_bf16 v[122:125], v[174:177], v[194:197], 0
	v_mfma_f32_16x16x32_bf16 v[114:117], v[186:189], v[194:197], 0
	v_mfma_f32_16x16x32_bf16 v[106:109], v[174:177], v[202:205], 0
	v_mfma_f32_16x16x32_bf16 v[98:101], v[186:189], v[202:205], 0
	v_mfma_f32_16x16x32_bf16 v[90:93], v[174:177], v[210:213], 0
	v_mfma_f32_16x16x32_bf16 v[82:85], v[186:189], v[210:213], 0
	v_mfma_f32_16x16x32_bf16 v[74:77], v[174:177], v[218:221], 0
	v_mfma_f32_16x16x32_bf16 v[66:69], v[186:189], v[218:221], 0
	v_mfma_f32_16x16x32_bf16 v[122:125], v[182:185], v[198:201], v[122:125]
	v_mfma_f32_16x16x32_bf16 v[114:117], v[190:193], v[198:201], v[114:117]
	v_mfma_f32_16x16x32_bf16 v[106:109], v[182:185], v[206:209], v[106:109]
	v_mfma_f32_16x16x32_bf16 v[98:101], v[190:193], v[206:209], v[98:101]
	v_mfma_f32_16x16x32_bf16 v[90:93], v[182:185], v[214:217], v[90:93]
	v_mfma_f32_16x16x32_bf16 v[82:85], v[190:193], v[214:217], v[82:85]
	v_mfma_f32_16x16x32_bf16 v[74:77], v[182:185], v[222:225], v[74:77]
	v_mfma_f32_16x16x32_bf16 v[66:69], v[190:193], v[222:225], v[66:69]
	s_setprio 0
	s_barrier
	s_add_i32 s33, s46, s19
	v_lshl_add_u64 v[178:179], s[24:25], 0, v[132:133]
	s_mov_b32 m0, s33
	ds_read_b128 v[194:197], v156 offset:16384
	ds_read_b128 v[198:201], v156 offset:17408
	ds_read_b128 v[202:205], v156 offset:18432
	ds_read_b128 v[206:209], v156 offset:19456
	ds_read_b128 v[210:213], v156 offset:20480
	ds_read_b128 v[214:217], v156 offset:21504
	ds_read_b128 v[218:221], v156 offset:22528
	ds_read_b128 v[222:225], v156 offset:23552
	global_load_lds_dwordx4 v[178:179], off
	s_add_i32 m0, s33, 0x2000
	s_add_u32 s58, s24, 0x40000
	v_lshl_add_u64 v[226:227], s[24:25], 0, v[136:137]
	s_addc_u32 s59, s25, 0
	s_add_i32 s33, s47, s19
	global_load_lds_dwordx4 v[226:227], off
	v_lshl_add_u64 v[228:229], s[58:59], 0, v[132:133]
	s_mov_b32 m0, s33
	v_lshl_add_u64 v[230:231], s[26:27], 0, v[134:135]
	global_load_lds_dwordx4 v[228:229], off
	v_lshl_add_u64 v[228:229], s[58:59], 0, v[136:137]
	s_add_i32 m0, s33, 0x2000
	s_nop 0
	global_load_lds_dwordx4 v[228:229], off
	v_lshl_add_u64 v[228:229], s[26:27], 0, v[130:131]
	s_mov_b32 m0, s21
	s_nop 0
	global_load_lds_dwordx4 v[228:229], off
	s_mov_b32 m0, s31
	s_nop 0
	global_load_lds_dwordx4 v[230:231], off
	s_waitcnt vmcnt(8)
	s_waitcnt lgkmcnt(0)
	s_barrier
	s_setprio 1
	s_waitcnt lgkmcnt(0)
	v_mfma_f32_16x16x32_bf16 v[62:65], v[158:161], v[194:197], 0
	v_mfma_f32_16x16x32_bf16 v[54:57], v[166:169], v[194:197], 0
	v_mfma_f32_16x16x32_bf16 v[46:49], v[158:161], v[202:205], 0
	v_mfma_f32_16x16x32_bf16 v[38:41], v[166:169], v[202:205], 0
	v_mfma_f32_16x16x32_bf16 v[30:33], v[158:161], v[210:213], 0
	v_mfma_f32_16x16x32_bf16 v[22:25], v[166:169], v[210:213], 0
	v_mfma_f32_16x16x32_bf16 v[14:17], v[158:161], v[218:221], 0
	v_mfma_f32_16x16x32_bf16 v[6:9], v[166:169], v[218:221], 0
	v_mfma_f32_16x16x32_bf16 v[62:65], v[162:165], v[198:201], v[62:65]
	v_mfma_f32_16x16x32_bf16 v[54:57], v[170:173], v[198:201], v[54:57]
	v_mfma_f32_16x16x32_bf16 v[46:49], v[162:165], v[206:209], v[46:49]
	v_mfma_f32_16x16x32_bf16 v[38:41], v[170:173], v[206:209], v[38:41]
	v_mfma_f32_16x16x32_bf16 v[30:33], v[162:165], v[214:217], v[30:33]
	v_mfma_f32_16x16x32_bf16 v[22:25], v[170:173], v[214:217], v[22:25]
	v_mfma_f32_16x16x32_bf16 v[14:17], v[162:165], v[222:225], v[14:17]
	v_mfma_f32_16x16x32_bf16 v[6:9], v[170:173], v[222:225], v[6:9]
	s_setprio 0
	s_setprio 1
	v_mfma_f32_16x16x32_bf16 v[58:61], v[174:177], v[194:197], 0
	v_mfma_f32_16x16x32_bf16 v[50:53], v[186:189], v[194:197], 0
	v_mfma_f32_16x16x32_bf16 v[42:45], v[174:177], v[202:205], 0
	v_mfma_f32_16x16x32_bf16 v[34:37], v[186:189], v[202:205], 0
	v_mfma_f32_16x16x32_bf16 v[26:29], v[174:177], v[210:213], 0
	v_mfma_f32_16x16x32_bf16 v[18:21], v[186:189], v[210:213], 0
	v_mfma_f32_16x16x32_bf16 v[10:13], v[174:177], v[218:221], 0
	v_mfma_f32_16x16x32_bf16 v[2:5], v[186:189], v[218:221], 0
	v_mfma_f32_16x16x32_bf16 v[58:61], v[182:185], v[198:201], v[58:61]
	v_mfma_f32_16x16x32_bf16 v[50:53], v[190:193], v[198:201], v[50:53]
	v_mfma_f32_16x16x32_bf16 v[42:45], v[182:185], v[206:209], v[42:45]
	v_mfma_f32_16x16x32_bf16 v[34:37], v[190:193], v[206:209], v[34:37]
	v_mfma_f32_16x16x32_bf16 v[26:29], v[182:185], v[214:217], v[26:29]
	v_mfma_f32_16x16x32_bf16 v[18:21], v[190:193], v[214:217], v[18:21]
	v_mfma_f32_16x16x32_bf16 v[10:13], v[182:185], v[222:225], v[10:13]
	v_mfma_f32_16x16x32_bf16 v[2:5], v[190:193], v[222:225], v[2:5]
	s_setprio 0
	s_barrier
	s_add_i32 s33, 0, 0x18000
	s_add_i32 s51, 0, 0x1c000
	v_add_u32_e32 v170, s33, v152
	v_add_u32_e32 v181, s51, v152
	ds_read_b128 v[158:161], v170
	ds_read_b128 v[162:165], v170 offset:1024
	ds_read_b128 v[166:169], v170 offset:2048
	ds_read_b128 v[170:173], v170 offset:3072
	ds_read_b128 v[174:177], v181
	ds_read_b128 v[182:185], v181 offset:1024
	ds_read_b128 v[186:189], v181 offset:2048
	ds_read_b128 v[190:193], v181 offset:3072
	s_add_u32 s26, s26, 0x40000
	s_addc_u32 s27, s27, 0
	s_mov_b32 m0, s34
	v_lshl_add_u64 v[232:233], s[26:27], 0, v[130:131]
	ds_read_b128 v[194:197], v156 offset:32768
	ds_read_b128 v[198:201], v156 offset:33792
	ds_read_b128 v[202:205], v156 offset:34816
	ds_read_b128 v[206:209], v156 offset:35840
	ds_read_b128 v[210:213], v156 offset:36864
	ds_read_b128 v[214:217], v156 offset:37888
	ds_read_b128 v[218:221], v156 offset:38912
	ds_read_b128 v[222:225], v156 offset:39936
	global_load_lds_dwordx4 v[232:233], off
	v_lshl_add_u64 v[232:233], s[26:27], 0, v[134:135]
	s_mov_b32 m0, s35
	s_nop 0
	global_load_lds_dwordx4 v[232:233], off
	s_waitcnt vmcnt(8)
	s_waitcnt lgkmcnt(0)
	s_barrier
	s_setprio 1
	s_waitcnt lgkmcnt(0)
	v_mfma_f32_16x16x32_bf16 v[126:129], v[158:161], v[194:197], v[126:129]
	v_mfma_f32_16x16x32_bf16 v[118:121], v[166:169], v[194:197], v[118:121]
	v_mfma_f32_16x16x32_bf16 v[110:113], v[158:161], v[202:205], v[110:113]
	v_mfma_f32_16x16x32_bf16 v[102:105], v[166:169], v[202:205], v[102:105]
	v_mfma_f32_16x16x32_bf16 v[94:97], v[158:161], v[210:213], v[94:97]
	v_mfma_f32_16x16x32_bf16 v[86:89], v[166:169], v[210:213], v[86:89]
	v_mfma_f32_16x16x32_bf16 v[78:81], v[158:161], v[218:221], v[78:81]
	v_mfma_f32_16x16x32_bf16 v[70:73], v[166:169], v[218:221], v[70:73]
	v_mfma_f32_16x16x32_bf16 v[126:129], v[162:165], v[198:201], v[126:129]
	v_mfma_f32_16x16x32_bf16 v[118:121], v[170:173], v[198:201], v[118:121]
	v_mfma_f32_16x16x32_bf16 v[110:113], v[162:165], v[206:209], v[110:113]
	v_mfma_f32_16x16x32_bf16 v[102:105], v[170:173], v[206:209], v[102:105]
	v_mfma_f32_16x16x32_bf16 v[94:97], v[162:165], v[214:217], v[94:97]
	v_mfma_f32_16x16x32_bf16 v[86:89], v[170:173], v[214:217], v[86:89]
	v_mfma_f32_16x16x32_bf16 v[78:81], v[162:165], v[222:225], v[78:81]
	v_mfma_f32_16x16x32_bf16 v[70:73], v[170:173], v[222:225], v[70:73]
	s_setprio 0
	s_setprio 1
	v_mfma_f32_16x16x32_bf16 v[122:125], v[174:177], v[194:197], v[122:125]
	v_mfma_f32_16x16x32_bf16 v[114:117], v[186:189], v[194:197], v[114:117]
	v_mfma_f32_16x16x32_bf16 v[106:109], v[174:177], v[202:205], v[106:109]
	v_mfma_f32_16x16x32_bf16 v[98:101], v[186:189], v[202:205], v[98:101]
	v_mfma_f32_16x16x32_bf16 v[90:93], v[174:177], v[210:213], v[90:93]
	v_mfma_f32_16x16x32_bf16 v[82:85], v[186:189], v[210:213], v[82:85]
	v_mfma_f32_16x16x32_bf16 v[74:77], v[174:177], v[218:221], v[74:77]
	v_mfma_f32_16x16x32_bf16 v[66:69], v[186:189], v[218:221], v[66:69]
	v_mfma_f32_16x16x32_bf16 v[122:125], v[182:185], v[198:201], v[122:125]
	v_mfma_f32_16x16x32_bf16 v[114:117], v[190:193], v[198:201], v[114:117]
	v_mfma_f32_16x16x32_bf16 v[106:109], v[182:185], v[206:209], v[106:109]
	v_mfma_f32_16x16x32_bf16 v[98:101], v[190:193], v[206:209], v[98:101]
	v_mfma_f32_16x16x32_bf16 v[90:93], v[182:185], v[214:217], v[90:93]
	v_mfma_f32_16x16x32_bf16 v[82:85], v[190:193], v[214:217], v[82:85]
	v_mfma_f32_16x16x32_bf16 v[74:77], v[182:185], v[222:225], v[74:77]
	v_mfma_f32_16x16x32_bf16 v[66:69], v[190:193], v[222:225], v[66:69]
	s_setprio 0
	s_barrier
	s_add_i32 s26, s33, s19
	v_lshl_add_u64 v[178:179], v[178:179], 0, s[8:9]
	s_mov_b32 m0, s26
	ds_read_b128 v[194:197], v156 offset:49152
	ds_read_b128 v[198:201], v156 offset:50176
	ds_read_b128 v[202:205], v156 offset:51200
	ds_read_b128 v[206:209], v156 offset:52224
	ds_read_b128 v[210:213], v156 offset:53248
	ds_read_b128 v[214:217], v156 offset:54272
	ds_read_b128 v[218:221], v156 offset:55296
	ds_read_b128 v[222:225], v156 offset:56320
	global_load_lds_dwordx4 v[178:179], off
	s_add_i32 m0, s26, 0x2000
	s_add_u32 s24, s24, 0x40080
	v_lshl_add_u64 v[178:179], v[226:227], 0, s[8:9]
	s_addc_u32 s25, s25, 0
	s_add_i32 s26, s51, s19
	global_load_lds_dwordx4 v[178:179], off
	v_lshl_add_u64 v[178:179], s[24:25], 0, v[132:133]
	s_mov_b32 m0, s26
	s_nop 0
	global_load_lds_dwordx4 v[178:179], off
	v_lshl_add_u64 v[178:179], s[24:25], 0, v[136:137]
	s_add_i32 m0, s26, 0x2000
	s_nop 0
	global_load_lds_dwordx4 v[178:179], off
	v_lshl_add_u64 v[178:179], v[228:229], 0, s[8:9]
	s_mov_b32 m0, s38
	s_nop 0
	global_load_lds_dwordx4 v[178:179], off
	v_lshl_add_u64 v[178:179], v[230:231], 0, s[8:9]
	s_mov_b32 m0, s39
	s_nop 0
	global_load_lds_dwordx4 v[178:179], off
	s_waitcnt vmcnt(8)
	s_waitcnt lgkmcnt(0)
	s_barrier
	s_setprio 1
	s_waitcnt lgkmcnt(0)
	v_mfma_f32_16x16x32_bf16 v[62:65], v[158:161], v[194:197], v[62:65]
	v_mfma_f32_16x16x32_bf16 v[54:57], v[166:169], v[194:197], v[54:57]
	v_mfma_f32_16x16x32_bf16 v[46:49], v[158:161], v[202:205], v[46:49]
	v_mfma_f32_16x16x32_bf16 v[38:41], v[166:169], v[202:205], v[38:41]
	v_mfma_f32_16x16x32_bf16 v[30:33], v[158:161], v[210:213], v[30:33]
	v_mfma_f32_16x16x32_bf16 v[22:25], v[166:169], v[210:213], v[22:25]
	v_mfma_f32_16x16x32_bf16 v[14:17], v[158:161], v[218:221], v[14:17]
	v_mfma_f32_16x16x32_bf16 v[6:9], v[166:169], v[218:221], v[6:9]
	v_mfma_f32_16x16x32_bf16 v[62:65], v[162:165], v[198:201], v[62:65]
	v_mfma_f32_16x16x32_bf16 v[54:57], v[170:173], v[198:201], v[54:57]
	v_mfma_f32_16x16x32_bf16 v[46:49], v[162:165], v[206:209], v[46:49]
	v_mfma_f32_16x16x32_bf16 v[38:41], v[170:173], v[206:209], v[38:41]
	v_mfma_f32_16x16x32_bf16 v[30:33], v[162:165], v[214:217], v[30:33]
	v_mfma_f32_16x16x32_bf16 v[22:25], v[170:173], v[214:217], v[22:25]
	v_mfma_f32_16x16x32_bf16 v[14:17], v[162:165], v[222:225], v[14:17]
	v_mfma_f32_16x16x32_bf16 v[6:9], v[170:173], v[222:225], v[6:9]
	s_setprio 0
	s_setprio 1
	v_mfma_f32_16x16x32_bf16 v[58:61], v[174:177], v[194:197], v[58:61]
	v_mfma_f32_16x16x32_bf16 v[50:53], v[186:189], v[194:197], v[50:53]
	v_mfma_f32_16x16x32_bf16 v[42:45], v[174:177], v[202:205], v[42:45]
	v_mfma_f32_16x16x32_bf16 v[34:37], v[186:189], v[202:205], v[34:37]
	v_mfma_f32_16x16x32_bf16 v[26:29], v[174:177], v[210:213], v[26:29]
	v_mfma_f32_16x16x32_bf16 v[18:21], v[186:189], v[210:213], v[18:21]
	v_mfma_f32_16x16x32_bf16 v[10:13], v[174:177], v[218:221], v[10:13]
	v_mfma_f32_16x16x32_bf16 v[2:5], v[186:189], v[218:221], v[2:5]
	v_mfma_f32_16x16x32_bf16 v[58:61], v[182:185], v[198:201], v[58:61]
	v_mfma_f32_16x16x32_bf16 v[50:53], v[190:193], v[198:201], v[50:53]
	v_mfma_f32_16x16x32_bf16 v[42:45], v[182:185], v[206:209], v[42:45]
	v_mfma_f32_16x16x32_bf16 v[34:37], v[190:193], v[206:209], v[34:37]
	v_mfma_f32_16x16x32_bf16 v[26:29], v[182:185], v[214:217], v[26:29]
	v_mfma_f32_16x16x32_bf16 v[18:21], v[190:193], v[214:217], v[18:21]
	v_mfma_f32_16x16x32_bf16 v[10:13], v[182:185], v[222:225], v[10:13]
	v_mfma_f32_16x16x32_bf16 v[2:5], v[190:193], v[222:225], v[2:5]
	s_setprio 0
	s_barrier
	s_add_i32 s57, s57, 2
	s_add_u32 s22, s22, 0x100
	s_addc_u32 s23, s23, 0
	s_add_u32 s55, s55, 0x100
	s_addc_u32 s56, s56, 0

.LBB0_2036:
	s_add_u32 s40, s12, 0x100
	s_addc_u32 s41, s13, 0
	s_add_u32 s12, s14, 0xc000

	s_addc_u32 s13, s15, 0
	s_mov_b32 s42, -2


	ds_read_b128 v[144:147], v153
	ds_read_b128 v[156:159], v153 offset:1024
	ds_read_b128 v[160:163], v153 offset:2048
	ds_read_b128 v[164:167], v153 offset:3072
	ds_read_b128 v[168:171], v154
	ds_read_b128 v[172:175], v154 offset:1024
	ds_read_b128 v[176:179], v154 offset:2048
	ds_read_b128 v[180:183], v154 offset:3072
	s_add_u32 s14, s12, 0x4000
	s_addc_u32 s15, s13, 0
	s_cmp_eq_u32 s42, 40
	s_cselect_b32 s18, s2, s14
	s_cselect_b32 s19, s3, s15
	s_cselect_b32 s16, s10, s40
	s_cselect_b32 s17, s11, s41
	s_add_u32 s14, s18, 0x8000
	s_addc_u32 s15, s19, 0
	v_lshl_add_u64 v[148:149], s[12:13], 0, v[136:137]
	s_add_i32 m0, s24, 0xc000
	ds_read_b128 v[184:187], v155
	ds_read_b128 v[188:191], v155 offset:1024
	ds_read_b128 v[192:195], v155 offset:2048
	ds_read_b128 v[196:199], v155 offset:3072
	ds_read_b128 v[200:203], v155 offset:4096
	ds_read_b128 v[204:207], v155 offset:5120
	ds_read_b128 v[208:211], v155 offset:6144
	ds_read_b128 v[212:215], v155 offset:7168
	global_load_lds_dwordx4 v[148:149], off
	v_lshl_add_u64 v[148:149], s[12:13], 0, v[138:139]
	s_add_i32 m0, s24, 0xe000
	s_nop 0
	global_load_lds_dwordx4 v[148:149], off
	s_waitcnt vmcnt(8)
	s_waitcnt lgkmcnt(0)
	s_barrier
	s_setprio 1
	s_waitcnt lgkmcnt(0)
	v_mfma_f32_16x16x32_bf16 v[124:127], v[144:147], v[184:187], 0
	v_mfma_f32_16x16x32_bf16 v[120:123], v[160:163], v[184:187], 0
	v_mfma_f32_16x16x32_bf16 v[108:111], v[144:147], v[192:195], 0
	v_mfma_f32_16x16x32_bf16 v[104:107], v[160:163], v[192:195], 0
	v_mfma_f32_16x16x32_bf16 v[92:95], v[144:147], v[200:203], 0
	v_mfma_f32_16x16x32_bf16 v[88:91], v[160:163], v[200:203], 0
	v_mfma_f32_16x16x32_bf16 v[76:79], v[144:147], v[208:211], 0
	v_mfma_f32_16x16x32_bf16 v[72:75], v[160:163], v[208:211], 0
	v_mfma_f32_16x16x32_bf16 v[124:127], v[156:159], v[188:191], v[124:127]
	v_mfma_f32_16x16x32_bf16 v[120:123], v[164:167], v[188:191], v[120:123]
	v_mfma_f32_16x16x32_bf16 v[108:111], v[156:159], v[196:199], v[108:111]
	v_mfma_f32_16x16x32_bf16 v[104:107], v[164:167], v[196:199], v[104:107]
	v_mfma_f32_16x16x32_bf16 v[92:95], v[156:159], v[204:207], v[92:95]
	v_mfma_f32_16x16x32_bf16 v[88:91], v[164:167], v[204:207], v[88:91]
	v_mfma_f32_16x16x32_bf16 v[76:79], v[156:159], v[212:215], v[76:79]
	v_mfma_f32_16x16x32_bf16 v[72:75], v[164:167], v[212:215], v[72:75]
	s_setprio 0
	s_setprio 1
	v_mfma_f32_16x16x32_bf16 v[116:119], v[168:171], v[184:187], 0
	v_mfma_f32_16x16x32_bf16 v[112:115], v[176:179], v[184:187], 0
	v_mfma_f32_16x16x32_bf16 v[100:103], v[168:171], v[192:195], 0
	v_mfma_f32_16x16x32_bf16 v[96:99], v[176:179], v[192:195], 0
	v_mfma_f32_16x16x32_bf16 v[84:87], v[168:171], v[200:203], 0
	v_mfma_f32_16x16x32_bf16 v[80:83], v[176:179], v[200:203], 0
	v_mfma_f32_16x16x32_bf16 v[68:71], v[168:171], v[208:211], 0
	v_mfma_f32_16x16x32_bf16 v[64:67], v[176:179], v[208:211], 0
	v_mfma_f32_16x16x32_bf16 v[116:119], v[172:175], v[188:191], v[116:119]
	v_mfma_f32_16x16x32_bf16 v[112:115], v[180:183], v[188:191], v[112:115]
	v_mfma_f32_16x16x32_bf16 v[100:103], v[172:175], v[196:199], v[100:103]
	v_mfma_f32_16x16x32_bf16 v[96:99], v[180:183], v[196:199], v[96:99]
	v_mfma_f32_16x16x32_bf16 v[84:87], v[172:175], v[204:207], v[84:87]
	v_mfma_f32_16x16x32_bf16 v[80:83], v[180:183], v[204:207], v[80:83]
	v_mfma_f32_16x16x32_bf16 v[68:71], v[172:175], v[212:215], v[68:71]
	v_mfma_f32_16x16x32_bf16 v[64:67], v[180:183], v[212:215], v[64:67]
	s_setprio 0
	s_barrier
	s_add_i32 s33, s34, s23
	v_lshl_add_u64 v[148:149], s[16:17], 0, v[130:131]
	s_mov_b32 m0, s33
	ds_read_b128 v[184:187], v155 offset:16384
	ds_read_b128 v[188:191], v155 offset:17408
	ds_read_b128 v[192:195], v155 offset:18432
	ds_read_b128 v[196:199], v155 offset:19456
	ds_read_b128 v[200:203], v155 offset:20480
	ds_read_b128 v[204:207], v155 offset:21504
	ds_read_b128 v[208:211], v155 offset:22528
	ds_read_b128 v[212:215], v155 offset:23552
	global_load_lds_dwordx4 v[148:149], off
	s_add_i32 m0, s33, 0x2000
	s_add_u32 s46, s16, 0xb0000
	v_lshl_add_u64 v[216:217], s[16:17], 0, v[134:135]
	s_addc_u32 s47, s17, 0
	s_add_i32 s33, s35, s23
	global_load_lds_dwordx4 v[216:217], off
	v_lshl_add_u64 v[218:219], s[46:47], 0, v[130:131]
	s_mov_b32 m0, s33
	s_nop 0
	global_load_lds_dwordx4 v[218:219], off
	v_lshl_add_u64 v[218:219], s[46:47], 0, v[134:135]
	s_add_i32 m0, s33, 0x2000
	s_nop 0
	global_load_lds_dwordx4 v[218:219], off
	v_lshl_add_u64 v[218:219], s[18:19], 0, v[128:129]
	s_mov_b32 m0, s24
	s_nop 0
	global_load_lds_dwordx4 v[218:219], off
	v_lshl_add_u64 v[218:219], s[18:19], 0, v[132:133]
	s_mov_b32 m0, s25
	s_nop 0
	global_load_lds_dwordx4 v[218:219], off
	s_waitcnt vmcnt(8)
	s_waitcnt lgkmcnt(0)
	s_barrier
	s_setprio 1
	s_waitcnt lgkmcnt(0)
	v_mfma_f32_16x16x32_bf16 v[60:63], v[144:147], v[184:187], 0
	v_mfma_f32_16x16x32_bf16 v[56:59], v[160:163], v[184:187], 0
	v_mfma_f32_16x16x32_bf16 v[44:47], v[144:147], v[192:195], 0
	v_mfma_f32_16x16x32_bf16 v[40:43], v[160:163], v[192:195], 0
	v_mfma_f32_16x16x32_bf16 v[28:31], v[144:147], v[200:203], 0
	v_mfma_f32_16x16x32_bf16 v[24:27], v[160:163], v[200:203], 0
	v_mfma_f32_16x16x32_bf16 v[12:15], v[144:147], v[208:211], 0
	v_mfma_f32_16x16x32_bf16 v[8:11], v[160:163], v[208:211], 0
	v_mfma_f32_16x16x32_bf16 v[60:63], v[156:159], v[188:191], v[60:63]
	v_mfma_f32_16x16x32_bf16 v[56:59], v[164:167], v[188:191], v[56:59]
	v_mfma_f32_16x16x32_bf16 v[44:47], v[156:159], v[196:199], v[44:47]
	v_mfma_f32_16x16x32_bf16 v[40:43], v[164:167], v[196:199], v[40:43]
	v_mfma_f32_16x16x32_bf16 v[28:31], v[156:159], v[204:207], v[28:31]
	v_mfma_f32_16x16x32_bf16 v[24:27], v[164:167], v[204:207], v[24:27]
	v_mfma_f32_16x16x32_bf16 v[12:15], v[156:159], v[212:215], v[12:15]
	v_mfma_f32_16x16x32_bf16 v[8:11], v[164:167], v[212:215], v[8:11]
	s_setprio 0
	s_setprio 1
	v_mfma_f32_16x16x32_bf16 v[52:55], v[168:171], v[184:187], 0
	v_mfma_f32_16x16x32_bf16 v[48:51], v[176:179], v[184:187], 0
	v_mfma_f32_16x16x32_bf16 v[36:39], v[168:171], v[192:195], 0
	v_mfma_f32_16x16x32_bf16 v[32:35], v[176:179], v[192:195], 0
	v_mfma_f32_16x16x32_bf16 v[20:23], v[168:171], v[200:203], 0
	v_mfma_f32_16x16x32_bf16 v[16:19], v[176:179], v[200:203], 0
	v_mfma_f32_16x16x32_bf16 v[4:7], v[168:171], v[208:211], 0
	v_mfma_f32_16x16x32_bf16 v[0:3], v[176:179], v[208:211], 0
	v_mfma_f32_16x16x32_bf16 v[52:55], v[172:175], v[188:191], v[52:55]
	v_mfma_f32_16x16x32_bf16 v[48:51], v[180:183], v[188:191], v[48:51]
	v_mfma_f32_16x16x32_bf16 v[36:39], v[172:175], v[196:199], v[36:39]
	v_mfma_f32_16x16x32_bf16 v[32:35], v[180:183], v[196:199], v[32:35]
	v_mfma_f32_16x16x32_bf16 v[20:23], v[172:175], v[204:207], v[20:23]
	v_mfma_f32_16x16x32_bf16 v[16:19], v[180:183], v[204:207], v[16:19]
	v_mfma_f32_16x16x32_bf16 v[4:7], v[172:175], v[212:215], v[4:7]
	v_mfma_f32_16x16x32_bf16 v[0:3], v[180:183], v[212:215], v[0:3]
	s_setprio 0
	s_barrier
	s_add_i32 s33, 0, 0x18000
	s_add_i32 s43, 0, 0x1c000
	v_add_u32_e32 v164, s33, v151
	v_add_u32_e32 v180, s43, v151
	ds_read_b128 v[144:147], v164
	ds_read_b128 v[156:159], v164 offset:1024
	ds_read_b128 v[160:163], v164 offset:2048
	ds_read_b128 v[164:167], v164 offset:3072
	ds_read_b128 v[168:171], v180
	ds_read_b128 v[172:175], v180 offset:1024
	ds_read_b128 v[176:179], v180 offset:2048
	ds_read_b128 v[180:183], v180 offset:3072
	s_add_u32 s18, s18, 0x4000
	s_addc_u32 s19, s19, 0
	s_mov_b32 m0, s26
	v_lshl_add_u64 v[218:219], s[18:19], 0, v[128:129]
	ds_read_b128 v[184:187], v155 offset:32768
	ds_read_b128 v[188:191], v155 offset:33792
	ds_read_b128 v[192:195], v155 offset:34816
	ds_read_b128 v[196:199], v155 offset:35840
	ds_read_b128 v[200:203], v155 offset:36864
	ds_read_b128 v[204:207], v155 offset:37888
	ds_read_b128 v[208:211], v155 offset:38912
	ds_read_b128 v[212:215], v155 offset:39936
	global_load_lds_dwordx4 v[218:219], off
	v_lshl_add_u64 v[218:219], s[18:19], 0, v[132:133]
	s_mov_b32 m0, s27
	s_nop 0
	global_load_lds_dwordx4 v[218:219], off
	s_waitcnt vmcnt(8)
	s_waitcnt lgkmcnt(0)
	s_barrier
	s_setprio 1
	s_waitcnt lgkmcnt(0)
	v_mfma_f32_16x16x32_bf16 v[124:127], v[144:147], v[184:187], v[124:127]
	v_mfma_f32_16x16x32_bf16 v[120:123], v[160:163], v[184:187], v[120:123]
	v_mfma_f32_16x16x32_bf16 v[108:111], v[144:147], v[192:195], v[108:111]
	v_mfma_f32_16x16x32_bf16 v[104:107], v[160:163], v[192:195], v[104:107]
	v_mfma_f32_16x16x32_bf16 v[92:95], v[144:147], v[200:203], v[92:95]
	v_mfma_f32_16x16x32_bf16 v[88:91], v[160:163], v[200:203], v[88:91]
	v_mfma_f32_16x16x32_bf16 v[76:79], v[144:147], v[208:211], v[76:79]
	v_mfma_f32_16x16x32_bf16 v[72:75], v[160:163], v[208:211], v[72:75]
	v_mfma_f32_16x16x32_bf16 v[124:127], v[156:159], v[188:191], v[124:127]
	v_mfma_f32_16x16x32_bf16 v[120:123], v[164:167], v[188:191], v[120:123]
	v_mfma_f32_16x16x32_bf16 v[108:111], v[156:159], v[196:199], v[108:111]
	v_mfma_f32_16x16x32_bf16 v[104:107], v[164:167], v[196:199], v[104:107]
	v_mfma_f32_16x16x32_bf16 v[92:95], v[156:159], v[204:207], v[92:95]
	v_mfma_f32_16x16x32_bf16 v[88:91], v[164:167], v[204:207], v[88:91]
	v_mfma_f32_16x16x32_bf16 v[76:79], v[156:159], v[212:215], v[76:79]
	v_mfma_f32_16x16x32_bf16 v[72:75], v[164:167], v[212:215], v[72:75]
	s_setprio 0
	s_setprio 1
	v_mfma_f32_16x16x32_bf16 v[116:119], v[168:171], v[184:187], v[116:119]
	v_mfma_f32_16x16x32_bf16 v[112:115], v[176:179], v[184:187], v[112:115]
	v_mfma_f32_16x16x32_bf16 v[100:103], v[168:171], v[192:195], v[100:103]
	v_mfma_f32_16x16x32_bf16 v[96:99], v[176:179], v[192:195], v[96:99]
	v_mfma_f32_16x16x32_bf16 v[84:87], v[168:171], v[200:203], v[84:87]
	v_mfma_f32_16x16x32_bf16 v[80:83], v[176:179], v[200:203], v[80:83]
	v_mfma_f32_16x16x32_bf16 v[68:71], v[168:171], v[208:211], v[68:71]
	v_mfma_f32_16x16x32_bf16 v[64:67], v[176:179], v[208:211], v[64:67]
	v_mfma_f32_16x16x32_bf16 v[116:119], v[172:175], v[188:191], v[116:119]
	v_mfma_f32_16x16x32_bf16 v[112:115], v[180:183], v[188:191], v[112:115]
	v_mfma_f32_16x16x32_bf16 v[100:103], v[172:175], v[196:199], v[100:103]
	v_mfma_f32_16x16x32_bf16 v[96:99], v[180:183], v[196:199], v[96:99]
	v_mfma_f32_16x16x32_bf16 v[84:87], v[172:175], v[204:207], v[84:87]
	v_mfma_f32_16x16x32_bf16 v[80:83], v[180:183], v[204:207], v[80:83]
	v_mfma_f32_16x16x32_bf16 v[68:71], v[172:175], v[212:215], v[68:71]
	v_mfma_f32_16x16x32_bf16 v[64:67], v[180:183], v[212:215], v[64:67]
	s_setprio 0
	s_barrier
	s_add_i32 s18, s33, s23
	v_lshl_add_u64 v[148:149], v[148:149], 0, s[6:7]
	s_mov_b32 m0, s18
	ds_read_b128 v[184:187], v155 offset:49152
	ds_read_b128 v[188:191], v155 offset:50176
	ds_read_b128 v[192:195], v155 offset:51200
	ds_read_b128 v[196:199], v155 offset:52224
	ds_read_b128 v[200:203], v155 offset:53248
	ds_read_b128 v[204:207], v155 offset:54272
	ds_read_b128 v[208:211], v155 offset:55296
	ds_read_b128 v[212:215], v155 offset:56320
	global_load_lds_dwordx4 v[148:149], off
	s_add_i32 m0, s18, 0x2000
	s_add_u32 s16, s16, 0xb0080
	v_lshl_add_u64 v[148:149], v[216:217], 0, s[6:7]
	s_addc_u32 s17, s17, 0
	s_add_i32 s18, s43, s23
	global_load_lds_dwordx4 v[148:149], off
	v_lshl_add_u64 v[148:149], s[16:17], 0, v[130:131]
	s_mov_b32 m0, s18
	s_nop 0
	global_load_lds_dwordx4 v[148:149], off
	v_lshl_add_u64 v[148:149], s[16:17], 0, v[134:135]
	s_add_i32 m0, s18, 0x2000
	s_nop 0
	global_load_lds_dwordx4 v[148:149], off
	v_lshl_add_u64 v[148:149], s[14:15], 0, v[128:129]
	s_mov_b32 m0, s29
	s_nop 0
	global_load_lds_dwordx4 v[148:149], off
	v_lshl_add_u64 v[148:149], s[14:15], 0, v[132:133]
	s_mov_b32 m0, s30
	s_nop 0
	global_load_lds_dwordx4 v[148:149], off
	s_waitcnt vmcnt(8)
	s_waitcnt lgkmcnt(0)
	s_barrier
	s_setprio 1
	s_waitcnt lgkmcnt(0)
	v_mfma_f32_16x16x32_bf16 v[60:63], v[144:147], v[184:187], v[60:63]
	v_mfma_f32_16x16x32_bf16 v[56:59], v[160:163], v[184:187], v[56:59]
	v_mfma_f32_16x16x32_bf16 v[44:47], v[144:147], v[192:195], v[44:47]
	v_mfma_f32_16x16x32_bf16 v[40:43], v[160:163], v[192:195], v[40:43]
	v_mfma_f32_16x16x32_bf16 v[28:31], v[144:147], v[200:203], v[28:31]
	v_mfma_f32_16x16x32_bf16 v[24:27], v[160:163], v[200:203], v[24:27]
	v_mfma_f32_16x16x32_bf16 v[12:15], v[144:147], v[208:211], v[12:15]
	v_mfma_f32_16x16x32_bf16 v[8:11], v[160:163], v[208:211], v[8:11]
	v_mfma_f32_16x16x32_bf16 v[60:63], v[156:159], v[188:191], v[60:63]
	v_mfma_f32_16x16x32_bf16 v[56:59], v[164:167], v[188:191], v[56:59]
	v_mfma_f32_16x16x32_bf16 v[44:47], v[156:159], v[196:199], v[44:47]
	v_mfma_f32_16x16x32_bf16 v[40:43], v[164:167], v[196:199], v[40:43]
	v_mfma_f32_16x16x32_bf16 v[28:31], v[156:159], v[204:207], v[28:31]
	v_mfma_f32_16x16x32_bf16 v[24:27], v[164:167], v[204:207], v[24:27]
	v_mfma_f32_16x16x32_bf16 v[12:15], v[156:159], v[212:215], v[12:15]
	v_mfma_f32_16x16x32_bf16 v[8:11], v[164:167], v[212:215], v[8:11]
	s_setprio 0
	s_setprio 1
	v_mfma_f32_16x16x32_bf16 v[52:55], v[168:171], v[184:187], v[52:55]
	v_mfma_f32_16x16x32_bf16 v[48:51], v[176:179], v[184:187], v[48:51]
	v_mfma_f32_16x16x32_bf16 v[36:39], v[168:171], v[192:195], v[36:39]
	v_mfma_f32_16x16x32_bf16 v[32:35], v[176:179], v[192:195], v[32:35]
	v_mfma_f32_16x16x32_bf16 v[20:23], v[168:171], v[200:203], v[20:23]
	v_mfma_f32_16x16x32_bf16 v[16:19], v[176:179], v[200:203], v[16:19]
	v_mfma_f32_16x16x32_bf16 v[4:7], v[168:171], v[208:211], v[4:7]
	v_mfma_f32_16x16x32_bf16 v[0:3], v[176:179], v[208:211], v[0:3]
	v_mfma_f32_16x16x32_bf16 v[52:55], v[172:175], v[188:191], v[52:55]
	v_mfma_f32_16x16x32_bf16 v[48:51], v[180:183], v[188:191], v[48:51]
	v_mfma_f32_16x16x32_bf16 v[36:39], v[172:175], v[196:199], v[36:39]
	v_mfma_f32_16x16x32_bf16 v[32:35], v[180:183], v[196:199], v[32:35]
	v_mfma_f32_16x16x32_bf16 v[20:23], v[172:175], v[204:207], v[20:23]
	v_mfma_f32_16x16x32_bf16 v[16:19], v[180:183], v[204:207], v[16:19]
	v_mfma_f32_16x16x32_bf16 v[4:7], v[172:175], v[212:215], v[4:7]
	v_mfma_f32_16x16x32_bf16 v[0:3], v[180:183], v[212:215], v[0:3]
	s_setprio 0
	s_barrier
	s_add_i32 s42, s42, 2
	s_add_u32 s40, s40, 0x100
	s_addc_u32 s41, s41, 0
	s_add_u32 s12, s12, 0x10000
	s_addc_u32 s13, s13, 0
